# accumulate-chain MFMA order with the K-half order alternating from one accumulator to the next, so the MFMA that opens a chain shares a source fragment with the one that closed the previous chain (f32
# baseline (speedup 1.0000x reference)
; #define PG8_STAGE(bufoff, gbase, voff) do { _Pragma("unroll") for (int _i = 0; _i < 2; ++_i) \
;         __builtin_amdgcn_global_load_lds((const unsigned*)((const char*)(gbase) + (voff)[_i]), (PG8_LAS unsigned*)(lds + (bufoff) + ldsw + _i * 8192), 16, 0, 0); } while (0)
; #define PG8_LDA(dst, b, h) do { _Pragma("unroll") for (int m = 0; m < 4; ++m) _Pragma("unroll") for (int k = 0; k < 2; ++k) dst[m][k] = *(const PG8_LAS bf16x8*)(lds + PG8_SA(b, h) + aoff + m * 2048 + k * 1024); } while (0)
; #define PG8_LDB(dst, b, h) do { _Pragma("unroll") for (int n = 0; n < 2; ++n) _Pragma("unroll") for (int k = 0; k < 2; ++k) dst[n][k] = *(const PG8_LAS bf16x8*)(lds + PG8_SB(b, h) + boff + n * 2048 + k * 1024); } while (0)
; #define PG8_WAIT_V(n) asm volatile("s_waitcnt vmcnt(" #n ")" ::: "memory")
; template <class Epi, class Sched, bool ALIGN_EPI = false, bool SP2 = false>
; __device__ __forceinline__ void gemm_phase(PG8_LAS unsigned char* lds, const Gemm g, const Sched& S, const Epi& E) {
;     ...
;     f32x4 acc[2][2][4][2];
; #pragma unroll
;     for (int a = 0; a < 2; ++a)
; #pragma unroll
;         for (int b = 0; b < 2; ++b)
; #pragma unroll
;             for (int m = 0; m < 4; ++m)
; #pragma unroll
;                 for (int n = 0; n < 2; ++n) acc[a][b][m][n] = (f32x4){0.f, 0.f, 0.f, 0.f};
;     ...
;         const bool has_next = S.next(ui + 1, nxt);
;         const char* nA = has_next ? (const char*)g.A + (size_t)nxt.pm * tstep : cA; const char* nB = has_next ? (const char*)g.Bt + (size_t)nxt.pn * tstep : cB;
;         for (int t = 0; t < nt; t += 2) {
;             const bool last = (t == nt - 2);
;             const char* a1 = cA + (size_t)(t + 1) * kstep;
;             const char* a2 = last ? nA : cA + (size_t)(t + 2) * kstep; const char* b2 = last ? nB : cB + (size_t)(t + 2) * kstep;
;             const char* a3 = a2 + kstep; const char* b3 = b2 + kstep;
;             if (last && has_next) S.a_ready(nxt);
;             if constexpr (SP2) {
;             PG8_LDB(B0, 0, 0); PG8_LDB(B1, 0, 1); PG8_SCHED; PG8_LDA(At, 0, 0); PG8_STAGE(PG8_SA(1, 1), a1 + hstep, voffA);
;             PG8_WAIT_V(8); PG8_WAIT_L(0); PG8_BAR; PG8_MMA(0, 0, At, B0); PG8_MMA(0, 1, At, B1); PG8_BAR; PG8_SCHED;
;             PG8_LDA(At, 0, 1); PG8_STAGE(PG8_SB(0, 0), b2, voffB); PG8_STAGE(PG8_SB(0, 1), b2 + hstepB, voffB); PG8_STAGE(PG8_SA(0, 0), a2, voffA);
.LBB0_169:
	s_add_u32 s93, s46, 0x100
	s_addc_u32 s94, s47, 0
	s_ashr_i32 s69, s68, 31
	s_lshl_b64 s[4:5], s[68:69], 20
	s_add_u32 s76, s52, s4
	s_addc_u32 s77, s53, s5
	s_and_b64 s[4:5], s[38:39], exec
	s_cselect_b32 s4, s77, s71
	s_cselect_b32 s5, s76, s70
	s_ashr_i32 s63, s62, 31
	s_lshl_b64 s[6:7], s[62:63], 20
	v_readlane_b32 s8, v249, 19
	v_readlane_b32 s9, v249, 20
	s_add_u32 s72, s8, s6
	s_addc_u32 s73, s9, s7
	s_and_b64 s[6:7], s[38:39], exec
	s_cselect_b32 s6, s73, s47
	s_cselect_b32 s7, s72, s46
	s_add_u32 s8, s70, 0x80080
	s_addc_u32 s9, s71, 0
	v_lshl_add_u64 v[144:145], s[8:9], 0, v[140:141]
	v_lshl_add_u64 v[146:147], s[8:9], 0, v[142:143]
	s_mov_b32 s8, -2
	s_mov_b64 s[46:47], 0
	v_add_u32_e32 v186, 0x10000, v139
	v_add_u32_e32 v187, 0x14000, v139
	v_add_u32_e32 v198, 0x18000, v139
	v_add_u32_e32 v199, 0x1c000, v139
	s_add_u32 s9, s70, s46
	s_addc_u32 s10, s71, s47
	s_add_u32 s9, s9, 0x100
	s_addc_u32 s10, s10, 0
	s_add_u32 s100, s9, 0x7ff80
	s_addc_u32 s101, s10, 0
	s_add_u32 s11, s93, s46
	s_addc_u32 s12, s94, s47
	s_add_i32 s13, 0, 0x10000
	s_cmpk_eq_i32 s46, 0xf00
	s_cselect_b32 s85, s4, s10
	s_cselect_b32 s84, s5, s9
	s_cselect_b32 s81, s6, s12
	s_cselect_b32 s80, s7, s11
	s_add_i32 s9, 0, 0x14000
	ds_read_b128 v[148:151], v186
	ds_read_b128 v[152:155], v186 offset:1024
	ds_read_b128 v[156:159], v186 offset:2048
	ds_read_b128 v[160:163], v186 offset:3072
	ds_read_b128 v[166:169], v187
	ds_read_b128 v[170:173], v187 offset:1024
	ds_read_b128 v[174:177], v187 offset:2048
	ds_read_b128 v[178:181], v187 offset:3072
	s_add_i32 m0, s1, 0xc000
	ds_read_b128 v[182:185], v165
	ds_read_b128 v[206:209], v165 offset:1024
	ds_read_b128 v[210:213], v165 offset:2048
	ds_read_b128 v[214:217], v165 offset:3072
	ds_read_b128 v[218:221], v165 offset:4096
	ds_read_b128 v[236:239], v165 offset:5120
	ds_read_b128 v[240:243], v165 offset:6144
	ds_read_b128 v[244:247], v165 offset:7168
	global_load_lds_dwordx4 v140, s[100:101]
	s_add_i32 m0, s1, 0xe000
	s_nop 0
	global_load_lds_dwordx4 v142, s[100:101]
	s_waitcnt vmcnt(8)
	s_waitcnt lgkmcnt(0)
	s_barrier
	v_mfma_f32_16x16x32_bf16 v[126:129], v[148:151], v[182:185], 0
	v_mfma_f32_16x16x32_bf16 v[126:129], v[152:155], v[206:209], v[126:129]
	v_mfma_f32_16x16x32_bf16 v[118:121], v[152:155], v[214:217], 0
	v_mfma_f32_16x16x32_bf16 v[118:121], v[148:151], v[210:213], v[118:121]
	v_mfma_f32_16x16x32_bf16 v[114:117], v[156:159], v[210:213], 0
	v_mfma_f32_16x16x32_bf16 v[114:117], v[160:163], v[214:217], v[114:117]
	v_mfma_f32_16x16x32_bf16 v[122:125], v[160:163], v[206:209], 0
	v_mfma_f32_16x16x32_bf16 v[122:125], v[156:159], v[182:185], v[122:125]
	v_mfma_f32_16x16x32_bf16 v[106:109], v[156:159], v[218:221], 0
	v_mfma_f32_16x16x32_bf16 v[106:109], v[160:163], v[236:239], v[106:109]
	v_mfma_f32_16x16x32_bf16 v[98:101], v[160:163], v[244:247], 0
	v_mfma_f32_16x16x32_bf16 v[98:101], v[156:159], v[240:243], v[98:101]
	v_mfma_f32_16x16x32_bf16 v[102:105], v[148:151], v[240:243], 0
	v_mfma_f32_16x16x32_bf16 v[102:105], v[152:155], v[244:247], v[102:105]
	v_mfma_f32_16x16x32_bf16 v[110:113], v[152:155], v[236:239], 0
	v_mfma_f32_16x16x32_bf16 v[110:113], v[148:151], v[218:221], v[110:113]
	v_mfma_f32_16x16x32_bf16 v[94:97], v[166:169], v[182:185], 0
	v_mfma_f32_16x16x32_bf16 v[94:97], v[170:173], v[206:209], v[94:97]
	v_mfma_f32_16x16x32_bf16 v[86:89], v[170:173], v[214:217], 0
	v_mfma_f32_16x16x32_bf16 v[86:89], v[166:169], v[210:213], v[86:89]
	v_mfma_f32_16x16x32_bf16 v[82:85], v[174:177], v[210:213], 0
	v_mfma_f32_16x16x32_bf16 v[82:85], v[178:181], v[214:217], v[82:85]
	v_mfma_f32_16x16x32_bf16 v[90:93], v[178:181], v[206:209], 0
	v_mfma_f32_16x16x32_bf16 v[90:93], v[174:177], v[182:185], v[90:93]
	v_mfma_f32_16x16x32_bf16 v[74:77], v[174:177], v[218:221], 0
	v_mfma_f32_16x16x32_bf16 v[74:77], v[178:181], v[236:239], v[74:77]
	v_mfma_f32_16x16x32_bf16 v[66:69], v[178:181], v[244:247], 0
	v_mfma_f32_16x16x32_bf16 v[66:69], v[174:177], v[240:243], v[66:69]
	v_mfma_f32_16x16x32_bf16 v[70:73], v[166:169], v[240:243], 0
	v_mfma_f32_16x16x32_bf16 v[70:73], v[170:173], v[244:247], v[70:73]
	v_mfma_f32_16x16x32_bf16 v[78:81], v[170:173], v[236:239], 0
	v_mfma_f32_16x16x32_bf16 v[78:81], v[166:169], v[218:221], v[78:81]
	s_barrier
	s_add_i32 s10, s13, s0
	s_mov_b32 m0, s10
	ds_read_b128 v[182:185], v165 offset:16384
	ds_read_b128 v[206:209], v165 offset:17408
	ds_read_b128 v[210:213], v165 offset:18432
	ds_read_b128 v[214:217], v165 offset:19456
	ds_read_b128 v[218:221], v165 offset:20480
	ds_read_b128 v[236:239], v165 offset:21504
	ds_read_b128 v[240:243], v165 offset:22528
	ds_read_b128 v[244:247], v165 offset:23552
	global_load_lds_dwordx4 v132, s[80:81]
	s_add_i32 m0, s10, 0x2000
	s_add_u32 s10, s80, 0x20000
	s_addc_u32 s11, s81, 0
	s_add_i32 s9, s9, s0
	global_load_lds_dwordx4 v136, s[80:81]
	s_mov_b32 m0, s9
	s_nop 0
	global_load_lds_dwordx4 v132, s[10:11]
	s_add_i32 m0, s9, 0x2000
	s_nop 0
	global_load_lds_dwordx4 v136, s[10:11]
	s_mov_b32 m0, s1
	s_nop 0
	global_load_lds_dwordx4 v130, s[84:85]
	s_mov_b32 m0, s25
	s_nop 0
	global_load_lds_dwordx4 v134, s[84:85]
	s_waitcnt vmcnt(8)
	s_waitcnt lgkmcnt(0)
	s_barrier
; #define PG8_STAGE(bufoff, gbase, voff) do { _Pragma("unroll") for (int _i = 0; _i < 2; ++_i) \
;         __builtin_amdgcn_global_load_lds((const unsigned*)((const char*)(gbase) + (voff)[_i]), (PG8_LAS unsigned*)(lds + (bufoff) + ldsw + _i * 8192), 16, 0, 0); } while (0)
; #define PG8_LDA(dst, b, h) do { _Pragma("unroll") for (int m = 0; m < 4; ++m) _Pragma("unroll") for (int k = 0; k < 2; ++k) dst[m][k] = *(const PG8_LAS bf16x8*)(lds + PG8_SA(b, h) + aoff + m * 2048 + k * 1024); } while (0)
; #define PG8_LDB(dst, b, h) do { _Pragma("unroll") for (int n = 0; n < 2; ++n) _Pragma("unroll") for (int k = 0; k < 2; ++k) dst[n][k] = *(const PG8_LAS bf16x8*)(lds + PG8_SB(b, h) + boff + n * 2048 + k * 1024); } while (0)
; #define PG8_MMA(ai, bj, At, Bt) do { __builtin_amdgcn_s_setprio(1); _Pragma("unroll") for (int m = 0; m < 4; ++m) _Pragma("unroll") for (int n = 0; n < 2; ++n) _Pragma("unroll") for (int k = 0; k < 2; ++k) \
;         acc[ai][bj][m][n] = __builtin_amdgcn_mfma_f32_16x16x32_bf16(Bt[n][k], At[m][k], acc[ai][bj][m][n], 0, 0, 0); __builtin_amdgcn_s_setprio(0); } while (0)
; #define PG8_BAR __builtin_amdgcn_s_barrier()
; template <class Epi, class Sched, bool ALIGN_EPI = false, bool SP2 = false>
; __device__ __forceinline__ void gemm_phase(PG8_LAS unsigned char* lds, const Gemm g, const Sched& S, const Epi& E) {
;     ...
;             const bool last = (t == nt - 2);
;             const char* a1 = cA + (size_t)(t + 1) * kstep;
;             const char* a2 = last ? nA : cA + (size_t)(t + 2) * kstep; const char* b2 = last ? nB : cB + (size_t)(t + 2) * kstep;
;             const char* a3 = a2 + kstep; const char* b3 = b2 + kstep;
;             if (last && has_next) S.a_ready(nxt);
;             if constexpr (SP2) {
;             PG8_LDB(B0, 0, 0); PG8_LDB(B1, 0, 1); PG8_SCHED; PG8_LDA(At, 0, 0); PG8_STAGE(PG8_SA(1, 1), a1 + hstep, voffA);
;             PG8_WAIT_V(8); PG8_WAIT_L(0); PG8_BAR; PG8_MMA(0, 0, At, B0); PG8_MMA(0, 1, At, B1); PG8_BAR; PG8_SCHED;
;             PG8_LDA(At, 0, 1); PG8_STAGE(PG8_SB(0, 0), b2, voffB); PG8_STAGE(PG8_SB(0, 1), b2 + hstepB, voffB); PG8_STAGE(PG8_SA(0, 0), a2, voffA);
;             PG8_WAIT_V(8); PG8_WAIT_L(0); PG8_BAR; PG8_MMA(1, 0, At, B0); PG8_MMA(1, 1, At, B1); PG8_BAR; PG8_SCHED;
;             PG8_LDB(B0, 1, 0); PG8_LDB(B1, 1, 1); PG8_SCHED; PG8_LDA(At, 1, 0); PG8_STAGE(PG8_SA(0, 1), a2 + hstep, voffA);
	v_mfma_f32_16x16x32_bf16 v[62:65], v[148:151], v[182:185], 0
	v_mfma_f32_16x16x32_bf16 v[62:65], v[152:155], v[206:209], v[62:65]
	v_mfma_f32_16x16x32_bf16 v[54:57], v[152:155], v[214:217], 0
	v_mfma_f32_16x16x32_bf16 v[54:57], v[148:151], v[210:213], v[54:57]
	v_mfma_f32_16x16x32_bf16 v[50:53], v[156:159], v[210:213], 0
	v_mfma_f32_16x16x32_bf16 v[50:53], v[160:163], v[214:217], v[50:53]
	v_mfma_f32_16x16x32_bf16 v[58:61], v[160:163], v[206:209], 0
	v_mfma_f32_16x16x32_bf16 v[58:61], v[156:159], v[182:185], v[58:61]
	v_mfma_f32_16x16x32_bf16 v[42:45], v[156:159], v[218:221], 0
	v_mfma_f32_16x16x32_bf16 v[42:45], v[160:163], v[236:239], v[42:45]
	v_mfma_f32_16x16x32_bf16 v[34:37], v[160:163], v[244:247], 0
	v_mfma_f32_16x16x32_bf16 v[34:37], v[156:159], v[240:243], v[34:37]
	v_mfma_f32_16x16x32_bf16 v[38:41], v[148:151], v[240:243], 0
	v_mfma_f32_16x16x32_bf16 v[38:41], v[152:155], v[244:247], v[38:41]
	v_mfma_f32_16x16x32_bf16 v[46:49], v[152:155], v[236:239], 0
	v_mfma_f32_16x16x32_bf16 v[46:49], v[148:151], v[218:221], v[46:49]
	v_mfma_f32_16x16x32_bf16 v[30:33], v[166:169], v[182:185], 0
	v_mfma_f32_16x16x32_bf16 v[30:33], v[170:173], v[206:209], v[30:33]
	v_mfma_f32_16x16x32_bf16 v[22:25], v[170:173], v[214:217], 0
	v_mfma_f32_16x16x32_bf16 v[22:25], v[166:169], v[210:213], v[22:25]
	v_mfma_f32_16x16x32_bf16 v[18:21], v[174:177], v[210:213], 0
	v_mfma_f32_16x16x32_bf16 v[18:21], v[178:181], v[214:217], v[18:21]
	v_mfma_f32_16x16x32_bf16 v[26:29], v[178:181], v[206:209], 0
	v_mfma_f32_16x16x32_bf16 v[26:29], v[174:177], v[182:185], v[26:29]
	v_mfma_f32_16x16x32_bf16 v[10:13], v[174:177], v[218:221], 0
	v_mfma_f32_16x16x32_bf16 v[10:13], v[178:181], v[236:239], v[10:13]
	v_mfma_f32_16x16x32_bf16 v[2:5], v[178:181], v[244:247], 0
	v_mfma_f32_16x16x32_bf16 v[2:5], v[174:177], v[240:243], v[2:5]
	v_mfma_f32_16x16x32_bf16 v[6:9], v[166:169], v[240:243], 0
	v_mfma_f32_16x16x32_bf16 v[6:9], v[170:173], v[244:247], v[6:9]
	v_mfma_f32_16x16x32_bf16 v[14:17], v[170:173], v[236:239], 0
	v_mfma_f32_16x16x32_bf16 v[14:17], v[166:169], v[218:221], v[14:17]
	s_barrier
	s_add_i32 s9, 0, 0x18000
	s_add_i32 s12, 0, 0x1c000
	ds_read_b128 v[148:151], v198
	ds_read_b128 v[152:155], v198 offset:1024
	ds_read_b128 v[156:159], v198 offset:2048
	ds_read_b128 v[160:163], v198 offset:3072
	ds_read_b128 v[166:169], v199
	ds_read_b128 v[170:173], v199 offset:1024
	ds_read_b128 v[174:177], v199 offset:2048
	ds_read_b128 v[178:181], v199 offset:3072
	s_add_u32 s10, s84, 0x80000
	s_addc_u32 s11, s85, 0
	s_mov_b32 m0, s42
	ds_read_b128 v[182:185], v165 offset:32768
	ds_read_b128 v[206:209], v165 offset:33792
	ds_read_b128 v[210:213], v165 offset:34816
	ds_read_b128 v[214:217], v165 offset:35840
	ds_read_b128 v[218:221], v165 offset:36864
	ds_read_b128 v[236:239], v165 offset:37888
	ds_read_b128 v[240:243], v165 offset:38912
	ds_read_b128 v[244:247], v165 offset:39936
	global_load_lds_dwordx4 v130, s[10:11]
	s_mov_b32 m0, s51
	s_nop 0
	global_load_lds_dwordx4 v134, s[10:11]
	s_waitcnt vmcnt(8)
	s_waitcnt lgkmcnt(0)
	s_barrier
	v_mfma_f32_16x16x32_bf16 v[126:129], v[148:151], v[182:185], v[126:129]
	v_mfma_f32_16x16x32_bf16 v[126:129], v[152:155], v[206:209], v[126:129]
	v_mfma_f32_16x16x32_bf16 v[118:121], v[152:155], v[214:217], v[118:121]
	v_mfma_f32_16x16x32_bf16 v[118:121], v[148:151], v[210:213], v[118:121]
	v_mfma_f32_16x16x32_bf16 v[114:117], v[156:159], v[210:213], v[114:117]
	v_mfma_f32_16x16x32_bf16 v[114:117], v[160:163], v[214:217], v[114:117]
	v_mfma_f32_16x16x32_bf16 v[122:125], v[160:163], v[206:209], v[122:125]
	v_mfma_f32_16x16x32_bf16 v[122:125], v[156:159], v[182:185], v[122:125]
	v_mfma_f32_16x16x32_bf16 v[106:109], v[156:159], v[218:221], v[106:109]
	v_mfma_f32_16x16x32_bf16 v[106:109], v[160:163], v[236:239], v[106:109]
	v_mfma_f32_16x16x32_bf16 v[98:101], v[160:163], v[244:247], v[98:101]
	v_mfma_f32_16x16x32_bf16 v[98:101], v[156:159], v[240:243], v[98:101]
	v_mfma_f32_16x16x32_bf16 v[102:105], v[148:151], v[240:243], v[102:105]
	v_mfma_f32_16x16x32_bf16 v[102:105], v[152:155], v[244:247], v[102:105]
	v_mfma_f32_16x16x32_bf16 v[110:113], v[152:155], v[236:239], v[110:113]
	v_mfma_f32_16x16x32_bf16 v[110:113], v[148:151], v[218:221], v[110:113]
	v_mfma_f32_16x16x32_bf16 v[94:97], v[166:169], v[182:185], v[94:97]
	v_mfma_f32_16x16x32_bf16 v[94:97], v[170:173], v[206:209], v[94:97]
	v_mfma_f32_16x16x32_bf16 v[86:89], v[170:173], v[214:217], v[86:89]
	v_mfma_f32_16x16x32_bf16 v[86:89], v[166:169], v[210:213], v[86:89]
	v_mfma_f32_16x16x32_bf16 v[82:85], v[174:177], v[210:213], v[82:85]
	v_mfma_f32_16x16x32_bf16 v[82:85], v[178:181], v[214:217], v[82:85]
	v_mfma_f32_16x16x32_bf16 v[90:93], v[178:181], v[206:209], v[90:93]
	v_mfma_f32_16x16x32_bf16 v[90:93], v[174:177], v[182:185], v[90:93]
	v_mfma_f32_16x16x32_bf16 v[74:77], v[174:177], v[218:221], v[74:77]
	v_mfma_f32_16x16x32_bf16 v[74:77], v[178:181], v[236:239], v[74:77]
	v_mfma_f32_16x16x32_bf16 v[66:69], v[178:181], v[244:247], v[66:69]
	v_mfma_f32_16x16x32_bf16 v[66:69], v[174:177], v[240:243], v[66:69]
	v_mfma_f32_16x16x32_bf16 v[70:73], v[166:169], v[240:243], v[70:73]
	v_mfma_f32_16x16x32_bf16 v[70:73], v[170:173], v[244:247], v[70:73]
	v_mfma_f32_16x16x32_bf16 v[78:81], v[170:173], v[236:239], v[78:81]
	v_mfma_f32_16x16x32_bf16 v[78:81], v[166:169], v[218:221], v[78:81]
	s_barrier
; #define PG8_STAGE(bufoff, gbase, voff) do { _Pragma("unroll") for (int _i = 0; _i < 2; ++_i) \
;         __builtin_amdgcn_global_load_lds((const unsigned*)((const char*)(gbase) + (voff)[_i]), (PG8_LAS unsigned*)(lds + (bufoff) + ldsw + _i * 8192), 16, 0, 0); } while (0)
; #define PG8_LDA(dst, b, h) do { _Pragma("unroll") for (int m = 0; m < 4; ++m) _Pragma("unroll") for (int k = 0; k < 2; ++k) dst[m][k] = *(const PG8_LAS bf16x8*)(lds + PG8_SA(b, h) + aoff + m * 2048 + k * 1024); } while (0)
; #define PG8_LDB(dst, b, h) do { _Pragma("unroll") for (int n = 0; n < 2; ++n) _Pragma("unroll") for (int k = 0; k < 2; ++k) dst[n][k] = *(const PG8_LAS bf16x8*)(lds + PG8_SB(b, h) + boff + n * 2048 + k * 1024); } while (0)
; template <class Epi, class Sched, bool ALIGN_EPI = false, bool SP2 = false>
; __device__ __forceinline__ void gemm_phase(PG8_LAS unsigned char* lds, const Gemm g, const Sched& S, const Epi& E) {
;     ...
;         for (int t = 0; t < nt; t += 2) {
;             const bool last = (t == nt - 2);
;             const char* a1 = cA + (size_t)(t + 1) * kstep;
;             const char* a2 = last ? nA : cA + (size_t)(t + 2) * kstep; const char* b2 = last ? nB : cB + (size_t)(t + 2) * kstep;
;             const char* a3 = a2 + kstep; const char* b3 = b2 + kstep;
;             if (last && has_next) S.a_ready(nxt);
;             if constexpr (SP2) {
;             PG8_LDB(B0, 0, 0); PG8_LDB(B1, 0, 1); PG8_SCHED; PG8_LDA(At, 0, 0); PG8_STAGE(PG8_SA(1, 1), a1 + hstep, voffA);
;             PG8_WAIT_V(8); PG8_WAIT_L(0); PG8_BAR; PG8_MMA(0, 0, At, B0); PG8_MMA(0, 1, At, B1); PG8_BAR; PG8_SCHED;
;             PG8_LDA(At, 0, 1); PG8_STAGE(PG8_SB(0, 0), b2, voffB); PG8_STAGE(PG8_SB(0, 1), b2 + hstepB, voffB); PG8_STAGE(PG8_SA(0, 0), a2, voffA);
;             PG8_WAIT_V(8); PG8_WAIT_L(0); PG8_BAR; PG8_MMA(1, 0, At, B0); PG8_MMA(1, 1, At, B1); PG8_BAR; PG8_SCHED;
;             PG8_LDB(B0, 1, 0); PG8_LDB(B1, 1, 1); PG8_SCHED; PG8_LDA(At, 1, 0); PG8_STAGE(PG8_SA(0, 1), a2 + hstep, voffA);
;             PG8_WAIT_V(8); PG8_WAIT_L(0); PG8_BAR; PG8_MMA(0, 0, At, B0); PG8_MMA(0, 1, At, B1); PG8_BAR; PG8_SCHED;
;             PG8_LDA(At, 1, 1); PG8_STAGE(PG8_SB(1, 0), b3, voffB); PG8_STAGE(PG8_SB(1, 1), b3 + hstepB, voffB); PG8_STAGE(PG8_SA(1, 0), a3, voffA);
;             PG8_WAIT_V(8); PG8_WAIT_L(0); PG8_BAR; PG8_MMA(1, 0, At, B0); PG8_MMA(1, 1, At, B1); PG8_BAR; PG8_SCHED;
	s_add_i32 s9, s9, s0
	s_mov_b32 m0, s9
	ds_read_b128 v[182:185], v165 offset:49152
	ds_read_b128 v[206:209], v165 offset:50176
	ds_read_b128 v[210:213], v165 offset:51200
	ds_read_b128 v[214:217], v165 offset:52224
	ds_read_b128 v[218:221], v165 offset:53248
	ds_read_b128 v[236:239], v165 offset:54272
	ds_read_b128 v[240:243], v165 offset:55296
	ds_read_b128 v[244:247], v165 offset:56320
	s_add_u32 s100, s80, s60
	s_addc_u32 s101, s81, s61
	global_load_lds_dwordx4 v132, s[100:101]
	s_add_i32 m0, s9, 0x2000
	s_add_u32 s10, s80, 0x20080
	s_addc_u32 s11, s81, 0
	s_add_i32 s9, s12, s0
	global_load_lds_dwordx4 v136, s[100:101]
	s_mov_b32 m0, s9
	s_nop 0
	global_load_lds_dwordx4 v132, s[10:11]
	s_add_i32 m0, s9, 0x2000
	s_nop 0
	global_load_lds_dwordx4 v136, s[10:11]
	s_mov_b32 m0, s66
	s_add_u32 s100, s84, s60
	s_addc_u32 s101, s85, s61
	global_load_lds_dwordx4 v130, s[100:101]
	s_mov_b32 m0, s67
	s_nop 0
	global_load_lds_dwordx4 v134, s[100:101]
	s_waitcnt vmcnt(8)
	s_waitcnt lgkmcnt(0)
	s_barrier
	v_mfma_f32_16x16x32_bf16 v[62:65], v[148:151], v[182:185], v[62:65]
	v_mfma_f32_16x16x32_bf16 v[62:65], v[152:155], v[206:209], v[62:65]
	v_mfma_f32_16x16x32_bf16 v[54:57], v[152:155], v[214:217], v[54:57]
	v_mfma_f32_16x16x32_bf16 v[54:57], v[148:151], v[210:213], v[54:57]
	v_mfma_f32_16x16x32_bf16 v[50:53], v[156:159], v[210:213], v[50:53]
	v_mfma_f32_16x16x32_bf16 v[50:53], v[160:163], v[214:217], v[50:53]
	v_mfma_f32_16x16x32_bf16 v[58:61], v[160:163], v[206:209], v[58:61]
	v_mfma_f32_16x16x32_bf16 v[58:61], v[156:159], v[182:185], v[58:61]
	v_mfma_f32_16x16x32_bf16 v[42:45], v[156:159], v[218:221], v[42:45]
	v_mfma_f32_16x16x32_bf16 v[42:45], v[160:163], v[236:239], v[42:45]
	v_mfma_f32_16x16x32_bf16 v[34:37], v[160:163], v[244:247], v[34:37]
	v_mfma_f32_16x16x32_bf16 v[34:37], v[156:159], v[240:243], v[34:37]
	v_mfma_f32_16x16x32_bf16 v[38:41], v[148:151], v[240:243], v[38:41]
	v_mfma_f32_16x16x32_bf16 v[38:41], v[152:155], v[244:247], v[38:41]
	v_mfma_f32_16x16x32_bf16 v[46:49], v[152:155], v[236:239], v[46:49]
	v_mfma_f32_16x16x32_bf16 v[46:49], v[148:151], v[218:221], v[46:49]
	v_mfma_f32_16x16x32_bf16 v[30:33], v[166:169], v[182:185], v[30:33]
	v_mfma_f32_16x16x32_bf16 v[30:33], v[170:173], v[206:209], v[30:33]
	v_mfma_f32_16x16x32_bf16 v[22:25], v[170:173], v[214:217], v[22:25]
	v_mfma_f32_16x16x32_bf16 v[22:25], v[166:169], v[210:213], v[22:25]
	v_mfma_f32_16x16x32_bf16 v[18:21], v[174:177], v[210:213], v[18:21]
	v_mfma_f32_16x16x32_bf16 v[18:21], v[178:181], v[214:217], v[18:21]
	v_mfma_f32_16x16x32_bf16 v[26:29], v[178:181], v[206:209], v[26:29]
	v_mfma_f32_16x16x32_bf16 v[26:29], v[174:177], v[182:185], v[26:29]
	v_mfma_f32_16x16x32_bf16 v[10:13], v[174:177], v[218:221], v[10:13]
	v_mfma_f32_16x16x32_bf16 v[10:13], v[178:181], v[236:239], v[10:13]
	v_mfma_f32_16x16x32_bf16 v[2:5], v[178:181], v[244:247], v[2:5]
	v_mfma_f32_16x16x32_bf16 v[2:5], v[174:177], v[240:243], v[2:5]
	v_mfma_f32_16x16x32_bf16 v[6:9], v[166:169], v[240:243], v[6:9]
	v_mfma_f32_16x16x32_bf16 v[6:9], v[170:173], v[244:247], v[6:9]
	v_mfma_f32_16x16x32_bf16 v[14:17], v[170:173], v[236:239], v[14:17]
	v_mfma_f32_16x16x32_bf16 v[14:17], v[166:169], v[218:221], v[14:17]
	s_barrier
	s_add_i32 s8, s8, 2
	s_add_u32 s46, s46, 0x100
	s_addc_u32 s47, s47, 0
	s_cmp_gt_u32 s8, 29
.LBB0_170:
	s_add_u32 s9, s70, s46
	s_addc_u32 s10, s71, s47
	s_add_u32 s9, s9, 0x100
	s_addc_u32 s10, s10, 0
	s_add_u32 s100, s9, 0x7ff80
	s_addc_u32 s101, s10, 0
	s_add_u32 s11, s93, s46
	s_addc_u32 s12, s94, s47
	s_add_i32 s13, 0, 0x10000
	s_cmpk_eq_i32 s46, 0xf00
	s_cselect_b32 s85, s4, s10
	s_cselect_b32 s84, s5, s9
	s_cselect_b32 s81, s6, s12
	s_cselect_b32 s80, s7, s11
	s_add_i32 s9, 0, 0x14000
	ds_read_b128 v[148:151], v186
	ds_read_b128 v[152:155], v186 offset:1024
	ds_read_b128 v[156:159], v186 offset:2048
	ds_read_b128 v[160:163], v186 offset:3072
	ds_read_b128 v[166:169], v187
	ds_read_b128 v[170:173], v187 offset:1024
	ds_read_b128 v[174:177], v187 offset:2048
	ds_read_b128 v[178:181], v187 offset:3072
	s_add_i32 m0, s1, 0xc000
	ds_read_b128 v[182:185], v165
	ds_read_b128 v[206:209], v165 offset:1024
	ds_read_b128 v[210:213], v165 offset:2048
	ds_read_b128 v[214:217], v165 offset:3072
	ds_read_b128 v[218:221], v165 offset:4096
	ds_read_b128 v[236:239], v165 offset:5120
	ds_read_b128 v[240:243], v165 offset:6144
	ds_read_b128 v[244:247], v165 offset:7168
	global_load_lds_dwordx4 v140, s[100:101]
	s_add_i32 m0, s1, 0xe000
	s_nop 0
	global_load_lds_dwordx4 v142, s[100:101]
	s_waitcnt vmcnt(8)
	s_waitcnt lgkmcnt(0)
	s_barrier
; #define PG8_STAGE(bufoff, gbase, voff) do { _Pragma("unroll") for (int _i = 0; _i < 2; ++_i) \
;         __builtin_amdgcn_global_load_lds((const unsigned*)((const char*)(gbase) + (voff)[_i]), (PG8_LAS unsigned*)(lds + (bufoff) + ldsw + _i * 8192), 16, 0, 0); } while (0)
; #define PG8_LDA(dst, b, h) do { _Pragma("unroll") for (int m = 0; m < 4; ++m) _Pragma("unroll") for (int k = 0; k < 2; ++k) dst[m][k] = *(const PG8_LAS bf16x8*)(lds + PG8_SA(b, h) + aoff + m * 2048 + k * 1024); } while (0)
; #define PG8_LDB(dst, b, h) do { _Pragma("unroll") for (int n = 0; n < 2; ++n) _Pragma("unroll") for (int k = 0; k < 2; ++k) dst[n][k] = *(const PG8_LAS bf16x8*)(lds + PG8_SB(b, h) + boff + n * 2048 + k * 1024); } while (0)
; template <class Epi, class Sched, bool ALIGN_EPI = false, bool SP2 = false>
; __device__ __forceinline__ void gemm_phase(PG8_LAS unsigned char* lds, const Gemm g, const Sched& S, const Epi& E) {
;     ...
;         for (int t = 0; t < nt; t += 2) {
;             const bool last = (t == nt - 2);
;             const char* a1 = cA + (size_t)(t + 1) * kstep;
;             const char* a2 = last ? nA : cA + (size_t)(t + 2) * kstep; const char* b2 = last ? nB : cB + (size_t)(t + 2) * kstep;
;             const char* a3 = a2 + kstep; const char* b3 = b2 + kstep;
;             if (last && has_next) S.a_ready(nxt);
;             if constexpr (SP2) {
;             PG8_LDB(B0, 0, 0); PG8_LDB(B1, 0, 1); PG8_SCHED; PG8_LDA(At, 0, 0); PG8_STAGE(PG8_SA(1, 1), a1 + hstep, voffA);
;             PG8_WAIT_V(8); PG8_WAIT_L(0); PG8_BAR; PG8_MMA(0, 0, At, B0); PG8_MMA(0, 1, At, B1); PG8_BAR; PG8_SCHED;
;             PG8_LDA(At, 0, 1); PG8_STAGE(PG8_SB(0, 0), b2, voffB); PG8_STAGE(PG8_SB(0, 1), b2 + hstepB, voffB); PG8_STAGE(PG8_SA(0, 0), a2, voffA);
;             PG8_WAIT_V(8); PG8_WAIT_L(0); PG8_BAR; PG8_MMA(1, 0, At, B0); PG8_MMA(1, 1, At, B1); PG8_BAR; PG8_SCHED;
;             PG8_LDB(B0, 1, 0); PG8_LDB(B1, 1, 1); PG8_SCHED; PG8_LDA(At, 1, 0); PG8_STAGE(PG8_SA(0, 1), a2 + hstep, voffA);
;             PG8_WAIT_V(8); PG8_WAIT_L(0); PG8_BAR; PG8_MMA(0, 0, At, B0); PG8_MMA(0, 1, At, B1); PG8_BAR; PG8_SCHED;
;             PG8_LDA(At, 1, 1); PG8_STAGE(PG8_SB(1, 0), b3, voffB); PG8_STAGE(PG8_SB(1, 1), b3 + hstepB, voffB); PG8_STAGE(PG8_SA(1, 0), a3, voffA);
;             PG8_WAIT_V(8); PG8_WAIT_L(0); PG8_BAR; PG8_MMA(1, 0, At, B0); PG8_MMA(1, 1, At, B1); PG8_BAR; PG8_SCHED;
	v_mfma_f32_16x16x32_bf16 v[126:129], v[148:151], v[182:185], v[126:129]
	v_mfma_f32_16x16x32_bf16 v[126:129], v[152:155], v[206:209], v[126:129]
	v_mfma_f32_16x16x32_bf16 v[118:121], v[152:155], v[214:217], v[118:121]
	v_mfma_f32_16x16x32_bf16 v[118:121], v[148:151], v[210:213], v[118:121]
	v_mfma_f32_16x16x32_bf16 v[114:117], v[156:159], v[210:213], v[114:117]
	v_mfma_f32_16x16x32_bf16 v[114:117], v[160:163], v[214:217], v[114:117]
	v_mfma_f32_16x16x32_bf16 v[122:125], v[160:163], v[206:209], v[122:125]
	v_mfma_f32_16x16x32_bf16 v[122:125], v[156:159], v[182:185], v[122:125]
	v_mfma_f32_16x16x32_bf16 v[106:109], v[156:159], v[218:221], v[106:109]
	v_mfma_f32_16x16x32_bf16 v[106:109], v[160:163], v[236:239], v[106:109]
	v_mfma_f32_16x16x32_bf16 v[98:101], v[160:163], v[244:247], v[98:101]
	v_mfma_f32_16x16x32_bf16 v[98:101], v[156:159], v[240:243], v[98:101]
	v_mfma_f32_16x16x32_bf16 v[102:105], v[148:151], v[240:243], v[102:105]
	v_mfma_f32_16x16x32_bf16 v[102:105], v[152:155], v[244:247], v[102:105]
	v_mfma_f32_16x16x32_bf16 v[110:113], v[152:155], v[236:239], v[110:113]
	v_mfma_f32_16x16x32_bf16 v[110:113], v[148:151], v[218:221], v[110:113]
	v_mfma_f32_16x16x32_bf16 v[94:97], v[166:169], v[182:185], v[94:97]
	v_mfma_f32_16x16x32_bf16 v[94:97], v[170:173], v[206:209], v[94:97]
	v_mfma_f32_16x16x32_bf16 v[86:89], v[170:173], v[214:217], v[86:89]
	v_mfma_f32_16x16x32_bf16 v[86:89], v[166:169], v[210:213], v[86:89]
	v_mfma_f32_16x16x32_bf16 v[82:85], v[174:177], v[210:213], v[82:85]
	v_mfma_f32_16x16x32_bf16 v[82:85], v[178:181], v[214:217], v[82:85]
	v_mfma_f32_16x16x32_bf16 v[90:93], v[178:181], v[206:209], v[90:93]
	v_mfma_f32_16x16x32_bf16 v[90:93], v[174:177], v[182:185], v[90:93]
	v_mfma_f32_16x16x32_bf16 v[74:77], v[174:177], v[218:221], v[74:77]
	v_mfma_f32_16x16x32_bf16 v[74:77], v[178:181], v[236:239], v[74:77]
	v_mfma_f32_16x16x32_bf16 v[66:69], v[178:181], v[244:247], v[66:69]
	v_mfma_f32_16x16x32_bf16 v[66:69], v[174:177], v[240:243], v[66:69]
	v_mfma_f32_16x16x32_bf16 v[70:73], v[166:169], v[240:243], v[70:73]
	v_mfma_f32_16x16x32_bf16 v[70:73], v[170:173], v[244:247], v[70:73]
	v_mfma_f32_16x16x32_bf16 v[78:81], v[170:173], v[236:239], v[78:81]
	v_mfma_f32_16x16x32_bf16 v[78:81], v[166:169], v[218:221], v[78:81]
	s_barrier
	s_add_i32 s10, s13, s0
	s_mov_b32 m0, s10
	ds_read_b128 v[182:185], v165 offset:16384
	ds_read_b128 v[206:209], v165 offset:17408
	ds_read_b128 v[210:213], v165 offset:18432
	ds_read_b128 v[214:217], v165 offset:19456
	ds_read_b128 v[218:221], v165 offset:20480
	ds_read_b128 v[236:239], v165 offset:21504
	ds_read_b128 v[240:243], v165 offset:22528
	ds_read_b128 v[244:247], v165 offset:23552
	global_load_lds_dwordx4 v132, s[80:81]
	s_add_i32 m0, s10, 0x2000
	s_add_u32 s10, s80, 0x20000
	s_addc_u32 s11, s81, 0
	s_add_i32 s9, s9, s0
	global_load_lds_dwordx4 v136, s[80:81]
	s_mov_b32 m0, s9
	s_nop 0
	global_load_lds_dwordx4 v132, s[10:11]
	s_add_i32 m0, s9, 0x2000
	s_nop 0
	global_load_lds_dwordx4 v136, s[10:11]
	s_mov_b32 m0, s1
	s_nop 0
	global_load_lds_dwordx4 v130, s[84:85]
	s_mov_b32 m0, s25
	s_nop 0
	global_load_lds_dwordx4 v134, s[84:85]
	s_waitcnt vmcnt(8)
	s_waitcnt lgkmcnt(0)
	s_barrier
	v_mfma_f32_16x16x32_bf16 v[62:65], v[148:151], v[182:185], v[62:65]
	v_mfma_f32_16x16x32_bf16 v[62:65], v[152:155], v[206:209], v[62:65]
	v_mfma_f32_16x16x32_bf16 v[54:57], v[152:155], v[214:217], v[54:57]
	v_mfma_f32_16x16x32_bf16 v[54:57], v[148:151], v[210:213], v[54:57]
	v_mfma_f32_16x16x32_bf16 v[50:53], v[156:159], v[210:213], v[50:53]
	v_mfma_f32_16x16x32_bf16 v[50:53], v[160:163], v[214:217], v[50:53]
	v_mfma_f32_16x16x32_bf16 v[58:61], v[160:163], v[206:209], v[58:61]
	v_mfma_f32_16x16x32_bf16 v[58:61], v[156:159], v[182:185], v[58:61]
	v_mfma_f32_16x16x32_bf16 v[42:45], v[156:159], v[218:221], v[42:45]
	v_mfma_f32_16x16x32_bf16 v[42:45], v[160:163], v[236:239], v[42:45]
	v_mfma_f32_16x16x32_bf16 v[34:37], v[160:163], v[244:247], v[34:37]
	v_mfma_f32_16x16x32_bf16 v[34:37], v[156:159], v[240:243], v[34:37]
	v_mfma_f32_16x16x32_bf16 v[38:41], v[148:151], v[240:243], v[38:41]
	v_mfma_f32_16x16x32_bf16 v[38:41], v[152:155], v[244:247], v[38:41]
	v_mfma_f32_16x16x32_bf16 v[46:49], v[152:155], v[236:239], v[46:49]
	v_mfma_f32_16x16x32_bf16 v[46:49], v[148:151], v[218:221], v[46:49]
	v_mfma_f32_16x16x32_bf16 v[30:33], v[166:169], v[182:185], v[30:33]
	v_mfma_f32_16x16x32_bf16 v[30:33], v[170:173], v[206:209], v[30:33]
	v_mfma_f32_16x16x32_bf16 v[22:25], v[170:173], v[214:217], v[22:25]
	v_mfma_f32_16x16x32_bf16 v[22:25], v[166:169], v[210:213], v[22:25]
	v_mfma_f32_16x16x32_bf16 v[18:21], v[174:177], v[210:213], v[18:21]
	v_mfma_f32_16x16x32_bf16 v[18:21], v[178:181], v[214:217], v[18:21]
	v_mfma_f32_16x16x32_bf16 v[26:29], v[178:181], v[206:209], v[26:29]
	v_mfma_f32_16x16x32_bf16 v[26:29], v[174:177], v[182:185], v[26:29]
	v_mfma_f32_16x16x32_bf16 v[10:13], v[174:177], v[218:221], v[10:13]
	v_mfma_f32_16x16x32_bf16 v[10:13], v[178:181], v[236:239], v[10:13]
	v_mfma_f32_16x16x32_bf16 v[2:5], v[178:181], v[244:247], v[2:5]
	v_mfma_f32_16x16x32_bf16 v[2:5], v[174:177], v[240:243], v[2:5]
	v_mfma_f32_16x16x32_bf16 v[6:9], v[166:169], v[240:243], v[6:9]
	v_mfma_f32_16x16x32_bf16 v[6:9], v[170:173], v[244:247], v[6:9]
	v_mfma_f32_16x16x32_bf16 v[14:17], v[170:173], v[236:239], v[14:17]
	v_mfma_f32_16x16x32_bf16 v[14:17], v[166:169], v[218:221], v[14:17]
	s_barrier
; #define PG8_STAGE(bufoff, gbase, voff) do { _Pragma("unroll") for (int _i = 0; _i < 2; ++_i) \
;         __builtin_amdgcn_global_load_lds((const unsigned*)((const char*)(gbase) + (voff)[_i]), (PG8_LAS unsigned*)(lds + (bufoff) + ldsw + _i * 8192), 16, 0, 0); } while (0)
; #define PG8_LDA(dst, b, h) do { _Pragma("unroll") for (int m = 0; m < 4; ++m) _Pragma("unroll") for (int k = 0; k < 2; ++k) dst[m][k] = *(const PG8_LAS bf16x8*)(lds + PG8_SA(b, h) + aoff + m * 2048 + k * 1024); } while (0)
; #define PG8_LDB(dst, b, h) do { _Pragma("unroll") for (int n = 0; n < 2; ++n) _Pragma("unroll") for (int k = 0; k < 2; ++k) dst[n][k] = *(const PG8_LAS bf16x8*)(lds + PG8_SB(b, h) + boff + n * 2048 + k * 1024); } while (0)
; template <class Epi, class Sched, bool ALIGN_EPI = false, bool SP2 = false>
; __device__ __forceinline__ void gemm_phase(PG8_LAS unsigned char* lds, const Gemm g, const Sched& S, const Epi& E) {
;     ...
;         for (int t = 0; t < nt; t += 2) {
;             const bool last = (t == nt - 2);
;             const char* a1 = cA + (size_t)(t + 1) * kstep;
;             const char* a2 = last ? nA : cA + (size_t)(t + 2) * kstep; const char* b2 = last ? nB : cB + (size_t)(t + 2) * kstep;
;             const char* a3 = a2 + kstep; const char* b3 = b2 + kstep;
;             if (last && has_next) S.a_ready(nxt);
;             if constexpr (SP2) {
;             PG8_LDB(B0, 0, 0); PG8_LDB(B1, 0, 1); PG8_SCHED; PG8_LDA(At, 0, 0); PG8_STAGE(PG8_SA(1, 1), a1 + hstep, voffA);
;             PG8_WAIT_V(8); PG8_WAIT_L(0); PG8_BAR; PG8_MMA(0, 0, At, B0); PG8_MMA(0, 1, At, B1); PG8_BAR; PG8_SCHED;
;             PG8_LDA(At, 0, 1); PG8_STAGE(PG8_SB(0, 0), b2, voffB); PG8_STAGE(PG8_SB(0, 1), b2 + hstepB, voffB); PG8_STAGE(PG8_SA(0, 0), a2, voffA);
;             PG8_WAIT_V(8); PG8_WAIT_L(0); PG8_BAR; PG8_MMA(1, 0, At, B0); PG8_MMA(1, 1, At, B1); PG8_BAR; PG8_SCHED;
;             PG8_LDB(B0, 1, 0); PG8_LDB(B1, 1, 1); PG8_SCHED; PG8_LDA(At, 1, 0); PG8_STAGE(PG8_SA(0, 1), a2 + hstep, voffA);
;             PG8_WAIT_V(8); PG8_WAIT_L(0); PG8_BAR; PG8_MMA(0, 0, At, B0); PG8_MMA(0, 1, At, B1); PG8_BAR; PG8_SCHED;
;             PG8_LDA(At, 1, 1); PG8_STAGE(PG8_SB(1, 0), b3, voffB); PG8_STAGE(PG8_SB(1, 1), b3 + hstepB, voffB); PG8_STAGE(PG8_SA(1, 0), a3, voffA);
;             PG8_WAIT_V(8); PG8_WAIT_L(0); PG8_BAR; PG8_MMA(1, 0, At, B0); PG8_MMA(1, 1, At, B1); PG8_BAR; PG8_SCHED;
	s_add_i32 s9, 0, 0x18000
	s_add_i32 s12, 0, 0x1c000
	ds_read_b128 v[148:151], v198
	ds_read_b128 v[152:155], v198 offset:1024
	ds_read_b128 v[156:159], v198 offset:2048
	ds_read_b128 v[160:163], v198 offset:3072
	ds_read_b128 v[166:169], v199
	ds_read_b128 v[170:173], v199 offset:1024
	ds_read_b128 v[174:177], v199 offset:2048
	ds_read_b128 v[178:181], v199 offset:3072
	s_add_u32 s10, s84, 0x80000
	s_addc_u32 s11, s85, 0
	s_mov_b32 m0, s42
	ds_read_b128 v[182:185], v165 offset:32768
	ds_read_b128 v[206:209], v165 offset:33792
	ds_read_b128 v[210:213], v165 offset:34816
	ds_read_b128 v[214:217], v165 offset:35840
	ds_read_b128 v[218:221], v165 offset:36864
	ds_read_b128 v[236:239], v165 offset:37888
	ds_read_b128 v[240:243], v165 offset:38912
	ds_read_b128 v[244:247], v165 offset:39936
	global_load_lds_dwordx4 v130, s[10:11]
	s_mov_b32 m0, s51
	s_nop 0
	global_load_lds_dwordx4 v134, s[10:11]
	s_waitcnt vmcnt(8)
	s_waitcnt lgkmcnt(0)
	s_barrier
	v_mfma_f32_16x16x32_bf16 v[126:129], v[148:151], v[182:185], v[126:129]
	v_mfma_f32_16x16x32_bf16 v[126:129], v[152:155], v[206:209], v[126:129]
	v_mfma_f32_16x16x32_bf16 v[118:121], v[152:155], v[214:217], v[118:121]
	v_mfma_f32_16x16x32_bf16 v[118:121], v[148:151], v[210:213], v[118:121]
	v_mfma_f32_16x16x32_bf16 v[114:117], v[156:159], v[210:213], v[114:117]
	v_mfma_f32_16x16x32_bf16 v[114:117], v[160:163], v[214:217], v[114:117]
	v_mfma_f32_16x16x32_bf16 v[122:125], v[160:163], v[206:209], v[122:125]
	v_mfma_f32_16x16x32_bf16 v[122:125], v[156:159], v[182:185], v[122:125]
	v_mfma_f32_16x16x32_bf16 v[106:109], v[156:159], v[218:221], v[106:109]
	v_mfma_f32_16x16x32_bf16 v[106:109], v[160:163], v[236:239], v[106:109]
	v_mfma_f32_16x16x32_bf16 v[98:101], v[160:163], v[244:247], v[98:101]
	v_mfma_f32_16x16x32_bf16 v[98:101], v[156:159], v[240:243], v[98:101]
	v_mfma_f32_16x16x32_bf16 v[102:105], v[148:151], v[240:243], v[102:105]
	v_mfma_f32_16x16x32_bf16 v[102:105], v[152:155], v[244:247], v[102:105]
	v_mfma_f32_16x16x32_bf16 v[110:113], v[152:155], v[236:239], v[110:113]
	v_mfma_f32_16x16x32_bf16 v[110:113], v[148:151], v[218:221], v[110:113]
	v_mfma_f32_16x16x32_bf16 v[94:97], v[166:169], v[182:185], v[94:97]
	v_mfma_f32_16x16x32_bf16 v[94:97], v[170:173], v[206:209], v[94:97]
	v_mfma_f32_16x16x32_bf16 v[86:89], v[170:173], v[214:217], v[86:89]
	v_mfma_f32_16x16x32_bf16 v[86:89], v[166:169], v[210:213], v[86:89]
	v_mfma_f32_16x16x32_bf16 v[82:85], v[174:177], v[210:213], v[82:85]
	v_mfma_f32_16x16x32_bf16 v[82:85], v[178:181], v[214:217], v[82:85]
	v_mfma_f32_16x16x32_bf16 v[90:93], v[178:181], v[206:209], v[90:93]
	v_mfma_f32_16x16x32_bf16 v[90:93], v[174:177], v[182:185], v[90:93]
	v_mfma_f32_16x16x32_bf16 v[74:77], v[174:177], v[218:221], v[74:77]
	v_mfma_f32_16x16x32_bf16 v[74:77], v[178:181], v[236:239], v[74:77]
	v_mfma_f32_16x16x32_bf16 v[66:69], v[178:181], v[244:247], v[66:69]
	v_mfma_f32_16x16x32_bf16 v[66:69], v[174:177], v[240:243], v[66:69]
	v_mfma_f32_16x16x32_bf16 v[70:73], v[166:169], v[240:243], v[70:73]
	v_mfma_f32_16x16x32_bf16 v[70:73], v[170:173], v[244:247], v[70:73]
	v_mfma_f32_16x16x32_bf16 v[78:81], v[170:173], v[236:239], v[78:81]
	v_mfma_f32_16x16x32_bf16 v[78:81], v[166:169], v[218:221], v[78:81]
	s_barrier
	s_add_i32 s9, s9, s0
	s_mov_b32 m0, s9
	ds_read_b128 v[182:185], v165 offset:49152
	ds_read_b128 v[206:209], v165 offset:50176
	ds_read_b128 v[210:213], v165 offset:51200
	ds_read_b128 v[214:217], v165 offset:52224
	ds_read_b128 v[218:221], v165 offset:53248
	ds_read_b128 v[236:239], v165 offset:54272
	ds_read_b128 v[240:243], v165 offset:55296
	ds_read_b128 v[244:247], v165 offset:56320
	s_add_u32 s100, s80, s60
	s_addc_u32 s101, s81, s61
	global_load_lds_dwordx4 v132, s[100:101]
	s_add_i32 m0, s9, 0x2000
	s_add_u32 s10, s80, 0x20080
	s_addc_u32 s11, s81, 0
	s_add_i32 s9, s12, s0
	global_load_lds_dwordx4 v136, s[100:101]
	s_mov_b32 m0, s9
	s_nop 0
	global_load_lds_dwordx4 v132, s[10:11]
	s_add_i32 m0, s9, 0x2000
	s_nop 0
	global_load_lds_dwordx4 v136, s[10:11]
	s_mov_b32 m0, s66
	s_add_u32 s100, s84, s60
	s_addc_u32 s101, s85, s61
	global_load_lds_dwordx4 v130, s[100:101]
	s_mov_b32 m0, s67
	s_nop 0
	global_load_lds_dwordx4 v134, s[100:101]
	s_waitcnt vmcnt(8)
	s_waitcnt lgkmcnt(0)
	s_barrier
	v_mfma_f32_16x16x32_bf16 v[62:65], v[148:151], v[182:185], v[62:65]
	v_mfma_f32_16x16x32_bf16 v[62:65], v[152:155], v[206:209], v[62:65]
	v_mfma_f32_16x16x32_bf16 v[54:57], v[152:155], v[214:217], v[54:57]
	v_mfma_f32_16x16x32_bf16 v[54:57], v[148:151], v[210:213], v[54:57]
	v_mfma_f32_16x16x32_bf16 v[50:53], v[156:159], v[210:213], v[50:53]
	v_mfma_f32_16x16x32_bf16 v[50:53], v[160:163], v[214:217], v[50:53]
	v_mfma_f32_16x16x32_bf16 v[58:61], v[160:163], v[206:209], v[58:61]
	v_mfma_f32_16x16x32_bf16 v[58:61], v[156:159], v[182:185], v[58:61]
	v_mfma_f32_16x16x32_bf16 v[42:45], v[156:159], v[218:221], v[42:45]
	v_mfma_f32_16x16x32_bf16 v[42:45], v[160:163], v[236:239], v[42:45]
	v_mfma_f32_16x16x32_bf16 v[34:37], v[160:163], v[244:247], v[34:37]
	v_mfma_f32_16x16x32_bf16 v[34:37], v[156:159], v[240:243], v[34:37]
	v_mfma_f32_16x16x32_bf16 v[38:41], v[148:151], v[240:243], v[38:41]
	v_mfma_f32_16x16x32_bf16 v[38:41], v[152:155], v[244:247], v[38:41]
	v_mfma_f32_16x16x32_bf16 v[46:49], v[152:155], v[236:239], v[46:49]
	v_mfma_f32_16x16x32_bf16 v[46:49], v[148:151], v[218:221], v[46:49]
	v_mfma_f32_16x16x32_bf16 v[30:33], v[166:169], v[182:185], v[30:33]
	v_mfma_f32_16x16x32_bf16 v[30:33], v[170:173], v[206:209], v[30:33]
	v_mfma_f32_16x16x32_bf16 v[22:25], v[170:173], v[214:217], v[22:25]
	v_mfma_f32_16x16x32_bf16 v[22:25], v[166:169], v[210:213], v[22:25]
	v_mfma_f32_16x16x32_bf16 v[18:21], v[174:177], v[210:213], v[18:21]
	v_mfma_f32_16x16x32_bf16 v[18:21], v[178:181], v[214:217], v[18:21]
	v_mfma_f32_16x16x32_bf16 v[26:29], v[178:181], v[206:209], v[26:29]
	v_mfma_f32_16x16x32_bf16 v[26:29], v[174:177], v[182:185], v[26:29]
	v_mfma_f32_16x16x32_bf16 v[10:13], v[174:177], v[218:221], v[10:13]
	v_mfma_f32_16x16x32_bf16 v[10:13], v[178:181], v[236:239], v[10:13]
	v_mfma_f32_16x16x32_bf16 v[2:5], v[178:181], v[244:247], v[2:5]
	v_mfma_f32_16x16x32_bf16 v[2:5], v[174:177], v[240:243], v[2:5]
	v_mfma_f32_16x16x32_bf16 v[6:9], v[166:169], v[240:243], v[6:9]
	v_mfma_f32_16x16x32_bf16 v[6:9], v[170:173], v[244:247], v[6:9]
	v_mfma_f32_16x16x32_bf16 v[14:17], v[170:173], v[236:239], v[14:17]
	v_mfma_f32_16x16x32_bf16 v[14:17], v[166:169], v[218:221], v[14:17]
	s_barrier
	s_add_i32 s8, s8, 2
	s_add_u32 s46, s46, 0x100
	s_addc_u32 s47, s47, 0
	s_cmp_gt_u32 s8, 29
	s_cbranch_scc0 .LBB0_170
	s_and_b64 vcc, exec, s[54:55]
	s_cbranch_vccz .LBB0_173
	s_barrier

; #define PG8_STAGE(bufoff, gbase, voff) do { _Pragma("unroll") for (int _i = 0; _i < 2; ++_i) \
;         __builtin_amdgcn_global_load_lds((const unsigned*)((const char*)(gbase) + (voff)[_i]), (PG8_LAS unsigned*)(lds + (bufoff) + ldsw + _i * 8192), 16, 0, 0); } while (0)
; #define PG8_LDA(dst, b, h) do { _Pragma("unroll") for (int m = 0; m < 4; ++m) _Pragma("unroll") for (int k = 0; k < 2; ++k) dst[m][k] = *(const PG8_LAS bf16x8*)(lds + PG8_SA(b, h) + aoff + m * 2048 + k * 1024); } while (0)
; #define PG8_LDB(dst, b, h) do { _Pragma("unroll") for (int n = 0; n < 2; ++n) _Pragma("unroll") for (int k = 0; k < 2; ++k) dst[n][k] = *(const PG8_LAS bf16x8*)(lds + PG8_SB(b, h) + boff + n * 2048 + k * 1024); } while (0)
; #define PG8_WAIT_V(n) asm volatile("s_waitcnt vmcnt(" #n ")" ::: "memory")
; template <class Epi, class Sched, bool ALIGN_EPI = false, bool SP2 = false>
; __device__ __forceinline__ void gemm_phase(PG8_LAS unsigned char* lds, const Gemm g, const Sched& S, const Epi& E) {
;     ...
;     f32x4 acc[2][2][4][2];
; #pragma unroll
;     for (int a = 0; a < 2; ++a)
; #pragma unroll
;         for (int b = 0; b < 2; ++b)
; #pragma unroll
;             for (int m = 0; m < 4; ++m)
; #pragma unroll
;                 for (int n = 0; n < 2; ++n) acc[a][b][m][n] = (f32x4){0.f, 0.f, 0.f, 0.f};
;     ...
;         const bool has_next = S.next(ui + 1, nxt);
;         const char* nA = has_next ? (const char*)g.A + (size_t)nxt.pm * tstep : cA; const char* nB = has_next ? (const char*)g.Bt + (size_t)nxt.pn * tstep : cB;
;         for (int t = 0; t < nt; t += 2) {
;             const bool last = (t == nt - 2);
;             const char* a1 = cA + (size_t)(t + 1) * kstep;
;             const char* a2 = last ? nA : cA + (size_t)(t + 2) * kstep; const char* b2 = last ? nB : cB + (size_t)(t + 2) * kstep;
;             const char* a3 = a2 + kstep; const char* b3 = b2 + kstep;
;             if (last && has_next) S.a_ready(nxt);
;             if constexpr (SP2) {
;             PG8_LDB(B0, 0, 0); PG8_LDB(B1, 0, 1); PG8_SCHED; PG8_LDA(At, 0, 0); PG8_STAGE(PG8_SA(1, 1), a1 + hstep, voffA);
;             PG8_WAIT_V(8); PG8_WAIT_L(0); PG8_BAR; PG8_MMA(0, 0, At, B0); PG8_MMA(0, 1, At, B1); PG8_BAR; PG8_SCHED;
;             PG8_LDA(At, 0, 1); PG8_STAGE(PG8_SB(0, 0), b2, voffB); PG8_STAGE(PG8_SB(0, 1), b2 + hstepB, voffB); PG8_STAGE(PG8_SA(0, 0), a2, voffA);
.LBB0_926:
	s_ashr_i32 s73, s72, 31
	s_lshl_b64 s[4:5], s[72:73], 20
	v_readlane_b32 s6, v249, 9
	v_readlane_b32 s7, v249, 10
	s_add_u32 s76, s6, s4
	s_addc_u32 s77, s7, s5
	s_and_b64 s[4:5], s[92:93], exec
	s_cselect_b32 s36, s77, s39
	s_cselect_b32 s37, s76, s38
	s_ashr_i32 s69, s68, 31
	s_lshl_b64 s[4:5], s[68:69], 20
	v_readlane_b32 s6, v249, 17
	v_readlane_b32 s7, v249, 18
	s_add_u32 s80, s6, s4
	s_addc_u32 s81, s7, s5
	s_and_b64 s[4:5], s[92:93], exec
	s_cselect_b32 s4, s81, s47
	s_cselect_b32 s5, s80, s46
	s_add_u32 s38, s38, 0x80080
	s_addc_u32 s39, s39, 0
	s_add_u32 s6, s46, 0x100
	v_mov_b32_e32 v2, 0
	s_addc_u32 s7, s47, 0
	s_mov_b32 s8, -2
	v_mov_b32_e32 v3, v2
	v_mov_b32_e32 v4, v2
	v_mov_b32_e32 v5, v2
	v_mov_b32_e32 v6, v2
	v_mov_b32_e32 v7, v2
	v_mov_b32_e32 v8, v2
	v_mov_b32_e32 v9, v2
	v_mov_b32_e32 v18, v2
	v_mov_b32_e32 v19, v2
	v_mov_b32_e32 v20, v2
	v_mov_b32_e32 v21, v2
	v_mov_b32_e32 v22, v2
	v_mov_b32_e32 v23, v2
	v_mov_b32_e32 v24, v2
	v_mov_b32_e32 v25, v2
	v_mov_b32_e32 v34, v2
	s_waitcnt lgkmcnt(0)
	v_add_u32_e32 v186, 0x10000, v193
	v_add_u32_e32 v187, 0x14000, v193
	v_add_u32_e32 v198, 0x18000, v193
	v_add_u32_e32 v199, 0x1c000, v193
	s_add_u32 s9, s38, 0xfff80080
	s_addc_u32 s10, s39, -1
	s_add_i32 s11, 0, 0x10000
	s_cmp_eq_u32 s8, 28
	s_cselect_b32 s95, s36, s10
	s_cselect_b32 s94, s37, s9
	s_cselect_b32 s47, s4, s7
	s_cselect_b32 s46, s5, s6
	s_add_i32 s9, 0, 0x14000
	ds_read_b128 v[66:69], v186
	ds_read_b128 v[70:73], v186 offset:1024
	ds_read_b128 v[78:81], v186 offset:2048
	ds_read_b128 v[86:89], v186 offset:3072
	ds_read_b128 v[146:149], v187
	ds_read_b128 v[150:153], v187 offset:1024
	ds_read_b128 v[154:157], v187 offset:2048
	ds_read_b128 v[158:161], v187 offset:3072
	s_add_i32 m0, s66, 0xc000
	ds_read_b128 v[162:165], v236
	ds_read_b128 v[166:169], v236 offset:1024
	ds_read_b128 v[170:173], v236 offset:2048
	ds_read_b128 v[174:177], v236 offset:3072
	ds_read_b128 v[178:181], v236 offset:4096
	ds_read_b128 v[182:185], v236 offset:5120
	ds_read_b128 v[216:219], v236 offset:6144
	ds_read_b128 v[220:223], v236 offset:7168
	global_load_lds_dwordx4 v212, s[38:39]
	s_add_i32 m0, s66, 0xe000
	s_nop 0
	global_load_lds_dwordx4 v214, s[38:39]
	s_waitcnt vmcnt(8)
	s_waitcnt lgkmcnt(0)
	s_barrier
	v_mfma_f32_16x16x32_bf16 v[142:145], v[66:69], v[162:165], 0
	v_mfma_f32_16x16x32_bf16 v[142:145], v[70:73], v[166:169], v[142:145]
	v_mfma_f32_16x16x32_bf16 v[126:129], v[70:73], v[174:177], 0
	v_mfma_f32_16x16x32_bf16 v[126:129], v[66:69], v[170:173], v[126:129]
	v_mfma_f32_16x16x32_bf16 v[122:125], v[78:81], v[170:173], 0
	v_mfma_f32_16x16x32_bf16 v[122:125], v[86:89], v[174:177], v[122:125]
	v_mfma_f32_16x16x32_bf16 v[138:141], v[86:89], v[166:169], 0
	v_mfma_f32_16x16x32_bf16 v[138:141], v[78:81], v[162:165], v[138:141]
	v_mfma_f32_16x16x32_bf16 v[106:109], v[78:81], v[178:181], 0
	v_mfma_f32_16x16x32_bf16 v[106:109], v[86:89], v[182:185], v[106:109]
	v_mfma_f32_16x16x32_bf16 v[90:93], v[86:89], v[220:223], 0
	v_mfma_f32_16x16x32_bf16 v[90:93], v[78:81], v[216:219], v[90:93]
	v_mfma_f32_16x16x32_bf16 v[94:97], v[66:69], v[216:219], 0
	v_mfma_f32_16x16x32_bf16 v[94:97], v[70:73], v[220:223], v[94:97]
	v_mfma_f32_16x16x32_bf16 v[110:113], v[70:73], v[182:185], 0
	v_mfma_f32_16x16x32_bf16 v[110:113], v[66:69], v[178:181], v[110:113]
	v_mfma_f32_16x16x32_bf16 v[134:137], v[146:149], v[162:165], 0
	v_mfma_f32_16x16x32_bf16 v[134:137], v[150:153], v[166:169], v[134:137]
	v_mfma_f32_16x16x32_bf16 v[118:121], v[150:153], v[174:177], 0
	v_mfma_f32_16x16x32_bf16 v[118:121], v[146:149], v[170:173], v[118:121]
	v_mfma_f32_16x16x32_bf16 v[114:117], v[154:157], v[170:173], 0
	v_mfma_f32_16x16x32_bf16 v[114:117], v[158:161], v[174:177], v[114:117]
	v_mfma_f32_16x16x32_bf16 v[130:133], v[158:161], v[166:169], 0
	v_mfma_f32_16x16x32_bf16 v[130:133], v[154:157], v[162:165], v[130:133]
	v_mfma_f32_16x16x32_bf16 v[98:101], v[154:157], v[178:181], 0
	v_mfma_f32_16x16x32_bf16 v[98:101], v[158:161], v[182:185], v[98:101]
	v_mfma_f32_16x16x32_bf16 v[74:77], v[158:161], v[220:223], 0
	v_mfma_f32_16x16x32_bf16 v[74:77], v[154:157], v[216:219], v[74:77]
	v_mfma_f32_16x16x32_bf16 v[82:85], v[146:149], v[216:219], 0
	v_mfma_f32_16x16x32_bf16 v[82:85], v[150:153], v[220:223], v[82:85]
	v_mfma_f32_16x16x32_bf16 v[102:105], v[150:153], v[182:185], 0
	v_mfma_f32_16x16x32_bf16 v[102:105], v[146:149], v[178:181], v[102:105]
	s_barrier
	s_add_i32 s10, s11, s25
	s_mov_b32 m0, s10
	ds_read_b128 v[162:165], v236 offset:16384
	ds_read_b128 v[166:169], v236 offset:17408
	ds_read_b128 v[170:173], v236 offset:18432
	ds_read_b128 v[174:177], v236 offset:19456
	ds_read_b128 v[178:181], v236 offset:20480
	ds_read_b128 v[182:185], v236 offset:21504
	ds_read_b128 v[216:219], v236 offset:22528
	ds_read_b128 v[220:223], v236 offset:23552
	global_load_lds_dwordx4 v190, s[46:47]
	s_add_i32 m0, s10, 0x2000
	s_add_u32 s10, s46, 0x20000
	s_addc_u32 s11, s47, 0
	s_add_i32 s9, s9, s25
	global_load_lds_dwordx4 v206, s[46:47]
	s_mov_b32 m0, s9
	s_nop 0
	global_load_lds_dwordx4 v190, s[10:11]
	s_add_i32 m0, s9, 0x2000
	s_nop 0
	global_load_lds_dwordx4 v206, s[10:11]
	s_mov_b32 m0, s66
	s_nop 0
	global_load_lds_dwordx4 v210, s[94:95]
	s_mov_b32 m0, s67
	s_nop 0
	global_load_lds_dwordx4 v208, s[94:95]
	s_waitcnt vmcnt(8)
	s_waitcnt lgkmcnt(0)
	s_barrier
; #define PG8_STAGE(bufoff, gbase, voff) do { _Pragma("unroll") for (int _i = 0; _i < 2; ++_i) \
;         __builtin_amdgcn_global_load_lds((const unsigned*)((const char*)(gbase) + (voff)[_i]), (PG8_LAS unsigned*)(lds + (bufoff) + ldsw + _i * 8192), 16, 0, 0); } while (0)
; #define PG8_LDA(dst, b, h) do { _Pragma("unroll") for (int m = 0; m < 4; ++m) _Pragma("unroll") for (int k = 0; k < 2; ++k) dst[m][k] = *(const PG8_LAS bf16x8*)(lds + PG8_SA(b, h) + aoff + m * 2048 + k * 1024); } while (0)
; #define PG8_LDB(dst, b, h) do { _Pragma("unroll") for (int n = 0; n < 2; ++n) _Pragma("unroll") for (int k = 0; k < 2; ++k) dst[n][k] = *(const PG8_LAS bf16x8*)(lds + PG8_SB(b, h) + boff + n * 2048 + k * 1024); } while (0)
; #define PG8_MMA(ai, bj, At, Bt) do { __builtin_amdgcn_s_setprio(1); _Pragma("unroll") for (int m = 0; m < 4; ++m) _Pragma("unroll") for (int n = 0; n < 2; ++n) _Pragma("unroll") for (int k = 0; k < 2; ++k) \
;         acc[ai][bj][m][n] = __builtin_amdgcn_mfma_f32_16x16x32_bf16(Bt[n][k], At[m][k], acc[ai][bj][m][n], 0, 0, 0); __builtin_amdgcn_s_setprio(0); } while (0)
; #define PG8_BAR __builtin_amdgcn_s_barrier()
; template <class Epi, class Sched, bool ALIGN_EPI = false, bool SP2 = false>
; __device__ __forceinline__ void gemm_phase(PG8_LAS unsigned char* lds, const Gemm g, const Sched& S, const Epi& E) {
;     ...
;             const bool last = (t == nt - 2);
;             const char* a1 = cA + (size_t)(t + 1) * kstep;
;             const char* a2 = last ? nA : cA + (size_t)(t + 2) * kstep; const char* b2 = last ? nB : cB + (size_t)(t + 2) * kstep;
;             const char* a3 = a2 + kstep; const char* b3 = b2 + kstep;
;             if (last && has_next) S.a_ready(nxt);
;             if constexpr (SP2) {
;             PG8_LDB(B0, 0, 0); PG8_LDB(B1, 0, 1); PG8_SCHED; PG8_LDA(At, 0, 0); PG8_STAGE(PG8_SA(1, 1), a1 + hstep, voffA);
;             PG8_WAIT_V(8); PG8_WAIT_L(0); PG8_BAR; PG8_MMA(0, 0, At, B0); PG8_MMA(0, 1, At, B1); PG8_BAR; PG8_SCHED;
;             PG8_LDA(At, 0, 1); PG8_STAGE(PG8_SB(0, 0), b2, voffB); PG8_STAGE(PG8_SB(0, 1), b2 + hstepB, voffB); PG8_STAGE(PG8_SA(0, 0), a2, voffA);
;             PG8_WAIT_V(8); PG8_WAIT_L(0); PG8_BAR; PG8_MMA(1, 0, At, B0); PG8_MMA(1, 1, At, B1); PG8_BAR; PG8_SCHED;
;             PG8_LDB(B0, 1, 0); PG8_LDB(B1, 1, 1); PG8_SCHED; PG8_LDA(At, 1, 0); PG8_STAGE(PG8_SA(0, 1), a2 + hstep, voffA);
	v_mfma_f32_16x16x32_bf16 v[62:65], v[66:69], v[162:165], 0
	v_mfma_f32_16x16x32_bf16 v[62:65], v[70:73], v[166:169], v[62:65]
	v_mfma_f32_16x16x32_bf16 v[46:49], v[70:73], v[174:177], 0
	v_mfma_f32_16x16x32_bf16 v[46:49], v[66:69], v[170:173], v[46:49]
	v_mfma_f32_16x16x32_bf16 v[42:45], v[78:81], v[170:173], 0
	v_mfma_f32_16x16x32_bf16 v[42:45], v[86:89], v[174:177], v[42:45]
	v_mfma_f32_16x16x32_bf16 v[58:61], v[86:89], v[166:169], 0
	v_mfma_f32_16x16x32_bf16 v[58:61], v[78:81], v[162:165], v[58:61]
	v_mfma_f32_16x16x32_bf16 v[26:29], v[78:81], v[178:181], 0
	v_mfma_f32_16x16x32_bf16 v[26:29], v[86:89], v[182:185], v[26:29]
	v_mfma_f32_16x16x32_bf16 v[10:13], v[86:89], v[220:223], 0
	v_mfma_f32_16x16x32_bf16 v[10:13], v[78:81], v[216:219], v[10:13]
	v_mfma_f32_16x16x32_bf16 v[14:17], v[66:69], v[216:219], 0
	v_mfma_f32_16x16x32_bf16 v[14:17], v[70:73], v[220:223], v[14:17]
	v_mfma_f32_16x16x32_bf16 v[30:33], v[70:73], v[182:185], 0
	v_mfma_f32_16x16x32_bf16 v[30:33], v[66:69], v[178:181], v[30:33]
	v_mfma_f32_16x16x32_bf16 v[54:57], v[146:149], v[162:165], 0
	v_mfma_f32_16x16x32_bf16 v[54:57], v[150:153], v[166:169], v[54:57]
	v_mfma_f32_16x16x32_bf16 v[38:41], v[150:153], v[174:177], 0
	v_mfma_f32_16x16x32_bf16 v[38:41], v[146:149], v[170:173], v[38:41]
	v_mfma_f32_16x16x32_bf16 v[34:37], v[154:157], v[170:173], 0
	v_mfma_f32_16x16x32_bf16 v[34:37], v[158:161], v[174:177], v[34:37]
	v_mfma_f32_16x16x32_bf16 v[50:53], v[158:161], v[166:169], 0
	v_mfma_f32_16x16x32_bf16 v[50:53], v[154:157], v[162:165], v[50:53]
	v_mfma_f32_16x16x32_bf16 v[18:21], v[154:157], v[178:181], 0
	v_mfma_f32_16x16x32_bf16 v[18:21], v[158:161], v[182:185], v[18:21]
	v_mfma_f32_16x16x32_bf16 v[2:5], v[158:161], v[220:223], 0
	v_mfma_f32_16x16x32_bf16 v[2:5], v[154:157], v[216:219], v[2:5]
	v_mfma_f32_16x16x32_bf16 v[6:9], v[146:149], v[216:219], 0
	v_mfma_f32_16x16x32_bf16 v[6:9], v[150:153], v[220:223], v[6:9]
	v_mfma_f32_16x16x32_bf16 v[22:25], v[150:153], v[182:185], 0
	v_mfma_f32_16x16x32_bf16 v[22:25], v[146:149], v[178:181], v[22:25]
	s_barrier
	s_add_i32 s9, 0, 0x18000
	s_add_i32 s12, 0, 0x1c000
	ds_read_b128 v[66:69], v198
	ds_read_b128 v[70:73], v198 offset:1024
	ds_read_b128 v[78:81], v198 offset:2048
	ds_read_b128 v[86:89], v198 offset:3072
	ds_read_b128 v[146:149], v199
	ds_read_b128 v[150:153], v199 offset:1024
	ds_read_b128 v[154:157], v199 offset:2048
	ds_read_b128 v[158:161], v199 offset:3072
	s_add_u32 s10, s94, 0x80000
	s_addc_u32 s11, s95, 0
	s_mov_b32 m0, s59
	ds_read_b128 v[162:165], v236 offset:32768
	ds_read_b128 v[166:169], v236 offset:33792
	ds_read_b128 v[170:173], v236 offset:34816
	ds_read_b128 v[174:177], v236 offset:35840
	ds_read_b128 v[178:181], v236 offset:36864
	ds_read_b128 v[182:185], v236 offset:37888
	ds_read_b128 v[216:219], v236 offset:38912
	ds_read_b128 v[220:223], v236 offset:39936
	global_load_lds_dwordx4 v210, s[10:11]
	s_mov_b32 m0, s74
	s_nop 0
	global_load_lds_dwordx4 v208, s[10:11]
	s_waitcnt vmcnt(8)
	s_waitcnt lgkmcnt(0)
	s_barrier
	v_mfma_f32_16x16x32_bf16 v[142:145], v[66:69], v[162:165], v[142:145]
	v_mfma_f32_16x16x32_bf16 v[142:145], v[70:73], v[166:169], v[142:145]
	v_mfma_f32_16x16x32_bf16 v[126:129], v[70:73], v[174:177], v[126:129]
	v_mfma_f32_16x16x32_bf16 v[126:129], v[66:69], v[170:173], v[126:129]
	v_mfma_f32_16x16x32_bf16 v[122:125], v[78:81], v[170:173], v[122:125]
	v_mfma_f32_16x16x32_bf16 v[122:125], v[86:89], v[174:177], v[122:125]
	v_mfma_f32_16x16x32_bf16 v[138:141], v[86:89], v[166:169], v[138:141]
	v_mfma_f32_16x16x32_bf16 v[138:141], v[78:81], v[162:165], v[138:141]
	v_mfma_f32_16x16x32_bf16 v[106:109], v[78:81], v[178:181], v[106:109]
	v_mfma_f32_16x16x32_bf16 v[106:109], v[86:89], v[182:185], v[106:109]
	v_mfma_f32_16x16x32_bf16 v[90:93], v[86:89], v[220:223], v[90:93]
	v_mfma_f32_16x16x32_bf16 v[90:93], v[78:81], v[216:219], v[90:93]
	v_mfma_f32_16x16x32_bf16 v[94:97], v[66:69], v[216:219], v[94:97]
	v_mfma_f32_16x16x32_bf16 v[94:97], v[70:73], v[220:223], v[94:97]
	v_mfma_f32_16x16x32_bf16 v[110:113], v[70:73], v[182:185], v[110:113]
	v_mfma_f32_16x16x32_bf16 v[110:113], v[66:69], v[178:181], v[110:113]
	v_mfma_f32_16x16x32_bf16 v[134:137], v[146:149], v[162:165], v[134:137]
	v_mfma_f32_16x16x32_bf16 v[134:137], v[150:153], v[166:169], v[134:137]
	v_mfma_f32_16x16x32_bf16 v[118:121], v[150:153], v[174:177], v[118:121]
	v_mfma_f32_16x16x32_bf16 v[118:121], v[146:149], v[170:173], v[118:121]
	v_mfma_f32_16x16x32_bf16 v[114:117], v[154:157], v[170:173], v[114:117]
	v_mfma_f32_16x16x32_bf16 v[114:117], v[158:161], v[174:177], v[114:117]
	v_mfma_f32_16x16x32_bf16 v[130:133], v[158:161], v[166:169], v[130:133]
	v_mfma_f32_16x16x32_bf16 v[130:133], v[154:157], v[162:165], v[130:133]
	v_mfma_f32_16x16x32_bf16 v[98:101], v[154:157], v[178:181], v[98:101]
	v_mfma_f32_16x16x32_bf16 v[98:101], v[158:161], v[182:185], v[98:101]
	v_mfma_f32_16x16x32_bf16 v[74:77], v[158:161], v[220:223], v[74:77]
	v_mfma_f32_16x16x32_bf16 v[74:77], v[154:157], v[216:219], v[74:77]
	v_mfma_f32_16x16x32_bf16 v[82:85], v[146:149], v[216:219], v[82:85]
	v_mfma_f32_16x16x32_bf16 v[82:85], v[150:153], v[220:223], v[82:85]
	v_mfma_f32_16x16x32_bf16 v[102:105], v[150:153], v[182:185], v[102:105]
	v_mfma_f32_16x16x32_bf16 v[102:105], v[146:149], v[178:181], v[102:105]
	s_barrier
; #define PG8_STAGE(bufoff, gbase, voff) do { _Pragma("unroll") for (int _i = 0; _i < 2; ++_i) \
;         __builtin_amdgcn_global_load_lds((const unsigned*)((const char*)(gbase) + (voff)[_i]), (PG8_LAS unsigned*)(lds + (bufoff) + ldsw + _i * 8192), 16, 0, 0); } while (0)
; #define PG8_LDA(dst, b, h) do { _Pragma("unroll") for (int m = 0; m < 4; ++m) _Pragma("unroll") for (int k = 0; k < 2; ++k) dst[m][k] = *(const PG8_LAS bf16x8*)(lds + PG8_SA(b, h) + aoff + m * 2048 + k * 1024); } while (0)
; #define PG8_LDB(dst, b, h) do { _Pragma("unroll") for (int n = 0; n < 2; ++n) _Pragma("unroll") for (int k = 0; k < 2; ++k) dst[n][k] = *(const PG8_LAS bf16x8*)(lds + PG8_SB(b, h) + boff + n * 2048 + k * 1024); } while (0)
; template <class Epi, class Sched, bool ALIGN_EPI = false, bool SP2 = false>
; __device__ __forceinline__ void gemm_phase(PG8_LAS unsigned char* lds, const Gemm g, const Sched& S, const Epi& E) {
;     ...
;         for (int t = 0; t < nt; t += 2) {
;             const bool last = (t == nt - 2);
;             const char* a1 = cA + (size_t)(t + 1) * kstep;
;             const char* a2 = last ? nA : cA + (size_t)(t + 2) * kstep; const char* b2 = last ? nB : cB + (size_t)(t + 2) * kstep;
;             const char* a3 = a2 + kstep; const char* b3 = b2 + kstep;
;             if (last && has_next) S.a_ready(nxt);
;             if constexpr (SP2) {
;             PG8_LDB(B0, 0, 0); PG8_LDB(B1, 0, 1); PG8_SCHED; PG8_LDA(At, 0, 0); PG8_STAGE(PG8_SA(1, 1), a1 + hstep, voffA);
;             PG8_WAIT_V(8); PG8_WAIT_L(0); PG8_BAR; PG8_MMA(0, 0, At, B0); PG8_MMA(0, 1, At, B1); PG8_BAR; PG8_SCHED;
;             PG8_LDA(At, 0, 1); PG8_STAGE(PG8_SB(0, 0), b2, voffB); PG8_STAGE(PG8_SB(0, 1), b2 + hstepB, voffB); PG8_STAGE(PG8_SA(0, 0), a2, voffA);
;             PG8_WAIT_V(8); PG8_WAIT_L(0); PG8_BAR; PG8_MMA(1, 0, At, B0); PG8_MMA(1, 1, At, B1); PG8_BAR; PG8_SCHED;
;             PG8_LDB(B0, 1, 0); PG8_LDB(B1, 1, 1); PG8_SCHED; PG8_LDA(At, 1, 0); PG8_STAGE(PG8_SA(0, 1), a2 + hstep, voffA);
;             PG8_WAIT_V(8); PG8_WAIT_L(0); PG8_BAR; PG8_MMA(0, 0, At, B0); PG8_MMA(0, 1, At, B1); PG8_BAR; PG8_SCHED;
;             PG8_LDA(At, 1, 1); PG8_STAGE(PG8_SB(1, 0), b3, voffB); PG8_STAGE(PG8_SB(1, 1), b3 + hstepB, voffB); PG8_STAGE(PG8_SA(1, 0), a3, voffA);
;             PG8_WAIT_V(8); PG8_WAIT_L(0); PG8_BAR; PG8_MMA(1, 0, At, B0); PG8_MMA(1, 1, At, B1); PG8_BAR; PG8_SCHED;
	s_add_i32 s9, s9, s25
	s_mov_b32 m0, s9
	ds_read_b128 v[162:165], v236 offset:49152
	ds_read_b128 v[166:169], v236 offset:50176
	ds_read_b128 v[170:173], v236 offset:51200
	ds_read_b128 v[174:177], v236 offset:52224
	ds_read_b128 v[178:181], v236 offset:53248
	ds_read_b128 v[182:185], v236 offset:54272
	ds_read_b128 v[216:219], v236 offset:55296
	ds_read_b128 v[220:223], v236 offset:56320
	s_add_u32 s100, s46, s60
	s_addc_u32 s101, s47, s61
	global_load_lds_dwordx4 v190, s[100:101]
	s_add_i32 m0, s9, 0x2000
	s_add_u32 s10, s46, 0x20080
	s_addc_u32 s11, s47, 0
	s_add_i32 s9, s12, s25
	global_load_lds_dwordx4 v206, s[100:101]
	s_mov_b32 m0, s9
	s_nop 0
	global_load_lds_dwordx4 v190, s[10:11]
	s_add_i32 m0, s9, 0x2000
	s_nop 0
	global_load_lds_dwordx4 v206, s[10:11]
	s_mov_b32 m0, s75
	s_add_u32 s100, s94, s60
	s_addc_u32 s101, s95, s61
	global_load_lds_dwordx4 v210, s[100:101]
	s_mov_b32 m0, s0
	s_nop 0
	global_load_lds_dwordx4 v208, s[100:101]
	s_waitcnt vmcnt(8)
	s_waitcnt lgkmcnt(0)
	s_barrier
	v_mfma_f32_16x16x32_bf16 v[62:65], v[66:69], v[162:165], v[62:65]
	v_mfma_f32_16x16x32_bf16 v[62:65], v[70:73], v[166:169], v[62:65]
	v_mfma_f32_16x16x32_bf16 v[46:49], v[70:73], v[174:177], v[46:49]
	v_mfma_f32_16x16x32_bf16 v[46:49], v[66:69], v[170:173], v[46:49]
	v_mfma_f32_16x16x32_bf16 v[42:45], v[78:81], v[170:173], v[42:45]
	v_mfma_f32_16x16x32_bf16 v[42:45], v[86:89], v[174:177], v[42:45]
	v_mfma_f32_16x16x32_bf16 v[58:61], v[86:89], v[166:169], v[58:61]
	v_mfma_f32_16x16x32_bf16 v[58:61], v[78:81], v[162:165], v[58:61]
	v_mfma_f32_16x16x32_bf16 v[26:29], v[78:81], v[178:181], v[26:29]
	v_mfma_f32_16x16x32_bf16 v[26:29], v[86:89], v[182:185], v[26:29]
	v_mfma_f32_16x16x32_bf16 v[10:13], v[86:89], v[220:223], v[10:13]
	v_mfma_f32_16x16x32_bf16 v[10:13], v[78:81], v[216:219], v[10:13]
	v_mfma_f32_16x16x32_bf16 v[14:17], v[66:69], v[216:219], v[14:17]
	v_mfma_f32_16x16x32_bf16 v[14:17], v[70:73], v[220:223], v[14:17]
	v_mfma_f32_16x16x32_bf16 v[30:33], v[70:73], v[182:185], v[30:33]
	v_mfma_f32_16x16x32_bf16 v[30:33], v[66:69], v[178:181], v[30:33]
	v_mfma_f32_16x16x32_bf16 v[54:57], v[146:149], v[162:165], v[54:57]
	v_mfma_f32_16x16x32_bf16 v[54:57], v[150:153], v[166:169], v[54:57]
	v_mfma_f32_16x16x32_bf16 v[38:41], v[150:153], v[174:177], v[38:41]
	v_mfma_f32_16x16x32_bf16 v[38:41], v[146:149], v[170:173], v[38:41]
	v_mfma_f32_16x16x32_bf16 v[34:37], v[154:157], v[170:173], v[34:37]
	v_mfma_f32_16x16x32_bf16 v[34:37], v[158:161], v[174:177], v[34:37]
	v_mfma_f32_16x16x32_bf16 v[50:53], v[158:161], v[166:169], v[50:53]
	v_mfma_f32_16x16x32_bf16 v[50:53], v[154:157], v[162:165], v[50:53]
	v_mfma_f32_16x16x32_bf16 v[18:21], v[154:157], v[178:181], v[18:21]
	v_mfma_f32_16x16x32_bf16 v[18:21], v[158:161], v[182:185], v[18:21]
	v_mfma_f32_16x16x32_bf16 v[2:5], v[158:161], v[220:223], v[2:5]
	v_mfma_f32_16x16x32_bf16 v[2:5], v[154:157], v[216:219], v[2:5]
	v_mfma_f32_16x16x32_bf16 v[6:9], v[146:149], v[216:219], v[6:9]
	v_mfma_f32_16x16x32_bf16 v[6:9], v[150:153], v[220:223], v[6:9]
	v_mfma_f32_16x16x32_bf16 v[22:25], v[150:153], v[182:185], v[22:25]
	v_mfma_f32_16x16x32_bf16 v[22:25], v[146:149], v[178:181], v[22:25]
	s_barrier
	s_add_i32 s8, s8, 2
	s_add_u32 s38, s38, 0x100
	s_addc_u32 s39, s39, 0
	s_add_u32 s6, s6, 0x100
	s_addc_u32 s7, s7, 0
	s_cmp_gt_u32 s8, 29
.LBB0_927:
	s_add_u32 s9, s38, 0xfff80080
	s_addc_u32 s10, s39, -1
	s_add_i32 s11, 0, 0x10000
	s_cmp_eq_u32 s8, 28
	s_cselect_b32 s95, s36, s10
	s_cselect_b32 s94, s37, s9
	s_cselect_b32 s47, s4, s7
	s_cselect_b32 s46, s5, s6
	s_add_i32 s9, 0, 0x14000
	ds_read_b128 v[66:69], v186
	ds_read_b128 v[70:73], v186 offset:1024
	ds_read_b128 v[78:81], v186 offset:2048
	ds_read_b128 v[86:89], v186 offset:3072
	ds_read_b128 v[146:149], v187
	ds_read_b128 v[150:153], v187 offset:1024
	ds_read_b128 v[154:157], v187 offset:2048
	ds_read_b128 v[158:161], v187 offset:3072
	s_add_i32 m0, s66, 0xc000
	ds_read_b128 v[162:165], v236
	ds_read_b128 v[166:169], v236 offset:1024
	ds_read_b128 v[170:173], v236 offset:2048
	ds_read_b128 v[174:177], v236 offset:3072
	ds_read_b128 v[178:181], v236 offset:4096
	ds_read_b128 v[182:185], v236 offset:5120
	ds_read_b128 v[216:219], v236 offset:6144
	ds_read_b128 v[220:223], v236 offset:7168
	global_load_lds_dwordx4 v212, s[38:39]
	s_add_i32 m0, s66, 0xe000
	s_nop 0
	global_load_lds_dwordx4 v214, s[38:39]
	s_waitcnt vmcnt(8)
	s_waitcnt lgkmcnt(0)
	s_barrier
	v_mfma_f32_16x16x32_bf16 v[142:145], v[66:69], v[162:165], v[142:145]
	v_mfma_f32_16x16x32_bf16 v[142:145], v[70:73], v[166:169], v[142:145]
	v_mfma_f32_16x16x32_bf16 v[126:129], v[70:73], v[174:177], v[126:129]
	v_mfma_f32_16x16x32_bf16 v[126:129], v[66:69], v[170:173], v[126:129]
	v_mfma_f32_16x16x32_bf16 v[122:125], v[78:81], v[170:173], v[122:125]
	v_mfma_f32_16x16x32_bf16 v[122:125], v[86:89], v[174:177], v[122:125]
	v_mfma_f32_16x16x32_bf16 v[138:141], v[86:89], v[166:169], v[138:141]
	v_mfma_f32_16x16x32_bf16 v[138:141], v[78:81], v[162:165], v[138:141]
	v_mfma_f32_16x16x32_bf16 v[106:109], v[78:81], v[178:181], v[106:109]
	v_mfma_f32_16x16x32_bf16 v[106:109], v[86:89], v[182:185], v[106:109]
	v_mfma_f32_16x16x32_bf16 v[90:93], v[86:89], v[220:223], v[90:93]
	v_mfma_f32_16x16x32_bf16 v[90:93], v[78:81], v[216:219], v[90:93]
	v_mfma_f32_16x16x32_bf16 v[94:97], v[66:69], v[216:219], v[94:97]
	v_mfma_f32_16x16x32_bf16 v[94:97], v[70:73], v[220:223], v[94:97]
	v_mfma_f32_16x16x32_bf16 v[110:113], v[70:73], v[182:185], v[110:113]
	v_mfma_f32_16x16x32_bf16 v[110:113], v[66:69], v[178:181], v[110:113]
	v_mfma_f32_16x16x32_bf16 v[134:137], v[146:149], v[162:165], v[134:137]
	v_mfma_f32_16x16x32_bf16 v[134:137], v[150:153], v[166:169], v[134:137]
	v_mfma_f32_16x16x32_bf16 v[118:121], v[150:153], v[174:177], v[118:121]
	v_mfma_f32_16x16x32_bf16 v[118:121], v[146:149], v[170:173], v[118:121]
	v_mfma_f32_16x16x32_bf16 v[114:117], v[154:157], v[170:173], v[114:117]
	v_mfma_f32_16x16x32_bf16 v[114:117], v[158:161], v[174:177], v[114:117]
	v_mfma_f32_16x16x32_bf16 v[130:133], v[158:161], v[166:169], v[130:133]
	v_mfma_f32_16x16x32_bf16 v[130:133], v[154:157], v[162:165], v[130:133]
	v_mfma_f32_16x16x32_bf16 v[98:101], v[154:157], v[178:181], v[98:101]
	v_mfma_f32_16x16x32_bf16 v[98:101], v[158:161], v[182:185], v[98:101]
	v_mfma_f32_16x16x32_bf16 v[74:77], v[158:161], v[220:223], v[74:77]
	v_mfma_f32_16x16x32_bf16 v[74:77], v[154:157], v[216:219], v[74:77]
	v_mfma_f32_16x16x32_bf16 v[82:85], v[146:149], v[216:219], v[82:85]
	v_mfma_f32_16x16x32_bf16 v[82:85], v[150:153], v[220:223], v[82:85]
	v_mfma_f32_16x16x32_bf16 v[102:105], v[150:153], v[182:185], v[102:105]
	v_mfma_f32_16x16x32_bf16 v[102:105], v[146:149], v[178:181], v[102:105]
	s_barrier
; #define PG8_STAGE(bufoff, gbase, voff) do { _Pragma("unroll") for (int _i = 0; _i < 2; ++_i) \
;         __builtin_amdgcn_global_load_lds((const unsigned*)((const char*)(gbase) + (voff)[_i]), (PG8_LAS unsigned*)(lds + (bufoff) + ldsw + _i * 8192), 16, 0, 0); } while (0)
; #define PG8_LDA(dst, b, h) do { _Pragma("unroll") for (int m = 0; m < 4; ++m) _Pragma("unroll") for (int k = 0; k < 2; ++k) dst[m][k] = *(const PG8_LAS bf16x8*)(lds + PG8_SA(b, h) + aoff + m * 2048 + k * 1024); } while (0)
; #define PG8_LDB(dst, b, h) do { _Pragma("unroll") for (int n = 0; n < 2; ++n) _Pragma("unroll") for (int k = 0; k < 2; ++k) dst[n][k] = *(const PG8_LAS bf16x8*)(lds + PG8_SB(b, h) + boff + n * 2048 + k * 1024); } while (0)
; #define PG8_MMA(ai, bj, At, Bt) do { __builtin_amdgcn_s_setprio(1); _Pragma("unroll") for (int m = 0; m < 4; ++m) _Pragma("unroll") for (int n = 0; n < 2; ++n) _Pragma("unroll") for (int k = 0; k < 2; ++k) \
;         acc[ai][bj][m][n] = __builtin_amdgcn_mfma_f32_16x16x32_bf16(Bt[n][k], At[m][k], acc[ai][bj][m][n], 0, 0, 0); __builtin_amdgcn_s_setprio(0); } while (0)
; template <class Epi, class Sched, bool ALIGN_EPI = false, bool SP2 = false>
; __device__ __forceinline__ void gemm_phase(PG8_LAS unsigned char* lds, const Gemm g, const Sched& S, const Epi& E) {
;     ...
;         for (int t = 0; t < nt; t += 2) {
;             const bool last = (t == nt - 2);
;             const char* a1 = cA + (size_t)(t + 1) * kstep;
;             const char* a2 = last ? nA : cA + (size_t)(t + 2) * kstep; const char* b2 = last ? nB : cB + (size_t)(t + 2) * kstep;
;             const char* a3 = a2 + kstep; const char* b3 = b2 + kstep;
;             if (last && has_next) S.a_ready(nxt);
;             if constexpr (SP2) {
;             PG8_LDB(B0, 0, 0); PG8_LDB(B1, 0, 1); PG8_SCHED; PG8_LDA(At, 0, 0); PG8_STAGE(PG8_SA(1, 1), a1 + hstep, voffA);
;             PG8_WAIT_V(8); PG8_WAIT_L(0); PG8_BAR; PG8_MMA(0, 0, At, B0); PG8_MMA(0, 1, At, B1); PG8_BAR; PG8_SCHED;
;             PG8_LDA(At, 0, 1); PG8_STAGE(PG8_SB(0, 0), b2, voffB); PG8_STAGE(PG8_SB(0, 1), b2 + hstepB, voffB); PG8_STAGE(PG8_SA(0, 0), a2, voffA);
;             PG8_WAIT_V(8); PG8_WAIT_L(0); PG8_BAR; PG8_MMA(1, 0, At, B0); PG8_MMA(1, 1, At, B1); PG8_BAR; PG8_SCHED;
;             PG8_LDB(B0, 1, 0); PG8_LDB(B1, 1, 1); PG8_SCHED; PG8_LDA(At, 1, 0); PG8_STAGE(PG8_SA(0, 1), a2 + hstep, voffA);
	s_add_i32 s10, s11, s25
	s_mov_b32 m0, s10
	ds_read_b128 v[162:165], v236 offset:16384
	ds_read_b128 v[166:169], v236 offset:17408
	ds_read_b128 v[170:173], v236 offset:18432
	ds_read_b128 v[174:177], v236 offset:19456
	ds_read_b128 v[178:181], v236 offset:20480
	ds_read_b128 v[182:185], v236 offset:21504
	ds_read_b128 v[216:219], v236 offset:22528
	ds_read_b128 v[220:223], v236 offset:23552
	global_load_lds_dwordx4 v190, s[46:47]
	s_add_i32 m0, s10, 0x2000
	s_add_u32 s10, s46, 0x20000
	s_addc_u32 s11, s47, 0
	s_add_i32 s9, s9, s25
	global_load_lds_dwordx4 v206, s[46:47]
	s_mov_b32 m0, s9
	s_nop 0
	global_load_lds_dwordx4 v190, s[10:11]
	s_add_i32 m0, s9, 0x2000
	s_nop 0
	global_load_lds_dwordx4 v206, s[10:11]
	s_mov_b32 m0, s66
	s_nop 0
	global_load_lds_dwordx4 v210, s[94:95]
	s_mov_b32 m0, s67
	s_nop 0
	global_load_lds_dwordx4 v208, s[94:95]
	s_waitcnt vmcnt(8)
	s_waitcnt lgkmcnt(0)
	s_barrier
	v_mfma_f32_16x16x32_bf16 v[62:65], v[66:69], v[162:165], v[62:65]
	v_mfma_f32_16x16x32_bf16 v[62:65], v[70:73], v[166:169], v[62:65]
	v_mfma_f32_16x16x32_bf16 v[46:49], v[70:73], v[174:177], v[46:49]
	v_mfma_f32_16x16x32_bf16 v[46:49], v[66:69], v[170:173], v[46:49]
	v_mfma_f32_16x16x32_bf16 v[42:45], v[78:81], v[170:173], v[42:45]
	v_mfma_f32_16x16x32_bf16 v[42:45], v[86:89], v[174:177], v[42:45]
	v_mfma_f32_16x16x32_bf16 v[58:61], v[86:89], v[166:169], v[58:61]
	v_mfma_f32_16x16x32_bf16 v[58:61], v[78:81], v[162:165], v[58:61]
	v_mfma_f32_16x16x32_bf16 v[26:29], v[78:81], v[178:181], v[26:29]
	v_mfma_f32_16x16x32_bf16 v[26:29], v[86:89], v[182:185], v[26:29]
	v_mfma_f32_16x16x32_bf16 v[10:13], v[86:89], v[220:223], v[10:13]
	v_mfma_f32_16x16x32_bf16 v[10:13], v[78:81], v[216:219], v[10:13]
	v_mfma_f32_16x16x32_bf16 v[14:17], v[66:69], v[216:219], v[14:17]
	v_mfma_f32_16x16x32_bf16 v[14:17], v[70:73], v[220:223], v[14:17]
	v_mfma_f32_16x16x32_bf16 v[30:33], v[70:73], v[182:185], v[30:33]
	v_mfma_f32_16x16x32_bf16 v[30:33], v[66:69], v[178:181], v[30:33]
	v_mfma_f32_16x16x32_bf16 v[54:57], v[146:149], v[162:165], v[54:57]
	v_mfma_f32_16x16x32_bf16 v[54:57], v[150:153], v[166:169], v[54:57]
	v_mfma_f32_16x16x32_bf16 v[38:41], v[150:153], v[174:177], v[38:41]
	v_mfma_f32_16x16x32_bf16 v[38:41], v[146:149], v[170:173], v[38:41]
	v_mfma_f32_16x16x32_bf16 v[34:37], v[154:157], v[170:173], v[34:37]
	v_mfma_f32_16x16x32_bf16 v[34:37], v[158:161], v[174:177], v[34:37]
	v_mfma_f32_16x16x32_bf16 v[50:53], v[158:161], v[166:169], v[50:53]
	v_mfma_f32_16x16x32_bf16 v[50:53], v[154:157], v[162:165], v[50:53]
	v_mfma_f32_16x16x32_bf16 v[18:21], v[154:157], v[178:181], v[18:21]
	v_mfma_f32_16x16x32_bf16 v[18:21], v[158:161], v[182:185], v[18:21]
	v_mfma_f32_16x16x32_bf16 v[2:5], v[158:161], v[220:223], v[2:5]
	v_mfma_f32_16x16x32_bf16 v[2:5], v[154:157], v[216:219], v[2:5]
	v_mfma_f32_16x16x32_bf16 v[6:9], v[146:149], v[216:219], v[6:9]
	v_mfma_f32_16x16x32_bf16 v[6:9], v[150:153], v[220:223], v[6:9]
	v_mfma_f32_16x16x32_bf16 v[22:25], v[150:153], v[182:185], v[22:25]
	v_mfma_f32_16x16x32_bf16 v[22:25], v[146:149], v[178:181], v[22:25]
	s_barrier
	s_add_i32 s9, 0, 0x18000
	s_add_i32 s12, 0, 0x1c000
	ds_read_b128 v[66:69], v198
	ds_read_b128 v[70:73], v198 offset:1024
	ds_read_b128 v[78:81], v198 offset:2048
	ds_read_b128 v[86:89], v198 offset:3072
	ds_read_b128 v[146:149], v199
	ds_read_b128 v[150:153], v199 offset:1024
	ds_read_b128 v[154:157], v199 offset:2048
	ds_read_b128 v[158:161], v199 offset:3072
	s_add_u32 s10, s94, 0x80000
	s_addc_u32 s11, s95, 0
	s_mov_b32 m0, s59
	ds_read_b128 v[162:165], v236 offset:32768
	ds_read_b128 v[166:169], v236 offset:33792
	ds_read_b128 v[170:173], v236 offset:34816
	ds_read_b128 v[174:177], v236 offset:35840
	ds_read_b128 v[178:181], v236 offset:36864
	ds_read_b128 v[182:185], v236 offset:37888
	ds_read_b128 v[216:219], v236 offset:38912
	ds_read_b128 v[220:223], v236 offset:39936
	global_load_lds_dwordx4 v210, s[10:11]
	s_mov_b32 m0, s74
	s_nop 0
	global_load_lds_dwordx4 v208, s[10:11]
	s_waitcnt vmcnt(8)
	s_waitcnt lgkmcnt(0)
	s_barrier
; #define PG8_STAGE(bufoff, gbase, voff) do { _Pragma("unroll") for (int _i = 0; _i < 2; ++_i) \
;         __builtin_amdgcn_global_load_lds((const unsigned*)((const char*)(gbase) + (voff)[_i]), (PG8_LAS unsigned*)(lds + (bufoff) + ldsw + _i * 8192), 16, 0, 0); } while (0)
; #define PG8_LDA(dst, b, h) do { _Pragma("unroll") for (int m = 0; m < 4; ++m) _Pragma("unroll") for (int k = 0; k < 2; ++k) dst[m][k] = *(const PG8_LAS bf16x8*)(lds + PG8_SA(b, h) + aoff + m * 2048 + k * 1024); } while (0)
; #define PG8_LDB(dst, b, h) do { _Pragma("unroll") for (int n = 0; n < 2; ++n) _Pragma("unroll") for (int k = 0; k < 2; ++k) dst[n][k] = *(const PG8_LAS bf16x8*)(lds + PG8_SB(b, h) + boff + n * 2048 + k * 1024); } while (0)
; template <class Epi, class Sched, bool ALIGN_EPI = false, bool SP2 = false>
; __device__ __forceinline__ void gemm_phase(PG8_LAS unsigned char* lds, const Gemm g, const Sched& S, const Epi& E) {
;     ...
;         for (int t = 0; t < nt; t += 2) {
;             const bool last = (t == nt - 2);
;             const char* a1 = cA + (size_t)(t + 1) * kstep;
;             const char* a2 = last ? nA : cA + (size_t)(t + 2) * kstep; const char* b2 = last ? nB : cB + (size_t)(t + 2) * kstep;
;             const char* a3 = a2 + kstep; const char* b3 = b2 + kstep;
;             if (last && has_next) S.a_ready(nxt);
;             if constexpr (SP2) {
;             PG8_LDB(B0, 0, 0); PG8_LDB(B1, 0, 1); PG8_SCHED; PG8_LDA(At, 0, 0); PG8_STAGE(PG8_SA(1, 1), a1 + hstep, voffA);
;             PG8_WAIT_V(8); PG8_WAIT_L(0); PG8_BAR; PG8_MMA(0, 0, At, B0); PG8_MMA(0, 1, At, B1); PG8_BAR; PG8_SCHED;
;             PG8_LDA(At, 0, 1); PG8_STAGE(PG8_SB(0, 0), b2, voffB); PG8_STAGE(PG8_SB(0, 1), b2 + hstepB, voffB); PG8_STAGE(PG8_SA(0, 0), a2, voffA);
;             PG8_WAIT_V(8); PG8_WAIT_L(0); PG8_BAR; PG8_MMA(1, 0, At, B0); PG8_MMA(1, 1, At, B1); PG8_BAR; PG8_SCHED;
;             PG8_LDB(B0, 1, 0); PG8_LDB(B1, 1, 1); PG8_SCHED; PG8_LDA(At, 1, 0); PG8_STAGE(PG8_SA(0, 1), a2 + hstep, voffA);
;             PG8_WAIT_V(8); PG8_WAIT_L(0); PG8_BAR; PG8_MMA(0, 0, At, B0); PG8_MMA(0, 1, At, B1); PG8_BAR; PG8_SCHED;
;             PG8_LDA(At, 1, 1); PG8_STAGE(PG8_SB(1, 0), b3, voffB); PG8_STAGE(PG8_SB(1, 1), b3 + hstepB, voffB); PG8_STAGE(PG8_SA(1, 0), a3, voffA);
;             PG8_WAIT_V(8); PG8_WAIT_L(0); PG8_BAR; PG8_MMA(1, 0, At, B0); PG8_MMA(1, 1, At, B1); PG8_BAR; PG8_SCHED;
	v_mfma_f32_16x16x32_bf16 v[142:145], v[66:69], v[162:165], v[142:145]
	v_mfma_f32_16x16x32_bf16 v[142:145], v[70:73], v[166:169], v[142:145]
	v_mfma_f32_16x16x32_bf16 v[126:129], v[70:73], v[174:177], v[126:129]
	v_mfma_f32_16x16x32_bf16 v[126:129], v[66:69], v[170:173], v[126:129]
	v_mfma_f32_16x16x32_bf16 v[122:125], v[78:81], v[170:173], v[122:125]
	v_mfma_f32_16x16x32_bf16 v[122:125], v[86:89], v[174:177], v[122:125]
	v_mfma_f32_16x16x32_bf16 v[138:141], v[86:89], v[166:169], v[138:141]
	v_mfma_f32_16x16x32_bf16 v[138:141], v[78:81], v[162:165], v[138:141]
	v_mfma_f32_16x16x32_bf16 v[106:109], v[78:81], v[178:181], v[106:109]
	v_mfma_f32_16x16x32_bf16 v[106:109], v[86:89], v[182:185], v[106:109]
	v_mfma_f32_16x16x32_bf16 v[90:93], v[86:89], v[220:223], v[90:93]
	v_mfma_f32_16x16x32_bf16 v[90:93], v[78:81], v[216:219], v[90:93]
	v_mfma_f32_16x16x32_bf16 v[94:97], v[66:69], v[216:219], v[94:97]
	v_mfma_f32_16x16x32_bf16 v[94:97], v[70:73], v[220:223], v[94:97]
	v_mfma_f32_16x16x32_bf16 v[110:113], v[70:73], v[182:185], v[110:113]
	v_mfma_f32_16x16x32_bf16 v[110:113], v[66:69], v[178:181], v[110:113]
	v_mfma_f32_16x16x32_bf16 v[134:137], v[146:149], v[162:165], v[134:137]
	v_mfma_f32_16x16x32_bf16 v[134:137], v[150:153], v[166:169], v[134:137]
	v_mfma_f32_16x16x32_bf16 v[118:121], v[150:153], v[174:177], v[118:121]
	v_mfma_f32_16x16x32_bf16 v[118:121], v[146:149], v[170:173], v[118:121]
	v_mfma_f32_16x16x32_bf16 v[114:117], v[154:157], v[170:173], v[114:117]
	v_mfma_f32_16x16x32_bf16 v[114:117], v[158:161], v[174:177], v[114:117]
	v_mfma_f32_16x16x32_bf16 v[130:133], v[158:161], v[166:169], v[130:133]
	v_mfma_f32_16x16x32_bf16 v[130:133], v[154:157], v[162:165], v[130:133]
	v_mfma_f32_16x16x32_bf16 v[98:101], v[154:157], v[178:181], v[98:101]
	v_mfma_f32_16x16x32_bf16 v[98:101], v[158:161], v[182:185], v[98:101]
	v_mfma_f32_16x16x32_bf16 v[74:77], v[158:161], v[220:223], v[74:77]
	v_mfma_f32_16x16x32_bf16 v[74:77], v[154:157], v[216:219], v[74:77]
	v_mfma_f32_16x16x32_bf16 v[82:85], v[146:149], v[216:219], v[82:85]
	v_mfma_f32_16x16x32_bf16 v[82:85], v[150:153], v[220:223], v[82:85]
	v_mfma_f32_16x16x32_bf16 v[102:105], v[150:153], v[182:185], v[102:105]
	v_mfma_f32_16x16x32_bf16 v[102:105], v[146:149], v[178:181], v[102:105]
	s_barrier
	s_add_i32 s9, s9, s25
	s_mov_b32 m0, s9
	ds_read_b128 v[162:165], v236 offset:49152
	ds_read_b128 v[166:169], v236 offset:50176
	ds_read_b128 v[170:173], v236 offset:51200
	ds_read_b128 v[174:177], v236 offset:52224
	ds_read_b128 v[178:181], v236 offset:53248
	ds_read_b128 v[182:185], v236 offset:54272
	ds_read_b128 v[216:219], v236 offset:55296
	ds_read_b128 v[220:223], v236 offset:56320
	s_add_u32 s100, s46, s60
	s_addc_u32 s101, s47, s61
	global_load_lds_dwordx4 v190, s[100:101]
	s_add_i32 m0, s9, 0x2000
	s_add_u32 s10, s46, 0x20080
	s_addc_u32 s11, s47, 0
	s_add_i32 s9, s12, s25
	global_load_lds_dwordx4 v206, s[100:101]
	s_mov_b32 m0, s9
	s_nop 0
	global_load_lds_dwordx4 v190, s[10:11]
	s_add_i32 m0, s9, 0x2000
	s_nop 0
	global_load_lds_dwordx4 v206, s[10:11]
	s_mov_b32 m0, s75
	s_add_u32 s100, s94, s60
	s_addc_u32 s101, s95, s61
	global_load_lds_dwordx4 v210, s[100:101]
	s_mov_b32 m0, s0
	s_nop 0
	global_load_lds_dwordx4 v208, s[100:101]
	s_waitcnt vmcnt(8)
	s_waitcnt lgkmcnt(0)
	s_barrier
	v_mfma_f32_16x16x32_bf16 v[62:65], v[66:69], v[162:165], v[62:65]
	v_mfma_f32_16x16x32_bf16 v[62:65], v[70:73], v[166:169], v[62:65]
	v_mfma_f32_16x16x32_bf16 v[46:49], v[70:73], v[174:177], v[46:49]
	v_mfma_f32_16x16x32_bf16 v[46:49], v[66:69], v[170:173], v[46:49]
	v_mfma_f32_16x16x32_bf16 v[42:45], v[78:81], v[170:173], v[42:45]
	v_mfma_f32_16x16x32_bf16 v[42:45], v[86:89], v[174:177], v[42:45]
	v_mfma_f32_16x16x32_bf16 v[58:61], v[86:89], v[166:169], v[58:61]
	v_mfma_f32_16x16x32_bf16 v[58:61], v[78:81], v[162:165], v[58:61]
	v_mfma_f32_16x16x32_bf16 v[26:29], v[78:81], v[178:181], v[26:29]
	v_mfma_f32_16x16x32_bf16 v[26:29], v[86:89], v[182:185], v[26:29]
	v_mfma_f32_16x16x32_bf16 v[10:13], v[86:89], v[220:223], v[10:13]
	v_mfma_f32_16x16x32_bf16 v[10:13], v[78:81], v[216:219], v[10:13]
	v_mfma_f32_16x16x32_bf16 v[14:17], v[66:69], v[216:219], v[14:17]
	v_mfma_f32_16x16x32_bf16 v[14:17], v[70:73], v[220:223], v[14:17]
	v_mfma_f32_16x16x32_bf16 v[30:33], v[70:73], v[182:185], v[30:33]
	v_mfma_f32_16x16x32_bf16 v[30:33], v[66:69], v[178:181], v[30:33]
	v_mfma_f32_16x16x32_bf16 v[54:57], v[146:149], v[162:165], v[54:57]
	v_mfma_f32_16x16x32_bf16 v[54:57], v[150:153], v[166:169], v[54:57]
	v_mfma_f32_16x16x32_bf16 v[38:41], v[150:153], v[174:177], v[38:41]
	v_mfma_f32_16x16x32_bf16 v[38:41], v[146:149], v[170:173], v[38:41]
	v_mfma_f32_16x16x32_bf16 v[34:37], v[154:157], v[170:173], v[34:37]
	v_mfma_f32_16x16x32_bf16 v[34:37], v[158:161], v[174:177], v[34:37]
	v_mfma_f32_16x16x32_bf16 v[50:53], v[158:161], v[166:169], v[50:53]
	v_mfma_f32_16x16x32_bf16 v[50:53], v[154:157], v[162:165], v[50:53]
	v_mfma_f32_16x16x32_bf16 v[18:21], v[154:157], v[178:181], v[18:21]
	v_mfma_f32_16x16x32_bf16 v[18:21], v[158:161], v[182:185], v[18:21]
	v_mfma_f32_16x16x32_bf16 v[2:5], v[158:161], v[220:223], v[2:5]
	v_mfma_f32_16x16x32_bf16 v[2:5], v[154:157], v[216:219], v[2:5]
	v_mfma_f32_16x16x32_bf16 v[6:9], v[146:149], v[216:219], v[6:9]
	v_mfma_f32_16x16x32_bf16 v[6:9], v[150:153], v[220:223], v[6:9]
	v_mfma_f32_16x16x32_bf16 v[22:25], v[150:153], v[182:185], v[22:25]
	v_mfma_f32_16x16x32_bf16 v[22:25], v[146:149], v[178:181], v[22:25]
	s_barrier
	s_add_i32 s8, s8, 2
	s_add_u32 s38, s38, 0x100
	s_addc_u32 s39, s39, 0
	s_add_u32 s6, s6, 0x100
	s_addc_u32 s7, s7, 0
	s_cmp_gt_u32 s8, 29
	s_cbranch_scc0 .LBB0_927
	s_and_b64 vcc, exec, s[70:71]
	s_cbranch_vccz .LBB0_930
	s_barrier

; #define PG8_STAGE(bufoff, gbase, voff) do { _Pragma("unroll") for (int _i = 0; _i < 2; ++_i) \
;         __builtin_amdgcn_global_load_lds((const unsigned*)((const char*)(gbase) + (voff)[_i]), (PG8_LAS unsigned*)(lds + (bufoff) + ldsw + _i * 8192), 16, 0, 0); } while (0)
; #define PG8_LDA(dst, b, h) do { _Pragma("unroll") for (int m = 0; m < 4; ++m) _Pragma("unroll") for (int k = 0; k < 2; ++k) dst[m][k] = *(const PG8_LAS bf16x8*)(lds + PG8_SA(b, h) + aoff + m * 2048 + k * 1024); } while (0)
; #define PG8_LDB(dst, b, h) do { _Pragma("unroll") for (int n = 0; n < 2; ++n) _Pragma("unroll") for (int k = 0; k < 2; ++k) dst[n][k] = *(const PG8_LAS bf16x8*)(lds + PG8_SB(b, h) + boff + n * 2048 + k * 1024); } while (0)
; #define PG8_WAIT_V(n) asm volatile("s_waitcnt vmcnt(" #n ")" ::: "memory")
; template <class Epi, class Sched, bool ALIGN_EPI = false, bool SP2 = false>
; __device__ __forceinline__ void gemm_phase(PG8_LAS unsigned char* lds, const Gemm g, const Sched& S, const Epi& E) {
;     ...
;     f32x4 acc[2][2][4][2];
; #pragma unroll
;     for (int a = 0; a < 2; ++a)
; #pragma unroll
;         for (int b = 0; b < 2; ++b)
; #pragma unroll
;             for (int m = 0; m < 4; ++m)
; #pragma unroll
;                 for (int n = 0; n < 2; ++n) acc[a][b][m][n] = (f32x4){0.f, 0.f, 0.f, 0.f};
;     ...
;         const bool has_next = S.next(ui + 1, nxt);
;         const char* nA = has_next ? (const char*)g.A + (size_t)nxt.pm * tstep : cA; const char* nB = has_next ? (const char*)g.Bt + (size_t)nxt.pn * tstep : cB;
;         for (int t = 0; t < nt; t += 2) {
;             const bool last = (t == nt - 2);
;             const char* a1 = cA + (size_t)(t + 1) * kstep;
;             const char* a2 = last ? nA : cA + (size_t)(t + 2) * kstep; const char* b2 = last ? nB : cB + (size_t)(t + 2) * kstep;
;             const char* a3 = a2 + kstep; const char* b3 = b2 + kstep;
;             if (last && has_next) S.a_ready(nxt);
;             if constexpr (SP2) {
;             PG8_LDB(B0, 0, 0); PG8_LDB(B1, 0, 1); PG8_SCHED; PG8_LDA(At, 0, 0); PG8_STAGE(PG8_SA(1, 1), a1 + hstep, voffA);
;             PG8_WAIT_V(8); PG8_WAIT_L(0); PG8_BAR; PG8_MMA(0, 0, At, B0); PG8_MMA(0, 1, At, B1); PG8_BAR; PG8_SCHED;
;             PG8_LDA(At, 0, 1); PG8_STAGE(PG8_SB(0, 0), b2, voffB); PG8_STAGE(PG8_SB(0, 1), b2 + hstepB, voffB); PG8_STAGE(PG8_SA(0, 0), a2, voffA);
.LBB0_1070:
	s_ashr_i32 s97, s96, 31
	s_lshl_b64 s[4:5], s[96:97], 22
	s_add_u32 s26, s0, s4
	s_addc_u32 s27, s1, s5
	s_and_b64 s[4:5], s[92:93], exec
	s_cselect_b32 s97, s27, s39
	s_cselect_b32 s4, s26, s38
	s_ashr_i32 s85, s84, 31
	s_lshl_b64 s[6:7], s[84:85], 22
	s_add_u32 s94, s56, s6
	s_addc_u32 s95, s57, s7
	s_and_b64 s[6:7], s[92:93], exec
	s_cselect_b32 s5, s95, s47
	s_cselect_b32 s6, s94, s46
	s_add_u32 s38, s38, 0x200080
	s_addc_u32 s39, s39, 0
	s_add_u32 s7, s46, 0x100
	s_addc_u32 s8, s47, 0
	s_mov_b32 s9, -2
	s_waitcnt lgkmcnt(0)
	v_add_u32_e32 v186, 0x10000, v164
	v_add_u32_e32 v187, 0x14000, v164
	v_add_u32_e32 v198, 0x18000, v164
	v_add_u32_e32 v199, 0x1c000, v164
	s_add_u32 s10, s38, 0xffe00080
	s_addc_u32 s11, s39, -1
	s_add_i32 s12, 0, 0x10000
	s_cmpk_eq_i32 s9, 0x7c
	s_cselect_b32 vcc_hi, s97, s11
	s_cselect_b32 vcc_lo, s4, s10
	s_cselect_b32 s47, s5, s8
	s_cselect_b32 s46, s6, s7
	s_add_i32 s13, 0, 0x14000
	ds_read_b128 v[130:133], v186
	ds_read_b128 v[134:137], v186 offset:1024
	ds_read_b128 v[138:141], v186 offset:2048
	ds_read_b128 v[152:155], v186 offset:3072
	ds_read_b128 v[156:159], v187
	ds_read_b128 v[160:163], v187 offset:1024
	ds_read_b128 v[168:171], v187 offset:2048
	ds_read_b128 v[172:175], v187 offset:3072
	s_add_i32 m0, s74, 0xc000
	ds_read_b128 v[176:179], v166
	ds_read_b128 v[180:183], v166 offset:1024
	ds_read_b128 v[206:209], v166 offset:2048
	ds_read_b128 v[210:213], v166 offset:3072
	ds_read_b128 v[214:217], v166 offset:4096
	ds_read_b128 v[218:221], v166 offset:5120
	ds_read_b128 v[236:239], v166 offset:6144
	ds_read_b128 v[240:243], v166 offset:7168
	global_load_lds_dwordx4 v148, s[38:39]
	s_add_i32 m0, s74, 0xe000
	s_nop 0
	global_load_lds_dwordx4 v150, s[38:39]
	s_waitcnt vmcnt(8)
	s_waitcnt lgkmcnt(0)
	s_barrier
	v_mfma_f32_16x16x32_bf16 v[126:129], v[130:133], v[176:179], 0
	v_mfma_f32_16x16x32_bf16 v[126:129], v[134:137], v[180:183], v[126:129]
	v_mfma_f32_16x16x32_bf16 v[110:113], v[134:137], v[210:213], 0
	v_mfma_f32_16x16x32_bf16 v[110:113], v[130:133], v[206:209], v[110:113]
	v_mfma_f32_16x16x32_bf16 v[106:109], v[138:141], v[206:209], 0
	v_mfma_f32_16x16x32_bf16 v[106:109], v[152:155], v[210:213], v[106:109]
	v_mfma_f32_16x16x32_bf16 v[122:125], v[152:155], v[180:183], 0
	v_mfma_f32_16x16x32_bf16 v[122:125], v[138:141], v[176:179], v[122:125]
	v_mfma_f32_16x16x32_bf16 v[90:93], v[138:141], v[214:217], 0
	v_mfma_f32_16x16x32_bf16 v[90:93], v[152:155], v[218:221], v[90:93]
	v_mfma_f32_16x16x32_bf16 v[74:77], v[152:155], v[240:243], 0
	v_mfma_f32_16x16x32_bf16 v[74:77], v[138:141], v[236:239], v[74:77]
	v_mfma_f32_16x16x32_bf16 v[78:81], v[130:133], v[236:239], 0
	v_mfma_f32_16x16x32_bf16 v[78:81], v[134:137], v[240:243], v[78:81]
	v_mfma_f32_16x16x32_bf16 v[94:97], v[134:137], v[218:221], 0
	v_mfma_f32_16x16x32_bf16 v[94:97], v[130:133], v[214:217], v[94:97]
	v_mfma_f32_16x16x32_bf16 v[118:121], v[156:159], v[176:179], 0
	v_mfma_f32_16x16x32_bf16 v[118:121], v[160:163], v[180:183], v[118:121]
	v_mfma_f32_16x16x32_bf16 v[102:105], v[160:163], v[210:213], 0
	v_mfma_f32_16x16x32_bf16 v[102:105], v[156:159], v[206:209], v[102:105]
	v_mfma_f32_16x16x32_bf16 v[98:101], v[168:171], v[206:209], 0
	v_mfma_f32_16x16x32_bf16 v[98:101], v[172:175], v[210:213], v[98:101]
	v_mfma_f32_16x16x32_bf16 v[114:117], v[172:175], v[180:183], 0
	v_mfma_f32_16x16x32_bf16 v[114:117], v[168:171], v[176:179], v[114:117]
	v_mfma_f32_16x16x32_bf16 v[82:85], v[168:171], v[214:217], 0
	v_mfma_f32_16x16x32_bf16 v[82:85], v[172:175], v[218:221], v[82:85]
	v_mfma_f32_16x16x32_bf16 v[66:69], v[172:175], v[240:243], 0
	v_mfma_f32_16x16x32_bf16 v[66:69], v[168:171], v[236:239], v[66:69]
	v_mfma_f32_16x16x32_bf16 v[70:73], v[156:159], v[236:239], 0
	v_mfma_f32_16x16x32_bf16 v[70:73], v[160:163], v[240:243], v[70:73]
	v_mfma_f32_16x16x32_bf16 v[86:89], v[160:163], v[218:221], 0
	v_mfma_f32_16x16x32_bf16 v[86:89], v[156:159], v[214:217], v[86:89]
	s_barrier
	s_add_i32 s10, s12, s67
	s_mov_b32 m0, s10
	ds_read_b128 v[176:179], v166 offset:16384
	ds_read_b128 v[180:183], v166 offset:17408
	ds_read_b128 v[206:209], v166 offset:18432
	ds_read_b128 v[210:213], v166 offset:19456
	ds_read_b128 v[214:217], v166 offset:20480
	ds_read_b128 v[218:221], v166 offset:21504
	ds_read_b128 v[236:239], v166 offset:22528
	ds_read_b128 v[240:243], v166 offset:23552
	global_load_lds_dwordx4 v146, s[46:47]
	s_add_i32 m0, s10, 0x2000
	s_add_u32 s10, s46, 0x80000
	s_addc_u32 s11, s47, 0
	s_add_i32 s12, s13, s67
	global_load_lds_dwordx4 v142, s[46:47]
	s_mov_b32 m0, s12
	s_nop 0
	global_load_lds_dwordx4 v146, s[10:11]
	s_add_i32 m0, s12, 0x2000
	s_nop 0
	global_load_lds_dwordx4 v142, s[10:11]
	s_mov_b32 m0, s74
	s_nop 0
	global_load_lds_dwordx4 v190, vcc
	s_mov_b32 m0, s75
	s_nop 0
	global_load_lds_dwordx4 v144, vcc
	s_waitcnt vmcnt(8)
	s_waitcnt lgkmcnt(0)
	s_barrier
; #define PG8_STAGE(bufoff, gbase, voff) do { _Pragma("unroll") for (int _i = 0; _i < 2; ++_i) \
;         __builtin_amdgcn_global_load_lds((const unsigned*)((const char*)(gbase) + (voff)[_i]), (PG8_LAS unsigned*)(lds + (bufoff) + ldsw + _i * 8192), 16, 0, 0); } while (0)
; #define PG8_LDA(dst, b, h) do { _Pragma("unroll") for (int m = 0; m < 4; ++m) _Pragma("unroll") for (int k = 0; k < 2; ++k) dst[m][k] = *(const PG8_LAS bf16x8*)(lds + PG8_SA(b, h) + aoff + m * 2048 + k * 1024); } while (0)
; #define PG8_LDB(dst, b, h) do { _Pragma("unroll") for (int n = 0; n < 2; ++n) _Pragma("unroll") for (int k = 0; k < 2; ++k) dst[n][k] = *(const PG8_LAS bf16x8*)(lds + PG8_SB(b, h) + boff + n * 2048 + k * 1024); } while (0)
; #define PG8_MMA(ai, bj, At, Bt) do { __builtin_amdgcn_s_setprio(1); _Pragma("unroll") for (int m = 0; m < 4; ++m) _Pragma("unroll") for (int n = 0; n < 2; ++n) _Pragma("unroll") for (int k = 0; k < 2; ++k) \
;         acc[ai][bj][m][n] = __builtin_amdgcn_mfma_f32_16x16x32_bf16(Bt[n][k], At[m][k], acc[ai][bj][m][n], 0, 0, 0); __builtin_amdgcn_s_setprio(0); } while (0)
; #define PG8_BAR __builtin_amdgcn_s_barrier()
; template <class Epi, class Sched, bool ALIGN_EPI = false, bool SP2 = false>
; __device__ __forceinline__ void gemm_phase(PG8_LAS unsigned char* lds, const Gemm g, const Sched& S, const Epi& E) {
;     ...
;             const bool last = (t == nt - 2);
;             const char* a1 = cA + (size_t)(t + 1) * kstep;
;             const char* a2 = last ? nA : cA + (size_t)(t + 2) * kstep; const char* b2 = last ? nB : cB + (size_t)(t + 2) * kstep;
;             const char* a3 = a2 + kstep; const char* b3 = b2 + kstep;
;             if (last && has_next) S.a_ready(nxt);
;             if constexpr (SP2) {
;             PG8_LDB(B0, 0, 0); PG8_LDB(B1, 0, 1); PG8_SCHED; PG8_LDA(At, 0, 0); PG8_STAGE(PG8_SA(1, 1), a1 + hstep, voffA);
;             PG8_WAIT_V(8); PG8_WAIT_L(0); PG8_BAR; PG8_MMA(0, 0, At, B0); PG8_MMA(0, 1, At, B1); PG8_BAR; PG8_SCHED;
;             PG8_LDA(At, 0, 1); PG8_STAGE(PG8_SB(0, 0), b2, voffB); PG8_STAGE(PG8_SB(0, 1), b2 + hstepB, voffB); PG8_STAGE(PG8_SA(0, 0), a2, voffA);
;             PG8_WAIT_V(8); PG8_WAIT_L(0); PG8_BAR; PG8_MMA(1, 0, At, B0); PG8_MMA(1, 1, At, B1); PG8_BAR; PG8_SCHED;
;             PG8_LDB(B0, 1, 0); PG8_LDB(B1, 1, 1); PG8_SCHED; PG8_LDA(At, 1, 0); PG8_STAGE(PG8_SA(0, 1), a2 + hstep, voffA);
	v_mfma_f32_16x16x32_bf16 v[62:65], v[130:133], v[176:179], 0
	v_mfma_f32_16x16x32_bf16 v[62:65], v[134:137], v[180:183], v[62:65]
	v_mfma_f32_16x16x32_bf16 v[46:49], v[134:137], v[210:213], 0
	v_mfma_f32_16x16x32_bf16 v[46:49], v[130:133], v[206:209], v[46:49]
	v_mfma_f32_16x16x32_bf16 v[42:45], v[138:141], v[206:209], 0
	v_mfma_f32_16x16x32_bf16 v[42:45], v[152:155], v[210:213], v[42:45]
	v_mfma_f32_16x16x32_bf16 v[58:61], v[152:155], v[180:183], 0
	v_mfma_f32_16x16x32_bf16 v[58:61], v[138:141], v[176:179], v[58:61]
	v_mfma_f32_16x16x32_bf16 v[26:29], v[138:141], v[214:217], 0
	v_mfma_f32_16x16x32_bf16 v[26:29], v[152:155], v[218:221], v[26:29]
	v_mfma_f32_16x16x32_bf16 v[10:13], v[152:155], v[240:243], 0
	v_mfma_f32_16x16x32_bf16 v[10:13], v[138:141], v[236:239], v[10:13]
	v_mfma_f32_16x16x32_bf16 v[14:17], v[130:133], v[236:239], 0
	v_mfma_f32_16x16x32_bf16 v[14:17], v[134:137], v[240:243], v[14:17]
	v_mfma_f32_16x16x32_bf16 v[30:33], v[134:137], v[218:221], 0
	v_mfma_f32_16x16x32_bf16 v[30:33], v[130:133], v[214:217], v[30:33]
	v_mfma_f32_16x16x32_bf16 v[54:57], v[156:159], v[176:179], 0
	v_mfma_f32_16x16x32_bf16 v[54:57], v[160:163], v[180:183], v[54:57]
	v_mfma_f32_16x16x32_bf16 v[38:41], v[160:163], v[210:213], 0
	v_mfma_f32_16x16x32_bf16 v[38:41], v[156:159], v[206:209], v[38:41]
	v_mfma_f32_16x16x32_bf16 v[34:37], v[168:171], v[206:209], 0
	v_mfma_f32_16x16x32_bf16 v[34:37], v[172:175], v[210:213], v[34:37]
	v_mfma_f32_16x16x32_bf16 v[50:53], v[172:175], v[180:183], 0
	v_mfma_f32_16x16x32_bf16 v[50:53], v[168:171], v[176:179], v[50:53]
	v_mfma_f32_16x16x32_bf16 v[18:21], v[168:171], v[214:217], 0
	v_mfma_f32_16x16x32_bf16 v[18:21], v[172:175], v[218:221], v[18:21]
	v_mfma_f32_16x16x32_bf16 v[2:5], v[172:175], v[240:243], 0
	v_mfma_f32_16x16x32_bf16 v[2:5], v[168:171], v[236:239], v[2:5]
	v_mfma_f32_16x16x32_bf16 v[6:9], v[156:159], v[236:239], 0
	v_mfma_f32_16x16x32_bf16 v[6:9], v[160:163], v[240:243], v[6:9]
	v_mfma_f32_16x16x32_bf16 v[22:25], v[160:163], v[218:221], 0
	v_mfma_f32_16x16x32_bf16 v[22:25], v[156:159], v[214:217], v[22:25]
	s_barrier
	s_add_i32 s12, 0, 0x18000
	s_add_i32 s13, 0, 0x1c000
	ds_read_b128 v[130:133], v198
	ds_read_b128 v[134:137], v198 offset:1024
	ds_read_b128 v[138:141], v198 offset:2048
	ds_read_b128 v[152:155], v198 offset:3072
	ds_read_b128 v[156:159], v199
	ds_read_b128 v[160:163], v199 offset:1024
	ds_read_b128 v[168:171], v199 offset:2048
	ds_read_b128 v[172:175], v199 offset:3072
	s_add_u32 s10, vcc_lo, 0x200000
	s_addc_u32 s11, vcc_hi, 0
	s_mov_b32 m0, s86
	ds_read_b128 v[176:179], v166 offset:32768
	ds_read_b128 v[180:183], v166 offset:33792
	ds_read_b128 v[206:209], v166 offset:34816
	ds_read_b128 v[210:213], v166 offset:35840
	ds_read_b128 v[214:217], v166 offset:36864
	ds_read_b128 v[218:221], v166 offset:37888
	ds_read_b128 v[236:239], v166 offset:38912
	ds_read_b128 v[240:243], v166 offset:39936
	global_load_lds_dwordx4 v190, s[10:11]
	s_mov_b32 m0, s87
	s_nop 0
	global_load_lds_dwordx4 v144, s[10:11]
	s_waitcnt vmcnt(8)
	s_waitcnt lgkmcnt(0)
	s_barrier
	v_mfma_f32_16x16x32_bf16 v[126:129], v[130:133], v[176:179], v[126:129]
	v_mfma_f32_16x16x32_bf16 v[126:129], v[134:137], v[180:183], v[126:129]
	v_mfma_f32_16x16x32_bf16 v[110:113], v[134:137], v[210:213], v[110:113]
	v_mfma_f32_16x16x32_bf16 v[110:113], v[130:133], v[206:209], v[110:113]
	v_mfma_f32_16x16x32_bf16 v[106:109], v[138:141], v[206:209], v[106:109]
	v_mfma_f32_16x16x32_bf16 v[106:109], v[152:155], v[210:213], v[106:109]
	v_mfma_f32_16x16x32_bf16 v[122:125], v[152:155], v[180:183], v[122:125]
	v_mfma_f32_16x16x32_bf16 v[122:125], v[138:141], v[176:179], v[122:125]
	v_mfma_f32_16x16x32_bf16 v[90:93], v[138:141], v[214:217], v[90:93]
	v_mfma_f32_16x16x32_bf16 v[90:93], v[152:155], v[218:221], v[90:93]
	v_mfma_f32_16x16x32_bf16 v[74:77], v[152:155], v[240:243], v[74:77]
	v_mfma_f32_16x16x32_bf16 v[74:77], v[138:141], v[236:239], v[74:77]
	v_mfma_f32_16x16x32_bf16 v[78:81], v[130:133], v[236:239], v[78:81]
	v_mfma_f32_16x16x32_bf16 v[78:81], v[134:137], v[240:243], v[78:81]
	v_mfma_f32_16x16x32_bf16 v[94:97], v[134:137], v[218:221], v[94:97]
	v_mfma_f32_16x16x32_bf16 v[94:97], v[130:133], v[214:217], v[94:97]
	v_mfma_f32_16x16x32_bf16 v[118:121], v[156:159], v[176:179], v[118:121]
	v_mfma_f32_16x16x32_bf16 v[118:121], v[160:163], v[180:183], v[118:121]
	v_mfma_f32_16x16x32_bf16 v[102:105], v[160:163], v[210:213], v[102:105]
	v_mfma_f32_16x16x32_bf16 v[102:105], v[156:159], v[206:209], v[102:105]
	v_mfma_f32_16x16x32_bf16 v[98:101], v[168:171], v[206:209], v[98:101]
	v_mfma_f32_16x16x32_bf16 v[98:101], v[172:175], v[210:213], v[98:101]
	v_mfma_f32_16x16x32_bf16 v[114:117], v[172:175], v[180:183], v[114:117]
	v_mfma_f32_16x16x32_bf16 v[114:117], v[168:171], v[176:179], v[114:117]
	v_mfma_f32_16x16x32_bf16 v[82:85], v[168:171], v[214:217], v[82:85]
	v_mfma_f32_16x16x32_bf16 v[82:85], v[172:175], v[218:221], v[82:85]
	v_mfma_f32_16x16x32_bf16 v[66:69], v[172:175], v[240:243], v[66:69]
	v_mfma_f32_16x16x32_bf16 v[66:69], v[168:171], v[236:239], v[66:69]
	v_mfma_f32_16x16x32_bf16 v[70:73], v[156:159], v[236:239], v[70:73]
	v_mfma_f32_16x16x32_bf16 v[70:73], v[160:163], v[240:243], v[70:73]
	v_mfma_f32_16x16x32_bf16 v[86:89], v[160:163], v[218:221], v[86:89]
	v_mfma_f32_16x16x32_bf16 v[86:89], v[156:159], v[214:217], v[86:89]
	s_barrier
; #define PG8_STAGE(bufoff, gbase, voff) do { _Pragma("unroll") for (int _i = 0; _i < 2; ++_i) \
;         __builtin_amdgcn_global_load_lds((const unsigned*)((const char*)(gbase) + (voff)[_i]), (PG8_LAS unsigned*)(lds + (bufoff) + ldsw + _i * 8192), 16, 0, 0); } while (0)
; #define PG8_LDA(dst, b, h) do { _Pragma("unroll") for (int m = 0; m < 4; ++m) _Pragma("unroll") for (int k = 0; k < 2; ++k) dst[m][k] = *(const PG8_LAS bf16x8*)(lds + PG8_SA(b, h) + aoff + m * 2048 + k * 1024); } while (0)
; #define PG8_LDB(dst, b, h) do { _Pragma("unroll") for (int n = 0; n < 2; ++n) _Pragma("unroll") for (int k = 0; k < 2; ++k) dst[n][k] = *(const PG8_LAS bf16x8*)(lds + PG8_SB(b, h) + boff + n * 2048 + k * 1024); } while (0)
; #define PG8_BAR __builtin_amdgcn_s_barrier()
; template <class Epi, class Sched, bool ALIGN_EPI = false, bool SP2 = false>
; __device__ __forceinline__ void gemm_phase(PG8_LAS unsigned char* lds, const Gemm g, const Sched& S, const Epi& E) {
;     ...
;             const bool last = (t == nt - 2);
;             const char* a1 = cA + (size_t)(t + 1) * kstep;
;             const char* a2 = last ? nA : cA + (size_t)(t + 2) * kstep; const char* b2 = last ? nB : cB + (size_t)(t + 2) * kstep;
;             const char* a3 = a2 + kstep; const char* b3 = b2 + kstep;
;             if (last && has_next) S.a_ready(nxt);
;             if constexpr (SP2) {
;             PG8_LDB(B0, 0, 0); PG8_LDB(B1, 0, 1); PG8_SCHED; PG8_LDA(At, 0, 0); PG8_STAGE(PG8_SA(1, 1), a1 + hstep, voffA);
;             PG8_WAIT_V(8); PG8_WAIT_L(0); PG8_BAR; PG8_MMA(0, 0, At, B0); PG8_MMA(0, 1, At, B1); PG8_BAR; PG8_SCHED;
;             PG8_LDA(At, 0, 1); PG8_STAGE(PG8_SB(0, 0), b2, voffB); PG8_STAGE(PG8_SB(0, 1), b2 + hstepB, voffB); PG8_STAGE(PG8_SA(0, 0), a2, voffA);
;             PG8_WAIT_V(8); PG8_WAIT_L(0); PG8_BAR; PG8_MMA(1, 0, At, B0); PG8_MMA(1, 1, At, B1); PG8_BAR; PG8_SCHED;
;             PG8_LDB(B0, 1, 0); PG8_LDB(B1, 1, 1); PG8_SCHED; PG8_LDA(At, 1, 0); PG8_STAGE(PG8_SA(0, 1), a2 + hstep, voffA);
;             PG8_WAIT_V(8); PG8_WAIT_L(0); PG8_BAR; PG8_MMA(0, 0, At, B0); PG8_MMA(0, 1, At, B1); PG8_BAR; PG8_SCHED;
;             PG8_LDA(At, 1, 1); PG8_STAGE(PG8_SB(1, 0), b3, voffB); PG8_STAGE(PG8_SB(1, 1), b3 + hstepB, voffB); PG8_STAGE(PG8_SA(1, 0), a3, voffA);
;             PG8_WAIT_V(8); PG8_WAIT_L(0); PG8_BAR; PG8_MMA(1, 0, At, B0); PG8_MMA(1, 1, At, B1); PG8_BAR; PG8_SCHED;
	s_add_i32 s10, s12, s67
	s_mov_b32 m0, s10
	ds_read_b128 v[176:179], v166 offset:49152
	ds_read_b128 v[180:183], v166 offset:50176
	ds_read_b128 v[206:209], v166 offset:51200
	ds_read_b128 v[210:213], v166 offset:52224
	ds_read_b128 v[214:217], v166 offset:53248
	ds_read_b128 v[218:221], v166 offset:54272
	ds_read_b128 v[236:239], v166 offset:55296
	ds_read_b128 v[240:243], v166 offset:56320
	s_add_u32 s100, s46, s60
	s_addc_u32 s101, s47, s61
	global_load_lds_dwordx4 v146, s[100:101]
	s_add_i32 m0, s10, 0x2000
	s_add_u32 s10, s46, 0x80080
	s_addc_u32 s11, s47, 0
	s_add_i32 s12, s13, s67
	global_load_lds_dwordx4 v142, s[100:101]
	s_mov_b32 m0, s12
	s_nop 0
	global_load_lds_dwordx4 v146, s[10:11]
	s_add_i32 m0, s12, 0x2000
	s_nop 0
	global_load_lds_dwordx4 v142, s[10:11]
	s_mov_b32 m0, s82
	s_add_u32 s100, vcc_lo, s60
	s_addc_u32 s101, vcc_hi, s61
	global_load_lds_dwordx4 v190, s[100:101]
	s_mov_b32 m0, s42
	s_nop 0
	global_load_lds_dwordx4 v144, s[100:101]
	s_waitcnt vmcnt(8)
	s_waitcnt lgkmcnt(0)
	s_barrier
	v_mfma_f32_16x16x32_bf16 v[62:65], v[130:133], v[176:179], v[62:65]
	v_mfma_f32_16x16x32_bf16 v[62:65], v[134:137], v[180:183], v[62:65]
	v_mfma_f32_16x16x32_bf16 v[46:49], v[134:137], v[210:213], v[46:49]
	v_mfma_f32_16x16x32_bf16 v[46:49], v[130:133], v[206:209], v[46:49]
	v_mfma_f32_16x16x32_bf16 v[42:45], v[138:141], v[206:209], v[42:45]
	v_mfma_f32_16x16x32_bf16 v[42:45], v[152:155], v[210:213], v[42:45]
	v_mfma_f32_16x16x32_bf16 v[58:61], v[152:155], v[180:183], v[58:61]
	v_mfma_f32_16x16x32_bf16 v[58:61], v[138:141], v[176:179], v[58:61]
	v_mfma_f32_16x16x32_bf16 v[26:29], v[138:141], v[214:217], v[26:29]
	v_mfma_f32_16x16x32_bf16 v[26:29], v[152:155], v[218:221], v[26:29]
	v_mfma_f32_16x16x32_bf16 v[10:13], v[152:155], v[240:243], v[10:13]
	v_mfma_f32_16x16x32_bf16 v[10:13], v[138:141], v[236:239], v[10:13]
	v_mfma_f32_16x16x32_bf16 v[14:17], v[130:133], v[236:239], v[14:17]
	v_mfma_f32_16x16x32_bf16 v[14:17], v[134:137], v[240:243], v[14:17]
	v_mfma_f32_16x16x32_bf16 v[30:33], v[134:137], v[218:221], v[30:33]
	v_mfma_f32_16x16x32_bf16 v[30:33], v[130:133], v[214:217], v[30:33]
	v_mfma_f32_16x16x32_bf16 v[54:57], v[156:159], v[176:179], v[54:57]
	v_mfma_f32_16x16x32_bf16 v[54:57], v[160:163], v[180:183], v[54:57]
	v_mfma_f32_16x16x32_bf16 v[38:41], v[160:163], v[210:213], v[38:41]
	v_mfma_f32_16x16x32_bf16 v[38:41], v[156:159], v[206:209], v[38:41]
	v_mfma_f32_16x16x32_bf16 v[34:37], v[168:171], v[206:209], v[34:37]
	v_mfma_f32_16x16x32_bf16 v[34:37], v[172:175], v[210:213], v[34:37]
	v_mfma_f32_16x16x32_bf16 v[50:53], v[172:175], v[180:183], v[50:53]
	v_mfma_f32_16x16x32_bf16 v[50:53], v[168:171], v[176:179], v[50:53]
	v_mfma_f32_16x16x32_bf16 v[18:21], v[168:171], v[214:217], v[18:21]
	v_mfma_f32_16x16x32_bf16 v[18:21], v[172:175], v[218:221], v[18:21]
	v_mfma_f32_16x16x32_bf16 v[2:5], v[172:175], v[240:243], v[2:5]
	v_mfma_f32_16x16x32_bf16 v[2:5], v[168:171], v[236:239], v[2:5]
	v_mfma_f32_16x16x32_bf16 v[6:9], v[156:159], v[236:239], v[6:9]
	v_mfma_f32_16x16x32_bf16 v[6:9], v[160:163], v[240:243], v[6:9]
	v_mfma_f32_16x16x32_bf16 v[22:25], v[160:163], v[218:221], v[22:25]
	v_mfma_f32_16x16x32_bf16 v[22:25], v[156:159], v[214:217], v[22:25]
	s_barrier
	s_add_i32 s9, s9, 2
	s_add_u32 s38, s38, 0x100
	s_addc_u32 s39, s39, 0
	s_add_u32 s7, s7, 0x100
	s_addc_u32 s8, s8, 0
	s_cmpk_gt_u32 s9, 0x7d
.LBB0_1071:
	s_add_u32 s10, s38, 0xffe00080
	s_addc_u32 s11, s39, -1
	s_add_i32 s12, 0, 0x10000
	s_cmpk_eq_i32 s9, 0x7c
	s_cselect_b32 vcc_hi, s97, s11
	s_cselect_b32 vcc_lo, s4, s10
	s_cselect_b32 s47, s5, s8
	s_cselect_b32 s46, s6, s7
	s_add_i32 s13, 0, 0x14000
	ds_read_b128 v[130:133], v186
	ds_read_b128 v[134:137], v186 offset:1024
	ds_read_b128 v[138:141], v186 offset:2048
	ds_read_b128 v[152:155], v186 offset:3072
	ds_read_b128 v[156:159], v187
	ds_read_b128 v[160:163], v187 offset:1024
	ds_read_b128 v[168:171], v187 offset:2048
	ds_read_b128 v[172:175], v187 offset:3072
	s_add_i32 m0, s74, 0xc000
	ds_read_b128 v[176:179], v166
	ds_read_b128 v[180:183], v166 offset:1024
	ds_read_b128 v[206:209], v166 offset:2048
	ds_read_b128 v[210:213], v166 offset:3072
	ds_read_b128 v[214:217], v166 offset:4096
	ds_read_b128 v[218:221], v166 offset:5120
	ds_read_b128 v[236:239], v166 offset:6144
	ds_read_b128 v[240:243], v166 offset:7168
	global_load_lds_dwordx4 v148, s[38:39]
	s_add_i32 m0, s74, 0xe000
	s_nop 0
	global_load_lds_dwordx4 v150, s[38:39]
	s_waitcnt vmcnt(8)
	s_waitcnt lgkmcnt(0)
	s_barrier
	v_mfma_f32_16x16x32_bf16 v[126:129], v[130:133], v[176:179], v[126:129]
	v_mfma_f32_16x16x32_bf16 v[126:129], v[134:137], v[180:183], v[126:129]
	v_mfma_f32_16x16x32_bf16 v[110:113], v[134:137], v[210:213], v[110:113]
	v_mfma_f32_16x16x32_bf16 v[110:113], v[130:133], v[206:209], v[110:113]
	v_mfma_f32_16x16x32_bf16 v[106:109], v[138:141], v[206:209], v[106:109]
	v_mfma_f32_16x16x32_bf16 v[106:109], v[152:155], v[210:213], v[106:109]
	v_mfma_f32_16x16x32_bf16 v[122:125], v[152:155], v[180:183], v[122:125]
	v_mfma_f32_16x16x32_bf16 v[122:125], v[138:141], v[176:179], v[122:125]
	v_mfma_f32_16x16x32_bf16 v[90:93], v[138:141], v[214:217], v[90:93]
	v_mfma_f32_16x16x32_bf16 v[90:93], v[152:155], v[218:221], v[90:93]
	v_mfma_f32_16x16x32_bf16 v[74:77], v[152:155], v[240:243], v[74:77]
	v_mfma_f32_16x16x32_bf16 v[74:77], v[138:141], v[236:239], v[74:77]
	v_mfma_f32_16x16x32_bf16 v[78:81], v[130:133], v[236:239], v[78:81]
	v_mfma_f32_16x16x32_bf16 v[78:81], v[134:137], v[240:243], v[78:81]
	v_mfma_f32_16x16x32_bf16 v[94:97], v[134:137], v[218:221], v[94:97]
	v_mfma_f32_16x16x32_bf16 v[94:97], v[130:133], v[214:217], v[94:97]
	v_mfma_f32_16x16x32_bf16 v[118:121], v[156:159], v[176:179], v[118:121]
	v_mfma_f32_16x16x32_bf16 v[118:121], v[160:163], v[180:183], v[118:121]
	v_mfma_f32_16x16x32_bf16 v[102:105], v[160:163], v[210:213], v[102:105]
	v_mfma_f32_16x16x32_bf16 v[102:105], v[156:159], v[206:209], v[102:105]
	v_mfma_f32_16x16x32_bf16 v[98:101], v[168:171], v[206:209], v[98:101]
	v_mfma_f32_16x16x32_bf16 v[98:101], v[172:175], v[210:213], v[98:101]
	v_mfma_f32_16x16x32_bf16 v[114:117], v[172:175], v[180:183], v[114:117]
	v_mfma_f32_16x16x32_bf16 v[114:117], v[168:171], v[176:179], v[114:117]
	v_mfma_f32_16x16x32_bf16 v[82:85], v[168:171], v[214:217], v[82:85]
	v_mfma_f32_16x16x32_bf16 v[82:85], v[172:175], v[218:221], v[82:85]
	v_mfma_f32_16x16x32_bf16 v[66:69], v[172:175], v[240:243], v[66:69]
	v_mfma_f32_16x16x32_bf16 v[66:69], v[168:171], v[236:239], v[66:69]
	v_mfma_f32_16x16x32_bf16 v[70:73], v[156:159], v[236:239], v[70:73]
	v_mfma_f32_16x16x32_bf16 v[70:73], v[160:163], v[240:243], v[70:73]
	v_mfma_f32_16x16x32_bf16 v[86:89], v[160:163], v[218:221], v[86:89]
	v_mfma_f32_16x16x32_bf16 v[86:89], v[156:159], v[214:217], v[86:89]
	s_barrier
; #define PG8_STAGE(bufoff, gbase, voff) do { _Pragma("unroll") for (int _i = 0; _i < 2; ++_i) \
;         __builtin_amdgcn_global_load_lds((const unsigned*)((const char*)(gbase) + (voff)[_i]), (PG8_LAS unsigned*)(lds + (bufoff) + ldsw + _i * 8192), 16, 0, 0); } while (0)
; #define PG8_LDA(dst, b, h) do { _Pragma("unroll") for (int m = 0; m < 4; ++m) _Pragma("unroll") for (int k = 0; k < 2; ++k) dst[m][k] = *(const PG8_LAS bf16x8*)(lds + PG8_SA(b, h) + aoff + m * 2048 + k * 1024); } while (0)
; #define PG8_LDB(dst, b, h) do { _Pragma("unroll") for (int n = 0; n < 2; ++n) _Pragma("unroll") for (int k = 0; k < 2; ++k) dst[n][k] = *(const PG8_LAS bf16x8*)(lds + PG8_SB(b, h) + boff + n * 2048 + k * 1024); } while (0)
; #define PG8_MMA(ai, bj, At, Bt) do { __builtin_amdgcn_s_setprio(1); _Pragma("unroll") for (int m = 0; m < 4; ++m) _Pragma("unroll") for (int n = 0; n < 2; ++n) _Pragma("unroll") for (int k = 0; k < 2; ++k) \
;         acc[ai][bj][m][n] = __builtin_amdgcn_mfma_f32_16x16x32_bf16(Bt[n][k], At[m][k], acc[ai][bj][m][n], 0, 0, 0); __builtin_amdgcn_s_setprio(0); } while (0)
; #define PG8_WAIT_V(n) asm volatile("s_waitcnt vmcnt(" #n ")" ::: "memory")
; #define PG8_WAIT_L(n) asm volatile("s_waitcnt lgkmcnt(" #n ")" ::: "memory")
; #define PG8_BAR __builtin_amdgcn_s_barrier()
; #define PG8_SCHED __builtin_amdgcn_sched_barrier(0)
; template <class Epi, class Sched, bool ALIGN_EPI = false, bool SP2 = false>
; __device__ __forceinline__ void gemm_phase(PG8_LAS unsigned char* lds, const Gemm g, const Sched& S, const Epi& E) {
;     ...
;             PG8_LDA(At, 0, 1); PG8_STAGE(PG8_SB(0, 0), b2, voffB); PG8_STAGE(PG8_SB(0, 1), b2 + hstepB, voffB); PG8_STAGE(PG8_SA(0, 0), a2, voffA);
;             PG8_WAIT_V(8); PG8_WAIT_L(0); PG8_BAR; PG8_MMA(1, 0, At, B0); PG8_MMA(1, 1, At, B1); PG8_BAR; PG8_SCHED;
;             PG8_LDB(B0, 1, 0); PG8_LDB(B1, 1, 1); PG8_SCHED; PG8_LDA(At, 1, 0); PG8_STAGE(PG8_SA(0, 1), a2 + hstep, voffA);
;             PG8_WAIT_V(8); PG8_WAIT_L(0); PG8_BAR; PG8_MMA(0, 0, At, B0); PG8_MMA(0, 1, At, B1); PG8_BAR; PG8_SCHED;
	s_add_i32 s10, s12, s67
	s_mov_b32 m0, s10
	ds_read_b128 v[176:179], v166 offset:16384
	ds_read_b128 v[180:183], v166 offset:17408
	ds_read_b128 v[206:209], v166 offset:18432
	ds_read_b128 v[210:213], v166 offset:19456
	ds_read_b128 v[214:217], v166 offset:20480
	ds_read_b128 v[218:221], v166 offset:21504
	ds_read_b128 v[236:239], v166 offset:22528
	ds_read_b128 v[240:243], v166 offset:23552
	global_load_lds_dwordx4 v146, s[46:47]
	s_add_i32 m0, s10, 0x2000
	s_add_u32 s10, s46, 0x80000
	s_addc_u32 s11, s47, 0
	s_add_i32 s12, s13, s67
	global_load_lds_dwordx4 v142, s[46:47]
	s_mov_b32 m0, s12
	s_nop 0
	global_load_lds_dwordx4 v146, s[10:11]
	s_add_i32 m0, s12, 0x2000
	s_nop 0
	global_load_lds_dwordx4 v142, s[10:11]
	s_mov_b32 m0, s74
	s_nop 0
	global_load_lds_dwordx4 v190, vcc
	s_mov_b32 m0, s75
	s_nop 0
	global_load_lds_dwordx4 v144, vcc
	s_waitcnt vmcnt(8)
	s_waitcnt lgkmcnt(0)
	s_barrier
	v_mfma_f32_16x16x32_bf16 v[62:65], v[130:133], v[176:179], v[62:65]
	v_mfma_f32_16x16x32_bf16 v[62:65], v[134:137], v[180:183], v[62:65]
	v_mfma_f32_16x16x32_bf16 v[46:49], v[134:137], v[210:213], v[46:49]
	v_mfma_f32_16x16x32_bf16 v[46:49], v[130:133], v[206:209], v[46:49]
	v_mfma_f32_16x16x32_bf16 v[42:45], v[138:141], v[206:209], v[42:45]
	v_mfma_f32_16x16x32_bf16 v[42:45], v[152:155], v[210:213], v[42:45]
	v_mfma_f32_16x16x32_bf16 v[58:61], v[152:155], v[180:183], v[58:61]
	v_mfma_f32_16x16x32_bf16 v[58:61], v[138:141], v[176:179], v[58:61]
	v_mfma_f32_16x16x32_bf16 v[26:29], v[138:141], v[214:217], v[26:29]
	v_mfma_f32_16x16x32_bf16 v[26:29], v[152:155], v[218:221], v[26:29]
	v_mfma_f32_16x16x32_bf16 v[10:13], v[152:155], v[240:243], v[10:13]
	v_mfma_f32_16x16x32_bf16 v[10:13], v[138:141], v[236:239], v[10:13]
	v_mfma_f32_16x16x32_bf16 v[14:17], v[130:133], v[236:239], v[14:17]
	v_mfma_f32_16x16x32_bf16 v[14:17], v[134:137], v[240:243], v[14:17]
	v_mfma_f32_16x16x32_bf16 v[30:33], v[134:137], v[218:221], v[30:33]
	v_mfma_f32_16x16x32_bf16 v[30:33], v[130:133], v[214:217], v[30:33]
	v_mfma_f32_16x16x32_bf16 v[54:57], v[156:159], v[176:179], v[54:57]
	v_mfma_f32_16x16x32_bf16 v[54:57], v[160:163], v[180:183], v[54:57]
	v_mfma_f32_16x16x32_bf16 v[38:41], v[160:163], v[210:213], v[38:41]
	v_mfma_f32_16x16x32_bf16 v[38:41], v[156:159], v[206:209], v[38:41]
	v_mfma_f32_16x16x32_bf16 v[34:37], v[168:171], v[206:209], v[34:37]
	v_mfma_f32_16x16x32_bf16 v[34:37], v[172:175], v[210:213], v[34:37]
	v_mfma_f32_16x16x32_bf16 v[50:53], v[172:175], v[180:183], v[50:53]
	v_mfma_f32_16x16x32_bf16 v[50:53], v[168:171], v[176:179], v[50:53]
	v_mfma_f32_16x16x32_bf16 v[18:21], v[168:171], v[214:217], v[18:21]
	v_mfma_f32_16x16x32_bf16 v[18:21], v[172:175], v[218:221], v[18:21]
	v_mfma_f32_16x16x32_bf16 v[2:5], v[172:175], v[240:243], v[2:5]
	v_mfma_f32_16x16x32_bf16 v[2:5], v[168:171], v[236:239], v[2:5]
	v_mfma_f32_16x16x32_bf16 v[6:9], v[156:159], v[236:239], v[6:9]
	v_mfma_f32_16x16x32_bf16 v[6:9], v[160:163], v[240:243], v[6:9]
	v_mfma_f32_16x16x32_bf16 v[22:25], v[160:163], v[218:221], v[22:25]
	v_mfma_f32_16x16x32_bf16 v[22:25], v[156:159], v[214:217], v[22:25]
	s_barrier
	s_add_i32 s12, 0, 0x18000
	s_add_i32 s13, 0, 0x1c000
	ds_read_b128 v[130:133], v198
	ds_read_b128 v[134:137], v198 offset:1024
	ds_read_b128 v[138:141], v198 offset:2048
	ds_read_b128 v[152:155], v198 offset:3072
	ds_read_b128 v[156:159], v199
	ds_read_b128 v[160:163], v199 offset:1024
	ds_read_b128 v[168:171], v199 offset:2048
	ds_read_b128 v[172:175], v199 offset:3072
	s_add_u32 s10, vcc_lo, 0x200000
	s_addc_u32 s11, vcc_hi, 0
	s_mov_b32 m0, s86
	ds_read_b128 v[176:179], v166 offset:32768
	ds_read_b128 v[180:183], v166 offset:33792
	ds_read_b128 v[206:209], v166 offset:34816
	ds_read_b128 v[210:213], v166 offset:35840
	ds_read_b128 v[214:217], v166 offset:36864
	ds_read_b128 v[218:221], v166 offset:37888
	ds_read_b128 v[236:239], v166 offset:38912
	ds_read_b128 v[240:243], v166 offset:39936
	global_load_lds_dwordx4 v190, s[10:11]
	s_mov_b32 m0, s87
	s_nop 0
	global_load_lds_dwordx4 v144, s[10:11]
	s_waitcnt vmcnt(8)
	s_waitcnt lgkmcnt(0)
	s_barrier
; #define PG8_STAGE(bufoff, gbase, voff) do { _Pragma("unroll") for (int _i = 0; _i < 2; ++_i) \
;         __builtin_amdgcn_global_load_lds((const unsigned*)((const char*)(gbase) + (voff)[_i]), (PG8_LAS unsigned*)(lds + (bufoff) + ldsw + _i * 8192), 16, 0, 0); } while (0)
; #define PG8_LDA(dst, b, h) do { _Pragma("unroll") for (int m = 0; m < 4; ++m) _Pragma("unroll") for (int k = 0; k < 2; ++k) dst[m][k] = *(const PG8_LAS bf16x8*)(lds + PG8_SA(b, h) + aoff + m * 2048 + k * 1024); } while (0)
; #define PG8_MMA(ai, bj, At, Bt) do { __builtin_amdgcn_s_setprio(1); _Pragma("unroll") for (int m = 0; m < 4; ++m) _Pragma("unroll") for (int n = 0; n < 2; ++n) _Pragma("unroll") for (int k = 0; k < 2; ++k) \
;         acc[ai][bj][m][n] = __builtin_amdgcn_mfma_f32_16x16x32_bf16(Bt[n][k], At[m][k], acc[ai][bj][m][n], 0, 0, 0); __builtin_amdgcn_s_setprio(0); } while (0)
; #define PG8_WAIT_V(n) asm volatile("s_waitcnt vmcnt(" #n ")" ::: "memory")
; #define PG8_WAIT_L(n) asm volatile("s_waitcnt lgkmcnt(" #n ")" ::: "memory")
; #define PG8_BAR __builtin_amdgcn_s_barrier()
; #define PG8_SCHED __builtin_amdgcn_sched_barrier(0)
; template <class Epi, class Sched, bool ALIGN_EPI = false, bool SP2 = false>
; __device__ __forceinline__ void gemm_phase(PG8_LAS unsigned char* lds, const Gemm g, const Sched& S, const Epi& E) {
;     ...
;             PG8_WAIT_V(8); PG8_WAIT_L(0); PG8_BAR; PG8_MMA(0, 0, At, B0); PG8_MMA(0, 1, At, B1); PG8_BAR; PG8_SCHED;
;             PG8_LDA(At, 1, 1); PG8_STAGE(PG8_SB(1, 0), b3, voffB); PG8_STAGE(PG8_SB(1, 1), b3 + hstepB, voffB); PG8_STAGE(PG8_SA(1, 0), a3, voffA);
;             PG8_WAIT_V(8); PG8_WAIT_L(0); PG8_BAR; PG8_MMA(1, 0, At, B0); PG8_MMA(1, 1, At, B1); PG8_BAR; PG8_SCHED;
;     ...
;         if constexpr (ALIGN_EPI) { if (wr == 0) PG8_BAR; }
	v_mfma_f32_16x16x32_bf16 v[126:129], v[130:133], v[176:179], v[126:129]
	v_mfma_f32_16x16x32_bf16 v[126:129], v[134:137], v[180:183], v[126:129]
	v_mfma_f32_16x16x32_bf16 v[110:113], v[134:137], v[210:213], v[110:113]
	v_mfma_f32_16x16x32_bf16 v[110:113], v[130:133], v[206:209], v[110:113]
	v_mfma_f32_16x16x32_bf16 v[106:109], v[138:141], v[206:209], v[106:109]
	v_mfma_f32_16x16x32_bf16 v[106:109], v[152:155], v[210:213], v[106:109]
	v_mfma_f32_16x16x32_bf16 v[122:125], v[152:155], v[180:183], v[122:125]
	v_mfma_f32_16x16x32_bf16 v[122:125], v[138:141], v[176:179], v[122:125]
	v_mfma_f32_16x16x32_bf16 v[90:93], v[138:141], v[214:217], v[90:93]
	v_mfma_f32_16x16x32_bf16 v[90:93], v[152:155], v[218:221], v[90:93]
	v_mfma_f32_16x16x32_bf16 v[74:77], v[152:155], v[240:243], v[74:77]
	v_mfma_f32_16x16x32_bf16 v[74:77], v[138:141], v[236:239], v[74:77]
	v_mfma_f32_16x16x32_bf16 v[78:81], v[130:133], v[236:239], v[78:81]
	v_mfma_f32_16x16x32_bf16 v[78:81], v[134:137], v[240:243], v[78:81]
	v_mfma_f32_16x16x32_bf16 v[94:97], v[134:137], v[218:221], v[94:97]
	v_mfma_f32_16x16x32_bf16 v[94:97], v[130:133], v[214:217], v[94:97]
	v_mfma_f32_16x16x32_bf16 v[118:121], v[156:159], v[176:179], v[118:121]
	v_mfma_f32_16x16x32_bf16 v[118:121], v[160:163], v[180:183], v[118:121]
	v_mfma_f32_16x16x32_bf16 v[102:105], v[160:163], v[210:213], v[102:105]
	v_mfma_f32_16x16x32_bf16 v[102:105], v[156:159], v[206:209], v[102:105]
	v_mfma_f32_16x16x32_bf16 v[98:101], v[168:171], v[206:209], v[98:101]
	v_mfma_f32_16x16x32_bf16 v[98:101], v[172:175], v[210:213], v[98:101]
	v_mfma_f32_16x16x32_bf16 v[114:117], v[172:175], v[180:183], v[114:117]
	v_mfma_f32_16x16x32_bf16 v[114:117], v[168:171], v[176:179], v[114:117]
	v_mfma_f32_16x16x32_bf16 v[82:85], v[168:171], v[214:217], v[82:85]
	v_mfma_f32_16x16x32_bf16 v[82:85], v[172:175], v[218:221], v[82:85]
	v_mfma_f32_16x16x32_bf16 v[66:69], v[172:175], v[240:243], v[66:69]
	v_mfma_f32_16x16x32_bf16 v[66:69], v[168:171], v[236:239], v[66:69]
	v_mfma_f32_16x16x32_bf16 v[70:73], v[156:159], v[236:239], v[70:73]
	v_mfma_f32_16x16x32_bf16 v[70:73], v[160:163], v[240:243], v[70:73]
	v_mfma_f32_16x16x32_bf16 v[86:89], v[160:163], v[218:221], v[86:89]
	v_mfma_f32_16x16x32_bf16 v[86:89], v[156:159], v[214:217], v[86:89]
	s_barrier
	s_add_i32 s10, s12, s67
	s_mov_b32 m0, s10
	ds_read_b128 v[176:179], v166 offset:49152
	ds_read_b128 v[180:183], v166 offset:50176
	ds_read_b128 v[206:209], v166 offset:51200
	ds_read_b128 v[210:213], v166 offset:52224
	ds_read_b128 v[214:217], v166 offset:53248
	ds_read_b128 v[218:221], v166 offset:54272
	ds_read_b128 v[236:239], v166 offset:55296
	ds_read_b128 v[240:243], v166 offset:56320
	s_add_u32 s100, s46, s60
	s_addc_u32 s101, s47, s61
	global_load_lds_dwordx4 v146, s[100:101]
	s_add_i32 m0, s10, 0x2000
	s_add_u32 s10, s46, 0x80080
	s_addc_u32 s11, s47, 0
	s_add_i32 s12, s13, s67
	global_load_lds_dwordx4 v142, s[100:101]
	s_mov_b32 m0, s12
	s_nop 0
	global_load_lds_dwordx4 v146, s[10:11]
	s_add_i32 m0, s12, 0x2000
	s_nop 0
	global_load_lds_dwordx4 v142, s[10:11]
	s_mov_b32 m0, s82
	s_add_u32 s100, vcc_lo, s60
	s_addc_u32 s101, vcc_hi, s61
	global_load_lds_dwordx4 v190, s[100:101]
	s_mov_b32 m0, s42
	s_nop 0
	global_load_lds_dwordx4 v144, s[100:101]
	s_waitcnt vmcnt(8)
	s_waitcnt lgkmcnt(0)
	s_barrier
	v_mfma_f32_16x16x32_bf16 v[62:65], v[130:133], v[176:179], v[62:65]
	v_mfma_f32_16x16x32_bf16 v[62:65], v[134:137], v[180:183], v[62:65]
	v_mfma_f32_16x16x32_bf16 v[46:49], v[134:137], v[210:213], v[46:49]
	v_mfma_f32_16x16x32_bf16 v[46:49], v[130:133], v[206:209], v[46:49]
	v_mfma_f32_16x16x32_bf16 v[42:45], v[138:141], v[206:209], v[42:45]
	v_mfma_f32_16x16x32_bf16 v[42:45], v[152:155], v[210:213], v[42:45]
	v_mfma_f32_16x16x32_bf16 v[58:61], v[152:155], v[180:183], v[58:61]
	v_mfma_f32_16x16x32_bf16 v[58:61], v[138:141], v[176:179], v[58:61]
	v_mfma_f32_16x16x32_bf16 v[26:29], v[138:141], v[214:217], v[26:29]
	v_mfma_f32_16x16x32_bf16 v[26:29], v[152:155], v[218:221], v[26:29]
	v_mfma_f32_16x16x32_bf16 v[10:13], v[152:155], v[240:243], v[10:13]
	v_mfma_f32_16x16x32_bf16 v[10:13], v[138:141], v[236:239], v[10:13]
	v_mfma_f32_16x16x32_bf16 v[14:17], v[130:133], v[236:239], v[14:17]
	v_mfma_f32_16x16x32_bf16 v[14:17], v[134:137], v[240:243], v[14:17]
	v_mfma_f32_16x16x32_bf16 v[30:33], v[134:137], v[218:221], v[30:33]
	v_mfma_f32_16x16x32_bf16 v[30:33], v[130:133], v[214:217], v[30:33]
	v_mfma_f32_16x16x32_bf16 v[54:57], v[156:159], v[176:179], v[54:57]
	v_mfma_f32_16x16x32_bf16 v[54:57], v[160:163], v[180:183], v[54:57]
	v_mfma_f32_16x16x32_bf16 v[38:41], v[160:163], v[210:213], v[38:41]
	v_mfma_f32_16x16x32_bf16 v[38:41], v[156:159], v[206:209], v[38:41]
	v_mfma_f32_16x16x32_bf16 v[34:37], v[168:171], v[206:209], v[34:37]
	v_mfma_f32_16x16x32_bf16 v[34:37], v[172:175], v[210:213], v[34:37]
	v_mfma_f32_16x16x32_bf16 v[50:53], v[172:175], v[180:183], v[50:53]
	v_mfma_f32_16x16x32_bf16 v[50:53], v[168:171], v[176:179], v[50:53]
	v_mfma_f32_16x16x32_bf16 v[18:21], v[168:171], v[214:217], v[18:21]
	v_mfma_f32_16x16x32_bf16 v[18:21], v[172:175], v[218:221], v[18:21]
	v_mfma_f32_16x16x32_bf16 v[2:5], v[172:175], v[240:243], v[2:5]
	v_mfma_f32_16x16x32_bf16 v[2:5], v[168:171], v[236:239], v[2:5]
	v_mfma_f32_16x16x32_bf16 v[6:9], v[156:159], v[236:239], v[6:9]
	v_mfma_f32_16x16x32_bf16 v[6:9], v[160:163], v[240:243], v[6:9]
	v_mfma_f32_16x16x32_bf16 v[22:25], v[160:163], v[218:221], v[22:25]
	v_mfma_f32_16x16x32_bf16 v[22:25], v[156:159], v[214:217], v[22:25]
	s_barrier
	s_add_i32 s9, s9, 2
	s_add_u32 s38, s38, 0x100
	s_addc_u32 s39, s39, 0
	s_add_u32 s7, s7, 0x100
	s_addc_u32 s8, s8, 0
	s_cmpk_gt_u32 s9, 0x7d
	s_cbranch_scc0 .LBB0_1071
	s_and_b64 vcc, exec, s[72:73]
	s_cbranch_vccz .LBB0_1074
	s_barrier

; #define PG8_STAGE(bufoff, gbase, voff) do { _Pragma("unroll") for (int _i = 0; _i < 2; ++_i) \
;         __builtin_amdgcn_global_load_lds((const unsigned*)((const char*)(gbase) + (voff)[_i]), (PG8_LAS unsigned*)(lds + (bufoff) + ldsw + _i * 8192), 16, 0, 0); } while (0)
; #define PG8_LDA(dst, b, h) do { _Pragma("unroll") for (int m = 0; m < 4; ++m) _Pragma("unroll") for (int k = 0; k < 2; ++k) dst[m][k] = *(const PG8_LAS bf16x8*)(lds + PG8_SA(b, h) + aoff + m * 2048 + k * 1024); } while (0)
; #define PG8_LDB(dst, b, h) do { _Pragma("unroll") for (int n = 0; n < 2; ++n) _Pragma("unroll") for (int k = 0; k < 2; ++k) dst[n][k] = *(const PG8_LAS bf16x8*)(lds + PG8_SB(b, h) + boff + n * 2048 + k * 1024); } while (0)
; #define PG8_WAIT_V(n) asm volatile("s_waitcnt vmcnt(" #n ")" ::: "memory")
; #define PG8_WAIT_L(n) asm volatile("s_waitcnt lgkmcnt(" #n ")" ::: "memory")
; #define PG8_BAR __builtin_amdgcn_s_barrier()
; #define PG8_SCHED __builtin_amdgcn_sched_barrier(0)
; template <class Epi, class Sched, bool ALIGN_EPI = false, bool SP2 = false>
; __device__ __forceinline__ void gemm_phase(PG8_LAS unsigned char* lds, const Gemm g, const Sched& S, const Epi& E) {
;     ...
;         const bool has_next = S.next(ui + 1, nxt);
;         const char* nA = has_next ? (const char*)g.A + (size_t)nxt.pm * tstep : cA; const char* nB = has_next ? (const char*)g.Bt + (size_t)nxt.pn * tstep : cB;
;         for (int t = 0; t < nt; t += 2) {
;             const bool last = (t == nt - 2);
;             const char* a1 = cA + (size_t)(t + 1) * kstep;
;             const char* a2 = last ? nA : cA + (size_t)(t + 2) * kstep; const char* b2 = last ? nB : cB + (size_t)(t + 2) * kstep;
;             const char* a3 = a2 + kstep; const char* b3 = b2 + kstep;
;             if (last && has_next) S.a_ready(nxt);
;             if constexpr (SP2) {
;             PG8_LDB(B0, 0, 0); PG8_LDB(B1, 0, 1); PG8_SCHED; PG8_LDA(At, 0, 0); PG8_STAGE(PG8_SA(1, 1), a1 + hstep, voffA);
;             PG8_WAIT_V(8); PG8_WAIT_L(0); PG8_BAR; PG8_MMA(0, 0, At, B0); PG8_MMA(0, 1, At, B1); PG8_BAR; PG8_SCHED;
;             PG8_LDA(At, 0, 1); PG8_STAGE(PG8_SB(0, 0), b2, voffB); PG8_STAGE(PG8_SB(0, 1), b2 + hstepB, voffB); PG8_STAGE(PG8_SA(0, 0), a2, voffA);
;             PG8_WAIT_V(8); PG8_WAIT_L(0); PG8_BAR; PG8_MMA(1, 0, At, B0); PG8_MMA(1, 1, At, B1); PG8_BAR; PG8_SCHED;
.LBB0_1232:
	s_add_u32 s36, s80, 0x100
	s_addc_u32 s37, s81, 0
	s_ashr_i32 s73, s72, 31
	s_lshl_b64 s[4:5], s[72:73], 20
	s_add_u32 s78, s0, s4
	s_addc_u32 s79, s1, s5
	s_and_b64 s[4:5], s[46:47], exec
	s_cselect_b32 s4, s79, s69
	s_cselect_b32 s5, s78, s68
	s_ashr_i32 s71, s70, 31
	s_lshl_b64 s[6:7], s[70:71], 20
	s_add_u32 s76, s34, s6
	s_addc_u32 s77, s35, s7
	s_and_b64 s[6:7], s[46:47], exec
	s_cselect_b32 s6, s77, s81
	s_cselect_b32 s7, s76, s80
	s_add_u32 s8, s68, 0x80080
	s_addc_u32 s9, s69, 0
	v_lshl_add_u64 v[140:141], s[8:9], 0, v[136:137]
	v_lshl_add_u64 v[142:143], s[8:9], 0, v[138:139]
	s_mov_b32 s8, -2
	s_mov_b64 s[80:81], 0
	v_add_u32_e32 v186, 0x10000, v145
	v_add_u32_e32 v187, 0x14000, v145
	v_add_u32_e32 v198, 0x18000, v145
	v_add_u32_e32 v199, 0x1c000, v145
	s_add_u32 s9, s68, s80
	s_addc_u32 s10, s69, s81
	s_add_u32 s9, s9, 0x100
	s_addc_u32 s10, s10, 0
	s_add_u32 s100, s9, 0x7ff80
	s_addc_u32 s101, s10, 0
	s_add_u32 s11, s36, s80
	s_addc_u32 s12, s37, s81
	s_add_i32 s13, 0, 0x10000
	s_cmpk_eq_i32 s80, 0xf00
	s_cselect_b32 s93, s4, s10
	s_cselect_b32 s92, s5, s9
	s_cselect_b32 s85, s6, s12
	s_cselect_b32 s84, s7, s11
	s_add_i32 s9, 0, 0x14000
	ds_read_b128 v[152:155], v186
	ds_read_b128 v[156:159], v186 offset:1024
	ds_read_b128 v[160:163], v186 offset:2048
	ds_read_b128 v[164:167], v186 offset:3072
	ds_read_b128 v[168:171], v187
	ds_read_b128 v[172:175], v187 offset:1024
	ds_read_b128 v[176:179], v187 offset:2048
	ds_read_b128 v[180:183], v187 offset:3072
	s_add_i32 m0, s51, 0xc000
	ds_read_b128 v[206:209], v151
	ds_read_b128 v[210:213], v151 offset:1024
	ds_read_b128 v[214:217], v151 offset:2048
	ds_read_b128 v[218:221], v151 offset:3072
	ds_read_b128 v[236:239], v151 offset:4096
	ds_read_b128 v[240:243], v151 offset:5120
	ds_read_b128 v[244:247], v151 offset:6144
	ds_read_b128 v[194:197], v151 offset:7168
	global_load_lds_dwordx4 v136, s[100:101]
	s_add_i32 m0, s51, 0xe000
	s_nop 0
	global_load_lds_dwordx4 v138, s[100:101]
	s_waitcnt vmcnt(8)
	s_waitcnt lgkmcnt(0)
	s_barrier
	v_mfma_f32_16x16x32_bf16 v[126:129], v[152:155], v[206:209], 0
	v_mfma_f32_16x16x32_bf16 v[126:129], v[156:159], v[210:213], v[126:129]
	v_mfma_f32_16x16x32_bf16 v[118:121], v[156:159], v[218:221], 0
	v_mfma_f32_16x16x32_bf16 v[118:121], v[152:155], v[214:217], v[118:121]
	v_mfma_f32_16x16x32_bf16 v[114:117], v[160:163], v[214:217], 0
	v_mfma_f32_16x16x32_bf16 v[114:117], v[164:167], v[218:221], v[114:117]
	v_mfma_f32_16x16x32_bf16 v[122:125], v[164:167], v[210:213], 0
	v_mfma_f32_16x16x32_bf16 v[122:125], v[160:163], v[206:209], v[122:125]
	v_mfma_f32_16x16x32_bf16 v[106:109], v[160:163], v[236:239], 0
	v_mfma_f32_16x16x32_bf16 v[106:109], v[164:167], v[240:243], v[106:109]
	v_mfma_f32_16x16x32_bf16 v[98:101], v[164:167], v[194:197], 0
	v_mfma_f32_16x16x32_bf16 v[98:101], v[160:163], v[244:247], v[98:101]
	v_mfma_f32_16x16x32_bf16 v[102:105], v[152:155], v[244:247], 0
	v_mfma_f32_16x16x32_bf16 v[102:105], v[156:159], v[194:197], v[102:105]
	v_mfma_f32_16x16x32_bf16 v[110:113], v[156:159], v[240:243], 0
	v_mfma_f32_16x16x32_bf16 v[110:113], v[152:155], v[236:239], v[110:113]
	v_mfma_f32_16x16x32_bf16 v[94:97], v[168:171], v[206:209], 0
	v_mfma_f32_16x16x32_bf16 v[94:97], v[172:175], v[210:213], v[94:97]
	v_mfma_f32_16x16x32_bf16 v[86:89], v[172:175], v[218:221], 0
	v_mfma_f32_16x16x32_bf16 v[86:89], v[168:171], v[214:217], v[86:89]
	v_mfma_f32_16x16x32_bf16 v[82:85], v[176:179], v[214:217], 0
	v_mfma_f32_16x16x32_bf16 v[82:85], v[180:183], v[218:221], v[82:85]
	v_mfma_f32_16x16x32_bf16 v[90:93], v[180:183], v[210:213], 0
	v_mfma_f32_16x16x32_bf16 v[90:93], v[176:179], v[206:209], v[90:93]
	v_mfma_f32_16x16x32_bf16 v[74:77], v[176:179], v[236:239], 0
	v_mfma_f32_16x16x32_bf16 v[74:77], v[180:183], v[240:243], v[74:77]
	v_mfma_f32_16x16x32_bf16 v[66:69], v[180:183], v[194:197], 0
	v_mfma_f32_16x16x32_bf16 v[66:69], v[176:179], v[244:247], v[66:69]
	v_mfma_f32_16x16x32_bf16 v[70:73], v[168:171], v[244:247], 0
	v_mfma_f32_16x16x32_bf16 v[70:73], v[172:175], v[194:197], v[70:73]
	v_mfma_f32_16x16x32_bf16 v[78:81], v[172:175], v[240:243], 0
	v_mfma_f32_16x16x32_bf16 v[78:81], v[168:171], v[236:239], v[78:81]
	s_barrier
	s_add_i32 s10, s13, s42
	s_mov_b32 m0, s10
	ds_read_b128 v[194:197], v151 offset:16384
	ds_read_b128 v[206:209], v151 offset:17408
	ds_read_b128 v[210:213], v151 offset:18432
	ds_read_b128 v[214:217], v151 offset:19456
	ds_read_b128 v[218:221], v151 offset:20480
	ds_read_b128 v[236:239], v151 offset:21504
	ds_read_b128 v[240:243], v151 offset:22528
	ds_read_b128 v[244:247], v151 offset:23552
	global_load_lds_dwordx4 v130, s[84:85]
	s_add_i32 m0, s10, 0x2000
	s_add_u32 s10, s84, 0x20000
	s_addc_u32 s11, s85, 0
	s_add_i32 s9, s9, s42
	global_load_lds_dwordx4 v134, s[84:85]
	s_mov_b32 m0, s9
	s_nop 0
	global_load_lds_dwordx4 v130, s[10:11]
	s_add_i32 m0, s9, 0x2000
	s_nop 0
	global_load_lds_dwordx4 v134, s[10:11]
	s_mov_b32 m0, s51
	s_nop 0
	global_load_lds_dwordx4 v190, s[92:93]
	s_mov_b32 m0, s67
	s_nop 0
	global_load_lds_dwordx4 v132, s[92:93]
	s_waitcnt vmcnt(8)
	s_waitcnt lgkmcnt(0)
	s_barrier
; #define PG8_STAGE(bufoff, gbase, voff) do { _Pragma("unroll") for (int _i = 0; _i < 2; ++_i) \
;         __builtin_amdgcn_global_load_lds((const unsigned*)((const char*)(gbase) + (voff)[_i]), (PG8_LAS unsigned*)(lds + (bufoff) + ldsw + _i * 8192), 16, 0, 0); } while (0)
; #define PG8_LDA(dst, b, h) do { _Pragma("unroll") for (int m = 0; m < 4; ++m) _Pragma("unroll") for (int k = 0; k < 2; ++k) dst[m][k] = *(const PG8_LAS bf16x8*)(lds + PG8_SA(b, h) + aoff + m * 2048 + k * 1024); } while (0)
; #define PG8_LDB(dst, b, h) do { _Pragma("unroll") for (int n = 0; n < 2; ++n) _Pragma("unroll") for (int k = 0; k < 2; ++k) dst[n][k] = *(const PG8_LAS bf16x8*)(lds + PG8_SB(b, h) + boff + n * 2048 + k * 1024); } while (0)
; #define PG8_MMA(ai, bj, At, Bt) do { __builtin_amdgcn_s_setprio(1); _Pragma("unroll") for (int m = 0; m < 4; ++m) _Pragma("unroll") for (int n = 0; n < 2; ++n) _Pragma("unroll") for (int k = 0; k < 2; ++k) \
;         acc[ai][bj][m][n] = __builtin_amdgcn_mfma_f32_16x16x32_bf16(Bt[n][k], At[m][k], acc[ai][bj][m][n], 0, 0, 0); __builtin_amdgcn_s_setprio(0); } while (0)
; #define PG8_WAIT_V(n) asm volatile("s_waitcnt vmcnt(" #n ")" ::: "memory")
; #define PG8_WAIT_L(n) asm volatile("s_waitcnt lgkmcnt(" #n ")" ::: "memory")
; #define PG8_BAR __builtin_amdgcn_s_barrier()
; #define PG8_SCHED __builtin_amdgcn_sched_barrier(0)
; template <class Epi, class Sched, bool ALIGN_EPI = false, bool SP2 = false>
; __device__ __forceinline__ void gemm_phase(PG8_LAS unsigned char* lds, const Gemm g, const Sched& S, const Epi& E) {
;     ...
;             PG8_WAIT_V(8); PG8_WAIT_L(0); PG8_BAR; PG8_MMA(1, 0, At, B0); PG8_MMA(1, 1, At, B1); PG8_BAR; PG8_SCHED;
;             PG8_LDB(B0, 1, 0); PG8_LDB(B1, 1, 1); PG8_SCHED; PG8_LDA(At, 1, 0); PG8_STAGE(PG8_SA(0, 1), a2 + hstep, voffA);
;             PG8_WAIT_V(8); PG8_WAIT_L(0); PG8_BAR; PG8_MMA(0, 0, At, B0); PG8_MMA(0, 1, At, B1); PG8_BAR; PG8_SCHED;
	v_mfma_f32_16x16x32_bf16 v[62:65], v[152:155], v[194:197], 0
	v_mfma_f32_16x16x32_bf16 v[62:65], v[156:159], v[206:209], v[62:65]
	v_mfma_f32_16x16x32_bf16 v[54:57], v[156:159], v[214:217], 0
	v_mfma_f32_16x16x32_bf16 v[54:57], v[152:155], v[210:213], v[54:57]
	v_mfma_f32_16x16x32_bf16 v[50:53], v[160:163], v[210:213], 0
	v_mfma_f32_16x16x32_bf16 v[50:53], v[164:167], v[214:217], v[50:53]
	v_mfma_f32_16x16x32_bf16 v[58:61], v[164:167], v[206:209], 0
	v_mfma_f32_16x16x32_bf16 v[58:61], v[160:163], v[194:197], v[58:61]
	v_mfma_f32_16x16x32_bf16 v[42:45], v[160:163], v[218:221], 0
	v_mfma_f32_16x16x32_bf16 v[42:45], v[164:167], v[236:239], v[42:45]
	v_mfma_f32_16x16x32_bf16 v[34:37], v[164:167], v[244:247], 0
	v_mfma_f32_16x16x32_bf16 v[34:37], v[160:163], v[240:243], v[34:37]
	v_mfma_f32_16x16x32_bf16 v[38:41], v[152:155], v[240:243], 0
	v_mfma_f32_16x16x32_bf16 v[38:41], v[156:159], v[244:247], v[38:41]
	v_mfma_f32_16x16x32_bf16 v[46:49], v[156:159], v[236:239], 0
	v_mfma_f32_16x16x32_bf16 v[46:49], v[152:155], v[218:221], v[46:49]
	v_mfma_f32_16x16x32_bf16 v[30:33], v[168:171], v[194:197], 0
	v_mfma_f32_16x16x32_bf16 v[30:33], v[172:175], v[206:209], v[30:33]
	v_mfma_f32_16x16x32_bf16 v[22:25], v[172:175], v[214:217], 0
	v_mfma_f32_16x16x32_bf16 v[22:25], v[168:171], v[210:213], v[22:25]
	v_mfma_f32_16x16x32_bf16 v[18:21], v[176:179], v[210:213], 0
	v_mfma_f32_16x16x32_bf16 v[18:21], v[180:183], v[214:217], v[18:21]
	v_mfma_f32_16x16x32_bf16 v[26:29], v[180:183], v[206:209], 0
	v_mfma_f32_16x16x32_bf16 v[26:29], v[176:179], v[194:197], v[26:29]
	v_mfma_f32_16x16x32_bf16 v[10:13], v[176:179], v[218:221], 0
	v_mfma_f32_16x16x32_bf16 v[10:13], v[180:183], v[236:239], v[10:13]
	v_mfma_f32_16x16x32_bf16 v[2:5], v[180:183], v[244:247], 0
	v_mfma_f32_16x16x32_bf16 v[2:5], v[176:179], v[240:243], v[2:5]
	v_mfma_f32_16x16x32_bf16 v[6:9], v[168:171], v[240:243], 0
	v_mfma_f32_16x16x32_bf16 v[6:9], v[172:175], v[244:247], v[6:9]
	v_mfma_f32_16x16x32_bf16 v[14:17], v[172:175], v[236:239], 0
	v_mfma_f32_16x16x32_bf16 v[14:17], v[168:171], v[218:221], v[14:17]
	s_barrier
	s_add_i32 s9, 0, 0x18000
	s_add_i32 s12, 0, 0x1c000
	ds_read_b128 v[152:155], v198
	ds_read_b128 v[156:159], v198 offset:1024
	ds_read_b128 v[160:163], v198 offset:2048
	ds_read_b128 v[164:167], v198 offset:3072
	ds_read_b128 v[168:171], v199
	ds_read_b128 v[172:175], v199 offset:1024
	ds_read_b128 v[176:179], v199 offset:2048
	ds_read_b128 v[180:183], v199 offset:3072
	s_add_u32 s10, s92, 0x80000
	s_addc_u32 s11, s93, 0
	s_mov_b32 m0, s74
	ds_read_b128 v[194:197], v151 offset:32768
	ds_read_b128 v[206:209], v151 offset:33792
	ds_read_b128 v[210:213], v151 offset:34816
	ds_read_b128 v[214:217], v151 offset:35840
	ds_read_b128 v[218:221], v151 offset:36864
	ds_read_b128 v[236:239], v151 offset:37888
	ds_read_b128 v[240:243], v151 offset:38912
	ds_read_b128 v[244:247], v151 offset:39936
	global_load_lds_dwordx4 v190, s[10:11]
	s_mov_b32 m0, s75
	s_nop 0
	global_load_lds_dwordx4 v132, s[10:11]
	s_waitcnt vmcnt(8)
	s_waitcnt lgkmcnt(0)
	s_barrier
	v_mfma_f32_16x16x32_bf16 v[126:129], v[152:155], v[194:197], v[126:129]
	v_mfma_f32_16x16x32_bf16 v[126:129], v[156:159], v[206:209], v[126:129]
	v_mfma_f32_16x16x32_bf16 v[118:121], v[156:159], v[214:217], v[118:121]
	v_mfma_f32_16x16x32_bf16 v[118:121], v[152:155], v[210:213], v[118:121]
	v_mfma_f32_16x16x32_bf16 v[114:117], v[160:163], v[210:213], v[114:117]
	v_mfma_f32_16x16x32_bf16 v[114:117], v[164:167], v[214:217], v[114:117]
	v_mfma_f32_16x16x32_bf16 v[122:125], v[164:167], v[206:209], v[122:125]
	v_mfma_f32_16x16x32_bf16 v[122:125], v[160:163], v[194:197], v[122:125]
	v_mfma_f32_16x16x32_bf16 v[106:109], v[160:163], v[218:221], v[106:109]
	v_mfma_f32_16x16x32_bf16 v[106:109], v[164:167], v[236:239], v[106:109]
	v_mfma_f32_16x16x32_bf16 v[98:101], v[164:167], v[244:247], v[98:101]
	v_mfma_f32_16x16x32_bf16 v[98:101], v[160:163], v[240:243], v[98:101]
	v_mfma_f32_16x16x32_bf16 v[102:105], v[152:155], v[240:243], v[102:105]
	v_mfma_f32_16x16x32_bf16 v[102:105], v[156:159], v[244:247], v[102:105]
	v_mfma_f32_16x16x32_bf16 v[110:113], v[156:159], v[236:239], v[110:113]
	v_mfma_f32_16x16x32_bf16 v[110:113], v[152:155], v[218:221], v[110:113]
	v_mfma_f32_16x16x32_bf16 v[94:97], v[168:171], v[194:197], v[94:97]
	v_mfma_f32_16x16x32_bf16 v[94:97], v[172:175], v[206:209], v[94:97]
	v_mfma_f32_16x16x32_bf16 v[86:89], v[172:175], v[214:217], v[86:89]
	v_mfma_f32_16x16x32_bf16 v[86:89], v[168:171], v[210:213], v[86:89]
	v_mfma_f32_16x16x32_bf16 v[82:85], v[176:179], v[210:213], v[82:85]
	v_mfma_f32_16x16x32_bf16 v[82:85], v[180:183], v[214:217], v[82:85]
	v_mfma_f32_16x16x32_bf16 v[90:93], v[180:183], v[206:209], v[90:93]
	v_mfma_f32_16x16x32_bf16 v[90:93], v[176:179], v[194:197], v[90:93]
	v_mfma_f32_16x16x32_bf16 v[74:77], v[176:179], v[218:221], v[74:77]
	v_mfma_f32_16x16x32_bf16 v[74:77], v[180:183], v[236:239], v[74:77]
	v_mfma_f32_16x16x32_bf16 v[66:69], v[180:183], v[244:247], v[66:69]
	v_mfma_f32_16x16x32_bf16 v[66:69], v[176:179], v[240:243], v[66:69]
	v_mfma_f32_16x16x32_bf16 v[70:73], v[168:171], v[240:243], v[70:73]
	v_mfma_f32_16x16x32_bf16 v[70:73], v[172:175], v[244:247], v[70:73]
	v_mfma_f32_16x16x32_bf16 v[78:81], v[172:175], v[236:239], v[78:81]
	v_mfma_f32_16x16x32_bf16 v[78:81], v[168:171], v[218:221], v[78:81]
	s_barrier
; #define PG8_STAGE(bufoff, gbase, voff) do { _Pragma("unroll") for (int _i = 0; _i < 2; ++_i) \
;         __builtin_amdgcn_global_load_lds((const unsigned*)((const char*)(gbase) + (voff)[_i]), (PG8_LAS unsigned*)(lds + (bufoff) + ldsw + _i * 8192), 16, 0, 0); } while (0)
; #define PG8_LDA(dst, b, h) do { _Pragma("unroll") for (int m = 0; m < 4; ++m) _Pragma("unroll") for (int k = 0; k < 2; ++k) dst[m][k] = *(const PG8_LAS bf16x8*)(lds + PG8_SA(b, h) + aoff + m * 2048 + k * 1024); } while (0)
; #define PG8_LDB(dst, b, h) do { _Pragma("unroll") for (int n = 0; n < 2; ++n) _Pragma("unroll") for (int k = 0; k < 2; ++k) dst[n][k] = *(const PG8_LAS bf16x8*)(lds + PG8_SB(b, h) + boff + n * 2048 + k * 1024); } while (0)
; #define PG8_BAR __builtin_amdgcn_s_barrier()
; template <class Epi, class Sched, bool ALIGN_EPI = false, bool SP2 = false>
; __device__ __forceinline__ void gemm_phase(PG8_LAS unsigned char* lds, const Gemm g, const Sched& S, const Epi& E) {
;     ...
;             const bool last = (t == nt - 2);
;             const char* a1 = cA + (size_t)(t + 1) * kstep;
;             const char* a2 = last ? nA : cA + (size_t)(t + 2) * kstep; const char* b2 = last ? nB : cB + (size_t)(t + 2) * kstep;
;             const char* a3 = a2 + kstep; const char* b3 = b2 + kstep;
;             if (last && has_next) S.a_ready(nxt);
;             if constexpr (SP2) {
;             PG8_LDB(B0, 0, 0); PG8_LDB(B1, 0, 1); PG8_SCHED; PG8_LDA(At, 0, 0); PG8_STAGE(PG8_SA(1, 1), a1 + hstep, voffA);
;             PG8_WAIT_V(8); PG8_WAIT_L(0); PG8_BAR; PG8_MMA(0, 0, At, B0); PG8_MMA(0, 1, At, B1); PG8_BAR; PG8_SCHED;
;             PG8_LDA(At, 0, 1); PG8_STAGE(PG8_SB(0, 0), b2, voffB); PG8_STAGE(PG8_SB(0, 1), b2 + hstepB, voffB); PG8_STAGE(PG8_SA(0, 0), a2, voffA);
;             PG8_WAIT_V(8); PG8_WAIT_L(0); PG8_BAR; PG8_MMA(1, 0, At, B0); PG8_MMA(1, 1, At, B1); PG8_BAR; PG8_SCHED;
;             PG8_LDB(B0, 1, 0); PG8_LDB(B1, 1, 1); PG8_SCHED; PG8_LDA(At, 1, 0); PG8_STAGE(PG8_SA(0, 1), a2 + hstep, voffA);
;             PG8_WAIT_V(8); PG8_WAIT_L(0); PG8_BAR; PG8_MMA(0, 0, At, B0); PG8_MMA(0, 1, At, B1); PG8_BAR; PG8_SCHED;
;             PG8_LDA(At, 1, 1); PG8_STAGE(PG8_SB(1, 0), b3, voffB); PG8_STAGE(PG8_SB(1, 1), b3 + hstepB, voffB); PG8_STAGE(PG8_SA(1, 0), a3, voffA);
;             PG8_WAIT_V(8); PG8_WAIT_L(0); PG8_BAR; PG8_MMA(1, 0, At, B0); PG8_MMA(1, 1, At, B1); PG8_BAR; PG8_SCHED;
	s_add_i32 s9, s9, s42
	s_mov_b32 m0, s9
	ds_read_b128 v[194:197], v151 offset:49152
	ds_read_b128 v[206:209], v151 offset:50176
	ds_read_b128 v[210:213], v151 offset:51200
	ds_read_b128 v[214:217], v151 offset:52224
	ds_read_b128 v[218:221], v151 offset:53248
	ds_read_b128 v[236:239], v151 offset:54272
	ds_read_b128 v[240:243], v151 offset:55296
	ds_read_b128 v[244:247], v151 offset:56320
	s_add_u32 s100, s84, s60
	s_addc_u32 s101, s85, s61
	global_load_lds_dwordx4 v130, s[100:101]
	s_add_i32 m0, s9, 0x2000
	s_add_u32 s10, s84, 0x20080
	s_addc_u32 s11, s85, 0
	s_add_i32 s9, s12, s42
	global_load_lds_dwordx4 v134, s[100:101]
	s_mov_b32 m0, s9
	s_nop 0
	global_load_lds_dwordx4 v130, s[10:11]
	s_add_i32 m0, s9, 0x2000
	s_nop 0
	global_load_lds_dwordx4 v134, s[10:11]
	s_mov_b32 m0, s82
	s_add_u32 s100, s92, s60
	s_addc_u32 s101, s93, s61
	global_load_lds_dwordx4 v190, s[100:101]
	s_mov_b32 m0, s86
	s_nop 0
	global_load_lds_dwordx4 v132, s[100:101]
	s_waitcnt vmcnt(8)
	s_waitcnt lgkmcnt(0)
	s_barrier
	v_mfma_f32_16x16x32_bf16 v[62:65], v[152:155], v[194:197], v[62:65]
	v_mfma_f32_16x16x32_bf16 v[62:65], v[156:159], v[206:209], v[62:65]
	v_mfma_f32_16x16x32_bf16 v[54:57], v[156:159], v[214:217], v[54:57]
	v_mfma_f32_16x16x32_bf16 v[54:57], v[152:155], v[210:213], v[54:57]
	v_mfma_f32_16x16x32_bf16 v[50:53], v[160:163], v[210:213], v[50:53]
	v_mfma_f32_16x16x32_bf16 v[50:53], v[164:167], v[214:217], v[50:53]
	v_mfma_f32_16x16x32_bf16 v[58:61], v[164:167], v[206:209], v[58:61]
	v_mfma_f32_16x16x32_bf16 v[58:61], v[160:163], v[194:197], v[58:61]
	v_mfma_f32_16x16x32_bf16 v[42:45], v[160:163], v[218:221], v[42:45]
	v_mfma_f32_16x16x32_bf16 v[42:45], v[164:167], v[236:239], v[42:45]
	v_mfma_f32_16x16x32_bf16 v[34:37], v[164:167], v[244:247], v[34:37]
	v_mfma_f32_16x16x32_bf16 v[34:37], v[160:163], v[240:243], v[34:37]
	v_mfma_f32_16x16x32_bf16 v[38:41], v[152:155], v[240:243], v[38:41]
	v_mfma_f32_16x16x32_bf16 v[38:41], v[156:159], v[244:247], v[38:41]
	v_mfma_f32_16x16x32_bf16 v[46:49], v[156:159], v[236:239], v[46:49]
	v_mfma_f32_16x16x32_bf16 v[46:49], v[152:155], v[218:221], v[46:49]
	v_mfma_f32_16x16x32_bf16 v[30:33], v[168:171], v[194:197], v[30:33]
	v_mfma_f32_16x16x32_bf16 v[30:33], v[172:175], v[206:209], v[30:33]
	v_mfma_f32_16x16x32_bf16 v[22:25], v[172:175], v[214:217], v[22:25]
	v_mfma_f32_16x16x32_bf16 v[22:25], v[168:171], v[210:213], v[22:25]
	v_mfma_f32_16x16x32_bf16 v[18:21], v[176:179], v[210:213], v[18:21]
	v_mfma_f32_16x16x32_bf16 v[18:21], v[180:183], v[214:217], v[18:21]
	v_mfma_f32_16x16x32_bf16 v[26:29], v[180:183], v[206:209], v[26:29]
	v_mfma_f32_16x16x32_bf16 v[26:29], v[176:179], v[194:197], v[26:29]
	v_mfma_f32_16x16x32_bf16 v[10:13], v[176:179], v[218:221], v[10:13]
	v_mfma_f32_16x16x32_bf16 v[10:13], v[180:183], v[236:239], v[10:13]
	v_mfma_f32_16x16x32_bf16 v[2:5], v[180:183], v[244:247], v[2:5]
	v_mfma_f32_16x16x32_bf16 v[2:5], v[176:179], v[240:243], v[2:5]
	v_mfma_f32_16x16x32_bf16 v[6:9], v[168:171], v[240:243], v[6:9]
	v_mfma_f32_16x16x32_bf16 v[6:9], v[172:175], v[244:247], v[6:9]
	v_mfma_f32_16x16x32_bf16 v[14:17], v[172:175], v[236:239], v[14:17]
	v_mfma_f32_16x16x32_bf16 v[14:17], v[168:171], v[218:221], v[14:17]
	s_barrier
	s_add_i32 s8, s8, 2
	s_add_u32 s80, s80, 0x100
	s_addc_u32 s81, s81, 0
	s_cmp_gt_u32 s8, 29
.LBB0_1233:
	s_add_u32 s9, s68, s80
	s_addc_u32 s10, s69, s81
	s_add_u32 s9, s9, 0x100
	s_addc_u32 s10, s10, 0
	s_add_u32 s100, s9, 0x7ff80
	s_addc_u32 s101, s10, 0
	s_add_u32 s11, s36, s80
	s_addc_u32 s12, s37, s81
	s_add_i32 s13, 0, 0x10000
	s_cmpk_eq_i32 s80, 0xf00
	s_cselect_b32 s93, s4, s10
	s_cselect_b32 s92, s5, s9
	s_cselect_b32 s85, s6, s12
	s_cselect_b32 s84, s7, s11
	s_add_i32 s9, 0, 0x14000
	ds_read_b128 v[152:155], v186
	ds_read_b128 v[156:159], v186 offset:1024
	ds_read_b128 v[160:163], v186 offset:2048
	ds_read_b128 v[164:167], v186 offset:3072
	ds_read_b128 v[168:171], v187
	ds_read_b128 v[172:175], v187 offset:1024
	ds_read_b128 v[176:179], v187 offset:2048
	ds_read_b128 v[180:183], v187 offset:3072
	s_add_i32 m0, s51, 0xc000
	ds_read_b128 v[206:209], v151
	ds_read_b128 v[210:213], v151 offset:1024
	ds_read_b128 v[214:217], v151 offset:2048
	ds_read_b128 v[218:221], v151 offset:3072
	ds_read_b128 v[236:239], v151 offset:4096
	ds_read_b128 v[240:243], v151 offset:5120
	ds_read_b128 v[244:247], v151 offset:6144
	ds_read_b128 v[194:197], v151 offset:7168
	global_load_lds_dwordx4 v136, s[100:101]
	s_add_i32 m0, s51, 0xe000
	s_nop 0
	global_load_lds_dwordx4 v138, s[100:101]
	s_waitcnt vmcnt(8)
	s_waitcnt lgkmcnt(0)
	s_barrier
; #define PG8_STAGE(bufoff, gbase, voff) do { _Pragma("unroll") for (int _i = 0; _i < 2; ++_i) \
;         __builtin_amdgcn_global_load_lds((const unsigned*)((const char*)(gbase) + (voff)[_i]), (PG8_LAS unsigned*)(lds + (bufoff) + ldsw + _i * 8192), 16, 0, 0); } while (0)
; #define PG8_LDA(dst, b, h) do { _Pragma("unroll") for (int m = 0; m < 4; ++m) _Pragma("unroll") for (int k = 0; k < 2; ++k) dst[m][k] = *(const PG8_LAS bf16x8*)(lds + PG8_SA(b, h) + aoff + m * 2048 + k * 1024); } while (0)
; #define PG8_MMA(ai, bj, At, Bt) do { __builtin_amdgcn_s_setprio(1); _Pragma("unroll") for (int m = 0; m < 4; ++m) _Pragma("unroll") for (int n = 0; n < 2; ++n) _Pragma("unroll") for (int k = 0; k < 2; ++k) \
;         acc[ai][bj][m][n] = __builtin_amdgcn_mfma_f32_16x16x32_bf16(Bt[n][k], At[m][k], acc[ai][bj][m][n], 0, 0, 0); __builtin_amdgcn_s_setprio(0); } while (0)
; #define PG8_WAIT_V(n) asm volatile("s_waitcnt vmcnt(" #n ")" ::: "memory")
; #define PG8_WAIT_L(n) asm volatile("s_waitcnt lgkmcnt(" #n ")" ::: "memory")
; #define PG8_BAR __builtin_amdgcn_s_barrier()
; #define PG8_SCHED __builtin_amdgcn_sched_barrier(0)
; template <class Epi, class Sched, bool ALIGN_EPI = false, bool SP2 = false>
; __device__ __forceinline__ void gemm_phase(PG8_LAS unsigned char* lds, const Gemm g, const Sched& S, const Epi& E) {
;     ...
;             PG8_WAIT_V(8); PG8_WAIT_L(0); PG8_BAR; PG8_MMA(0, 0, At, B0); PG8_MMA(0, 1, At, B1); PG8_BAR; PG8_SCHED;
;             PG8_LDA(At, 0, 1); PG8_STAGE(PG8_SB(0, 0), b2, voffB); PG8_STAGE(PG8_SB(0, 1), b2 + hstepB, voffB); PG8_STAGE(PG8_SA(0, 0), a2, voffA);
;             PG8_WAIT_V(8); PG8_WAIT_L(0); PG8_BAR; PG8_MMA(1, 0, At, B0); PG8_MMA(1, 1, At, B1); PG8_BAR; PG8_SCHED;
	v_mfma_f32_16x16x32_bf16 v[126:129], v[152:155], v[206:209], v[126:129]
	v_mfma_f32_16x16x32_bf16 v[126:129], v[156:159], v[210:213], v[126:129]
	v_mfma_f32_16x16x32_bf16 v[118:121], v[156:159], v[218:221], v[118:121]
	v_mfma_f32_16x16x32_bf16 v[118:121], v[152:155], v[214:217], v[118:121]
	v_mfma_f32_16x16x32_bf16 v[114:117], v[160:163], v[214:217], v[114:117]
	v_mfma_f32_16x16x32_bf16 v[114:117], v[164:167], v[218:221], v[114:117]
	v_mfma_f32_16x16x32_bf16 v[122:125], v[164:167], v[210:213], v[122:125]
	v_mfma_f32_16x16x32_bf16 v[122:125], v[160:163], v[206:209], v[122:125]
	v_mfma_f32_16x16x32_bf16 v[106:109], v[160:163], v[236:239], v[106:109]
	v_mfma_f32_16x16x32_bf16 v[106:109], v[164:167], v[240:243], v[106:109]
	v_mfma_f32_16x16x32_bf16 v[98:101], v[164:167], v[194:197], v[98:101]
	v_mfma_f32_16x16x32_bf16 v[98:101], v[160:163], v[244:247], v[98:101]
	v_mfma_f32_16x16x32_bf16 v[102:105], v[152:155], v[244:247], v[102:105]
	v_mfma_f32_16x16x32_bf16 v[102:105], v[156:159], v[194:197], v[102:105]
	v_mfma_f32_16x16x32_bf16 v[110:113], v[156:159], v[240:243], v[110:113]
	v_mfma_f32_16x16x32_bf16 v[110:113], v[152:155], v[236:239], v[110:113]
	v_mfma_f32_16x16x32_bf16 v[94:97], v[168:171], v[206:209], v[94:97]
	v_mfma_f32_16x16x32_bf16 v[94:97], v[172:175], v[210:213], v[94:97]
	v_mfma_f32_16x16x32_bf16 v[86:89], v[172:175], v[218:221], v[86:89]
	v_mfma_f32_16x16x32_bf16 v[86:89], v[168:171], v[214:217], v[86:89]
	v_mfma_f32_16x16x32_bf16 v[82:85], v[176:179], v[214:217], v[82:85]
	v_mfma_f32_16x16x32_bf16 v[82:85], v[180:183], v[218:221], v[82:85]
	v_mfma_f32_16x16x32_bf16 v[90:93], v[180:183], v[210:213], v[90:93]
	v_mfma_f32_16x16x32_bf16 v[90:93], v[176:179], v[206:209], v[90:93]
	v_mfma_f32_16x16x32_bf16 v[74:77], v[176:179], v[236:239], v[74:77]
	v_mfma_f32_16x16x32_bf16 v[74:77], v[180:183], v[240:243], v[74:77]
	v_mfma_f32_16x16x32_bf16 v[66:69], v[180:183], v[194:197], v[66:69]
	v_mfma_f32_16x16x32_bf16 v[66:69], v[176:179], v[244:247], v[66:69]
	v_mfma_f32_16x16x32_bf16 v[70:73], v[168:171], v[244:247], v[70:73]
	v_mfma_f32_16x16x32_bf16 v[70:73], v[172:175], v[194:197], v[70:73]
	v_mfma_f32_16x16x32_bf16 v[78:81], v[172:175], v[240:243], v[78:81]
	v_mfma_f32_16x16x32_bf16 v[78:81], v[168:171], v[236:239], v[78:81]
	s_barrier
	s_add_i32 s10, s13, s42
	s_mov_b32 m0, s10
	ds_read_b128 v[194:197], v151 offset:16384
	ds_read_b128 v[206:209], v151 offset:17408
	ds_read_b128 v[210:213], v151 offset:18432
	ds_read_b128 v[214:217], v151 offset:19456
	ds_read_b128 v[218:221], v151 offset:20480
	ds_read_b128 v[236:239], v151 offset:21504
	ds_read_b128 v[240:243], v151 offset:22528
	ds_read_b128 v[244:247], v151 offset:23552
	global_load_lds_dwordx4 v130, s[84:85]
	s_add_i32 m0, s10, 0x2000
	s_add_u32 s10, s84, 0x20000
	s_addc_u32 s11, s85, 0
	s_add_i32 s9, s9, s42
	global_load_lds_dwordx4 v134, s[84:85]
	s_mov_b32 m0, s9
	s_nop 0
	global_load_lds_dwordx4 v130, s[10:11]
	s_add_i32 m0, s9, 0x2000
	s_nop 0
	global_load_lds_dwordx4 v134, s[10:11]
	s_mov_b32 m0, s51
	s_nop 0
	global_load_lds_dwordx4 v190, s[92:93]
	s_mov_b32 m0, s67
	s_nop 0
	global_load_lds_dwordx4 v132, s[92:93]
	s_waitcnt vmcnt(8)
	s_waitcnt lgkmcnt(0)
	s_barrier
	v_mfma_f32_16x16x32_bf16 v[62:65], v[152:155], v[194:197], v[62:65]
	v_mfma_f32_16x16x32_bf16 v[62:65], v[156:159], v[206:209], v[62:65]
	v_mfma_f32_16x16x32_bf16 v[54:57], v[156:159], v[214:217], v[54:57]
	v_mfma_f32_16x16x32_bf16 v[54:57], v[152:155], v[210:213], v[54:57]
	v_mfma_f32_16x16x32_bf16 v[50:53], v[160:163], v[210:213], v[50:53]
	v_mfma_f32_16x16x32_bf16 v[50:53], v[164:167], v[214:217], v[50:53]
	v_mfma_f32_16x16x32_bf16 v[58:61], v[164:167], v[206:209], v[58:61]
	v_mfma_f32_16x16x32_bf16 v[58:61], v[160:163], v[194:197], v[58:61]
	v_mfma_f32_16x16x32_bf16 v[42:45], v[160:163], v[218:221], v[42:45]
	v_mfma_f32_16x16x32_bf16 v[42:45], v[164:167], v[236:239], v[42:45]
	v_mfma_f32_16x16x32_bf16 v[34:37], v[164:167], v[244:247], v[34:37]
	v_mfma_f32_16x16x32_bf16 v[34:37], v[160:163], v[240:243], v[34:37]
	v_mfma_f32_16x16x32_bf16 v[38:41], v[152:155], v[240:243], v[38:41]
	v_mfma_f32_16x16x32_bf16 v[38:41], v[156:159], v[244:247], v[38:41]
	v_mfma_f32_16x16x32_bf16 v[46:49], v[156:159], v[236:239], v[46:49]
	v_mfma_f32_16x16x32_bf16 v[46:49], v[152:155], v[218:221], v[46:49]
	v_mfma_f32_16x16x32_bf16 v[30:33], v[168:171], v[194:197], v[30:33]
	v_mfma_f32_16x16x32_bf16 v[30:33], v[172:175], v[206:209], v[30:33]
	v_mfma_f32_16x16x32_bf16 v[22:25], v[172:175], v[214:217], v[22:25]
	v_mfma_f32_16x16x32_bf16 v[22:25], v[168:171], v[210:213], v[22:25]
	v_mfma_f32_16x16x32_bf16 v[18:21], v[176:179], v[210:213], v[18:21]
	v_mfma_f32_16x16x32_bf16 v[18:21], v[180:183], v[214:217], v[18:21]
	v_mfma_f32_16x16x32_bf16 v[26:29], v[180:183], v[206:209], v[26:29]
	v_mfma_f32_16x16x32_bf16 v[26:29], v[176:179], v[194:197], v[26:29]
	v_mfma_f32_16x16x32_bf16 v[10:13], v[176:179], v[218:221], v[10:13]
	v_mfma_f32_16x16x32_bf16 v[10:13], v[180:183], v[236:239], v[10:13]
	v_mfma_f32_16x16x32_bf16 v[2:5], v[180:183], v[244:247], v[2:5]
	v_mfma_f32_16x16x32_bf16 v[2:5], v[176:179], v[240:243], v[2:5]
	v_mfma_f32_16x16x32_bf16 v[6:9], v[168:171], v[240:243], v[6:9]
	v_mfma_f32_16x16x32_bf16 v[6:9], v[172:175], v[244:247], v[6:9]
	v_mfma_f32_16x16x32_bf16 v[14:17], v[172:175], v[236:239], v[14:17]
	v_mfma_f32_16x16x32_bf16 v[14:17], v[168:171], v[218:221], v[14:17]
	s_barrier
; #define PG8_STAGE(bufoff, gbase, voff) do { _Pragma("unroll") for (int _i = 0; _i < 2; ++_i) \
;         __builtin_amdgcn_global_load_lds((const unsigned*)((const char*)(gbase) + (voff)[_i]), (PG8_LAS unsigned*)(lds + (bufoff) + ldsw + _i * 8192), 16, 0, 0); } while (0)
; #define PG8_LDA(dst, b, h) do { _Pragma("unroll") for (int m = 0; m < 4; ++m) _Pragma("unroll") for (int k = 0; k < 2; ++k) dst[m][k] = *(const PG8_LAS bf16x8*)(lds + PG8_SA(b, h) + aoff + m * 2048 + k * 1024); } while (0)
; #define PG8_LDB(dst, b, h) do { _Pragma("unroll") for (int n = 0; n < 2; ++n) _Pragma("unroll") for (int k = 0; k < 2; ++k) dst[n][k] = *(const PG8_LAS bf16x8*)(lds + PG8_SB(b, h) + boff + n * 2048 + k * 1024); } while (0)
; #define PG8_MMA(ai, bj, At, Bt) do { __builtin_amdgcn_s_setprio(1); _Pragma("unroll") for (int m = 0; m < 4; ++m) _Pragma("unroll") for (int n = 0; n < 2; ++n) _Pragma("unroll") for (int k = 0; k < 2; ++k) \
;         acc[ai][bj][m][n] = __builtin_amdgcn_mfma_f32_16x16x32_bf16(Bt[n][k], At[m][k], acc[ai][bj][m][n], 0, 0, 0); __builtin_amdgcn_s_setprio(0); } while (0)
; #define PG8_WAIT_V(n) asm volatile("s_waitcnt vmcnt(" #n ")" ::: "memory")
; #define PG8_WAIT_L(n) asm volatile("s_waitcnt lgkmcnt(" #n ")" ::: "memory")
; #define PG8_BAR __builtin_amdgcn_s_barrier()
; #define PG8_SCHED __builtin_amdgcn_sched_barrier(0)
; template <class Epi, class Sched, bool ALIGN_EPI = false, bool SP2 = false>
; __device__ __forceinline__ void gemm_phase(PG8_LAS unsigned char* lds, const Gemm g, const Sched& S, const Epi& E) {
;     ...
;             PG8_LDB(B0, 1, 0); PG8_LDB(B1, 1, 1); PG8_SCHED; PG8_LDA(At, 1, 0); PG8_STAGE(PG8_SA(0, 1), a2 + hstep, voffA);
;             PG8_WAIT_V(8); PG8_WAIT_L(0); PG8_BAR; PG8_MMA(0, 0, At, B0); PG8_MMA(0, 1, At, B1); PG8_BAR; PG8_SCHED;
;             PG8_LDA(At, 1, 1); PG8_STAGE(PG8_SB(1, 0), b3, voffB); PG8_STAGE(PG8_SB(1, 1), b3 + hstepB, voffB); PG8_STAGE(PG8_SA(1, 0), a3, voffA);
;             PG8_WAIT_V(8); PG8_WAIT_L(0); PG8_BAR; PG8_MMA(1, 0, At, B0); PG8_MMA(1, 1, At, B1); PG8_BAR; PG8_SCHED;
;     ...
;         if constexpr (ALIGN_EPI) { if (wr == 0) PG8_BAR; }
	s_add_i32 s9, 0, 0x18000
	s_add_i32 s12, 0, 0x1c000
	ds_read_b128 v[152:155], v198
	ds_read_b128 v[156:159], v198 offset:1024
	ds_read_b128 v[160:163], v198 offset:2048
	ds_read_b128 v[164:167], v198 offset:3072
	ds_read_b128 v[168:171], v199
	ds_read_b128 v[172:175], v199 offset:1024
	ds_read_b128 v[176:179], v199 offset:2048
	ds_read_b128 v[180:183], v199 offset:3072
	s_add_u32 s10, s92, 0x80000
	s_addc_u32 s11, s93, 0
	s_mov_b32 m0, s74
	ds_read_b128 v[194:197], v151 offset:32768
	ds_read_b128 v[206:209], v151 offset:33792
	ds_read_b128 v[210:213], v151 offset:34816
	ds_read_b128 v[214:217], v151 offset:35840
	ds_read_b128 v[218:221], v151 offset:36864
	ds_read_b128 v[236:239], v151 offset:37888
	ds_read_b128 v[240:243], v151 offset:38912
	ds_read_b128 v[244:247], v151 offset:39936
	global_load_lds_dwordx4 v190, s[10:11]
	s_mov_b32 m0, s75
	s_nop 0
	global_load_lds_dwordx4 v132, s[10:11]
	s_waitcnt vmcnt(8)
	s_waitcnt lgkmcnt(0)
	s_barrier
	v_mfma_f32_16x16x32_bf16 v[126:129], v[152:155], v[194:197], v[126:129]
	v_mfma_f32_16x16x32_bf16 v[126:129], v[156:159], v[206:209], v[126:129]
	v_mfma_f32_16x16x32_bf16 v[118:121], v[156:159], v[214:217], v[118:121]
	v_mfma_f32_16x16x32_bf16 v[118:121], v[152:155], v[210:213], v[118:121]
	v_mfma_f32_16x16x32_bf16 v[114:117], v[160:163], v[210:213], v[114:117]
	v_mfma_f32_16x16x32_bf16 v[114:117], v[164:167], v[214:217], v[114:117]
	v_mfma_f32_16x16x32_bf16 v[122:125], v[164:167], v[206:209], v[122:125]
	v_mfma_f32_16x16x32_bf16 v[122:125], v[160:163], v[194:197], v[122:125]
	v_mfma_f32_16x16x32_bf16 v[106:109], v[160:163], v[218:221], v[106:109]
	v_mfma_f32_16x16x32_bf16 v[106:109], v[164:167], v[236:239], v[106:109]
	v_mfma_f32_16x16x32_bf16 v[98:101], v[164:167], v[244:247], v[98:101]
	v_mfma_f32_16x16x32_bf16 v[98:101], v[160:163], v[240:243], v[98:101]
	v_mfma_f32_16x16x32_bf16 v[102:105], v[152:155], v[240:243], v[102:105]
	v_mfma_f32_16x16x32_bf16 v[102:105], v[156:159], v[244:247], v[102:105]
	v_mfma_f32_16x16x32_bf16 v[110:113], v[156:159], v[236:239], v[110:113]
	v_mfma_f32_16x16x32_bf16 v[110:113], v[152:155], v[218:221], v[110:113]
	v_mfma_f32_16x16x32_bf16 v[94:97], v[168:171], v[194:197], v[94:97]
	v_mfma_f32_16x16x32_bf16 v[94:97], v[172:175], v[206:209], v[94:97]
	v_mfma_f32_16x16x32_bf16 v[86:89], v[172:175], v[214:217], v[86:89]
	v_mfma_f32_16x16x32_bf16 v[86:89], v[168:171], v[210:213], v[86:89]
	v_mfma_f32_16x16x32_bf16 v[82:85], v[176:179], v[210:213], v[82:85]
	v_mfma_f32_16x16x32_bf16 v[82:85], v[180:183], v[214:217], v[82:85]
	v_mfma_f32_16x16x32_bf16 v[90:93], v[180:183], v[206:209], v[90:93]
	v_mfma_f32_16x16x32_bf16 v[90:93], v[176:179], v[194:197], v[90:93]
	v_mfma_f32_16x16x32_bf16 v[74:77], v[176:179], v[218:221], v[74:77]
	v_mfma_f32_16x16x32_bf16 v[74:77], v[180:183], v[236:239], v[74:77]
	v_mfma_f32_16x16x32_bf16 v[66:69], v[180:183], v[244:247], v[66:69]
	v_mfma_f32_16x16x32_bf16 v[66:69], v[176:179], v[240:243], v[66:69]
	v_mfma_f32_16x16x32_bf16 v[70:73], v[168:171], v[240:243], v[70:73]
	v_mfma_f32_16x16x32_bf16 v[70:73], v[172:175], v[244:247], v[70:73]
	v_mfma_f32_16x16x32_bf16 v[78:81], v[172:175], v[236:239], v[78:81]
	v_mfma_f32_16x16x32_bf16 v[78:81], v[168:171], v[218:221], v[78:81]
	s_barrier
	s_add_i32 s9, s9, s42
	s_mov_b32 m0, s9
	ds_read_b128 v[194:197], v151 offset:49152
	ds_read_b128 v[206:209], v151 offset:50176
	ds_read_b128 v[210:213], v151 offset:51200
	ds_read_b128 v[214:217], v151 offset:52224
	ds_read_b128 v[218:221], v151 offset:53248
	ds_read_b128 v[236:239], v151 offset:54272
	ds_read_b128 v[240:243], v151 offset:55296
	ds_read_b128 v[244:247], v151 offset:56320
	s_add_u32 s100, s84, s60
	s_addc_u32 s101, s85, s61
	global_load_lds_dwordx4 v130, s[100:101]
	s_add_i32 m0, s9, 0x2000
	s_add_u32 s10, s84, 0x20080
	s_addc_u32 s11, s85, 0
	s_add_i32 s9, s12, s42
	global_load_lds_dwordx4 v134, s[100:101]
	s_mov_b32 m0, s9
	s_nop 0
	global_load_lds_dwordx4 v130, s[10:11]
	s_add_i32 m0, s9, 0x2000
	s_nop 0
	global_load_lds_dwordx4 v134, s[10:11]
	s_mov_b32 m0, s82
	s_add_u32 s100, s92, s60
	s_addc_u32 s101, s93, s61
	global_load_lds_dwordx4 v190, s[100:101]
	s_mov_b32 m0, s86
	s_nop 0
	global_load_lds_dwordx4 v132, s[100:101]
	s_waitcnt vmcnt(8)
	s_waitcnt lgkmcnt(0)
	s_barrier
	v_mfma_f32_16x16x32_bf16 v[62:65], v[152:155], v[194:197], v[62:65]
	v_mfma_f32_16x16x32_bf16 v[62:65], v[156:159], v[206:209], v[62:65]
	v_mfma_f32_16x16x32_bf16 v[54:57], v[156:159], v[214:217], v[54:57]
	v_mfma_f32_16x16x32_bf16 v[54:57], v[152:155], v[210:213], v[54:57]
	v_mfma_f32_16x16x32_bf16 v[50:53], v[160:163], v[210:213], v[50:53]
	v_mfma_f32_16x16x32_bf16 v[50:53], v[164:167], v[214:217], v[50:53]
	v_mfma_f32_16x16x32_bf16 v[58:61], v[164:167], v[206:209], v[58:61]
	v_mfma_f32_16x16x32_bf16 v[58:61], v[160:163], v[194:197], v[58:61]
	v_mfma_f32_16x16x32_bf16 v[42:45], v[160:163], v[218:221], v[42:45]
	v_mfma_f32_16x16x32_bf16 v[42:45], v[164:167], v[236:239], v[42:45]
	v_mfma_f32_16x16x32_bf16 v[34:37], v[164:167], v[244:247], v[34:37]
	v_mfma_f32_16x16x32_bf16 v[34:37], v[160:163], v[240:243], v[34:37]
	v_mfma_f32_16x16x32_bf16 v[38:41], v[152:155], v[240:243], v[38:41]
	v_mfma_f32_16x16x32_bf16 v[38:41], v[156:159], v[244:247], v[38:41]
	v_mfma_f32_16x16x32_bf16 v[46:49], v[156:159], v[236:239], v[46:49]
	v_mfma_f32_16x16x32_bf16 v[46:49], v[152:155], v[218:221], v[46:49]
	v_mfma_f32_16x16x32_bf16 v[30:33], v[168:171], v[194:197], v[30:33]
	v_mfma_f32_16x16x32_bf16 v[30:33], v[172:175], v[206:209], v[30:33]
	v_mfma_f32_16x16x32_bf16 v[22:25], v[172:175], v[214:217], v[22:25]
	v_mfma_f32_16x16x32_bf16 v[22:25], v[168:171], v[210:213], v[22:25]
	v_mfma_f32_16x16x32_bf16 v[18:21], v[176:179], v[210:213], v[18:21]
	v_mfma_f32_16x16x32_bf16 v[18:21], v[180:183], v[214:217], v[18:21]
	v_mfma_f32_16x16x32_bf16 v[26:29], v[180:183], v[206:209], v[26:29]
	v_mfma_f32_16x16x32_bf16 v[26:29], v[176:179], v[194:197], v[26:29]
	v_mfma_f32_16x16x32_bf16 v[10:13], v[176:179], v[218:221], v[10:13]
	v_mfma_f32_16x16x32_bf16 v[10:13], v[180:183], v[236:239], v[10:13]
	v_mfma_f32_16x16x32_bf16 v[2:5], v[180:183], v[244:247], v[2:5]
	v_mfma_f32_16x16x32_bf16 v[2:5], v[176:179], v[240:243], v[2:5]
	v_mfma_f32_16x16x32_bf16 v[6:9], v[168:171], v[240:243], v[6:9]
	v_mfma_f32_16x16x32_bf16 v[6:9], v[172:175], v[244:247], v[6:9]
	v_mfma_f32_16x16x32_bf16 v[14:17], v[172:175], v[236:239], v[14:17]
	v_mfma_f32_16x16x32_bf16 v[14:17], v[168:171], v[218:221], v[14:17]
	s_barrier
	s_add_i32 s8, s8, 2
	s_add_u32 s80, s80, 0x100
	s_addc_u32 s81, s81, 0
	s_cmp_gt_u32 s8, 29
	s_cbranch_scc0 .LBB0_1233
	s_and_b64 vcc, exec, s[62:63]
	s_cbranch_vccz .LBB0_1236
	s_barrier
